# SwiGLU row-stat loads issued at the start of the tile K loop into phase-free registers v234-v249; first epilogue group no longer waits on vmcnt
# baseline (speedup 1.0000x reference)
; #define PG8_STAGE(bufoff, gbase, voff) do { _Pragma("unroll") for (int _i = 0; _i < 2; ++_i) \
;         __builtin_amdgcn_global_load_lds((const unsigned*)((const char*)(gbase) + (voff)[_i]), (PG8_LAS unsigned*)(lds + (bufoff) + ldsw + _i * 8192), 16, 0, 0); } while (0)
; #define PG8_LDA(dst, b, h) do { _Pragma("unroll") for (int m = 0; m < 4; ++m) _Pragma("unroll") for (int k = 0; k < 2; ++k) dst[m][k] = *(const PG8_LAS bf16x8*)(lds + PG8_SA(b, h) + aoff + m * 2048 + k * 1024); } while (0)
; #define PG8_LDB(dst, b, h) do { _Pragma("unroll") for (int n = 0; n < 2; ++n) _Pragma("unroll") for (int k = 0; k < 2; ++k) dst[n][k] = *(const PG8_LAS bf16x8*)(lds + PG8_SB(b, h) + boff + n * 2048 + k * 1024); } while (0)
; #define PG8_WAIT_V(n) asm volatile("s_waitcnt vmcnt(" #n ")" ::: "memory")
; #define PG8_WAIT_L(n) asm volatile("s_waitcnt lgkmcnt(" #n ")" ::: "memory")
; __device__ __forceinline__ float row_rs(const float* ssp, int row) { const unsigned long long v = ((const unsigned long long*)ssp)[row];
; template <class Epi, class Sched, bool ALIGN_EPI = false, bool SP2 = false>
; __device__ __forceinline__ void gemm_phase(PG8_LAS unsigned char* lds, const Gemm g, const Sched& S, const Epi& E) {
;     ...
;         const bool has_next = S.next(ui + 1, nxt);
;         const char* nA = has_next ? (const char*)g.A + (size_t)nxt.pm * tstep : cA; const char* nB = has_next ? (const char*)g.Bt + (size_t)nxt.pn * tstep : cB;
;         for (int t = 0; t < nt; t += 2) {
;             const bool last = (t == nt - 2);
;             const char* a1 = cA + (size_t)(t + 1) * kstep;
;             const char* a2 = last ? nA : cA + (size_t)(t + 2) * kstep; const char* b2 = last ? nB : cB + (size_t)(t + 2) * kstep;
;             const char* a3 = a2 + kstep; const char* b3 = b2 + kstep;
;             if (last && has_next) S.a_ready(nxt);
;             if constexpr (SP2) {
;             PG8_LDB(B0, 0, 0); PG8_LDB(B1, 0, 1); PG8_SCHED; PG8_LDA(At, 0, 0); PG8_STAGE(PG8_SA(1, 1), a1 + hstep, voffA);
;             PG8_WAIT_V(8); PG8_WAIT_L(0); PG8_BAR; PG8_MMA(0, 0, At, B0); PG8_MMA(0, 1, At, B1); PG8_BAR; PG8_SCHED;
;             PG8_LDA(At, 0, 1); PG8_STAGE(PG8_SB(0, 0), b2, voffB); PG8_STAGE(PG8_SB(0, 1), b2 + hstep, voffB); PG8_STAGE(PG8_SA(0, 0), a2, voffA);
;             PG8_WAIT_V(8); PG8_WAIT_L(0); PG8_BAR; PG8_MMA(1, 0, At, B0); PG8_MMA(1, 1, At, B1); PG8_BAR; PG8_SCHED;
.LBB0_190:
	v_lshl_add_u32 v144, s44, 8, v152
	v_ashrrev_i32_e32 v145, 31, v144
	v_lshl_add_u64 v[150:151], v[144:145], 3, s[6:7]
	global_load_dwordx2 v[234:235], v[150:151], off
	global_load_dwordx2 v[236:237], v[150:151], off offset:128
	global_load_dwordx2 v[238:239], v[150:151], off offset:256
	global_load_dwordx2 v[240:241], v[150:151], off offset:384
	global_load_dwordx2 v[242:243], v[150:151], off offset:1024
	global_load_dwordx2 v[244:245], v[150:151], off offset:1152
	global_load_dwordx2 v[246:247], v[150:151], off offset:1280
	global_load_dwordx2 v[248:249], v[150:151], off offset:1408
	s_ashr_i32 s27, s26, 31
	s_lshl_b64 s[14:15], s[26:27], 19
	s_add_u32 s28, s22, s14
	s_addc_u32 s29, s23, s15
	s_and_b64 s[14:15], s[0:1], exec
	s_cselect_b32 s27, s29, s49
	s_cselect_b32 s67, s28, s48
	s_ashr_i32 s25, s24, 31
	s_lshl_b64 s[14:15], s[24:25], 19
	s_add_u32 s40, s94, s14
	s_addc_u32 s41, s96, s15
	s_and_b64 s[14:15], s[0:1], exec
	s_cselect_b32 s25, s41, s51
	s_cselect_b32 s86, s40, s50
	s_add_u32 s48, s48, 0x40080
	s_addc_u32 s49, s49, 0
	s_add_u32 s87, s50, 0x100
	s_addc_u32 s88, s51, 0
	s_mov_b32 s89, -2
	ds_read_b128 v[144:147], v155
	ds_read_b128 v[148:151], v155 offset:1024
	ds_read_b128 v[160:163], v155 offset:2048
	ds_read_b128 v[168:171], v155 offset:3072
	ds_read_b128 v[172:175], v156
	ds_read_b128 v[176:179], v156 offset:1024
	ds_read_b128 v[182:185], v156 offset:2048
	ds_read_b128 v[186:189], v156 offset:3072
	s_add_u32 s3, s48, 0xfffc0080
	s_addc_u32 s14, s49, -1
	s_cmp_eq_u32 s89, 12
	s_cselect_b32 s55, s27, s14
	s_cselect_b32 s54, s67, s3
	s_cselect_b32 s51, s25, s88
	s_cselect_b32 s50, s86, s87
	v_lshl_add_u64 v[164:165], s[48:49], 0, v[136:137]
	s_add_i32 m0, s45, 0xc000
	ds_read_b128 v[190:193], v157
	ds_read_b128 v[194:197], v157 offset:1024
	ds_read_b128 v[198:201], v157 offset:2048
	ds_read_b128 v[208:211], v157 offset:3072
	ds_read_b128 v[212:215], v157 offset:4096
	ds_read_b128 v[216:219], v157 offset:5120
	ds_read_b128 v[220:223], v157 offset:6144
	ds_read_b128 v[224:227], v157 offset:7168
	global_load_lds_dwordx4 v[164:165], off
	v_lshl_add_u64 v[164:165], s[48:49], 0, v[138:139]
	s_add_i32 m0, s45, 0xe000
	s_nop 0
	global_load_lds_dwordx4 v[164:165], off
	s_waitcnt vmcnt(8)
	s_waitcnt lgkmcnt(0)
	s_barrier
	s_setprio 1
	s_waitcnt lgkmcnt(0)
	v_mfma_f32_16x16x32_bf16 v[124:127], v[144:147], v[190:193], 0
	v_mfma_f32_16x16x32_bf16 v[120:123], v[160:163], v[190:193], 0
	v_mfma_f32_16x16x32_bf16 v[108:111], v[144:147], v[198:201], 0
	v_mfma_f32_16x16x32_bf16 v[104:107], v[160:163], v[198:201], 0
	v_mfma_f32_16x16x32_bf16 v[92:95], v[144:147], v[212:215], 0
	v_mfma_f32_16x16x32_bf16 v[88:91], v[160:163], v[212:215], 0
	v_mfma_f32_16x16x32_bf16 v[76:79], v[144:147], v[220:223], 0
	v_mfma_f32_16x16x32_bf16 v[72:75], v[160:163], v[220:223], 0
	v_mfma_f32_16x16x32_bf16 v[124:127], v[148:151], v[194:197], v[124:127]
	v_mfma_f32_16x16x32_bf16 v[120:123], v[168:171], v[194:197], v[120:123]
	v_mfma_f32_16x16x32_bf16 v[108:111], v[148:151], v[208:211], v[108:111]
	v_mfma_f32_16x16x32_bf16 v[104:107], v[168:171], v[208:211], v[104:107]
	v_mfma_f32_16x16x32_bf16 v[92:95], v[148:151], v[216:219], v[92:95]
	v_mfma_f32_16x16x32_bf16 v[88:91], v[168:171], v[216:219], v[88:91]
	v_mfma_f32_16x16x32_bf16 v[76:79], v[148:151], v[224:227], v[76:79]
	v_mfma_f32_16x16x32_bf16 v[72:75], v[168:171], v[224:227], v[72:75]
	s_setprio 0
	s_setprio 1
	v_mfma_f32_16x16x32_bf16 v[116:119], v[172:175], v[190:193], 0
	v_mfma_f32_16x16x32_bf16 v[112:115], v[182:185], v[190:193], 0
	v_mfma_f32_16x16x32_bf16 v[100:103], v[172:175], v[198:201], 0
	v_mfma_f32_16x16x32_bf16 v[96:99], v[182:185], v[198:201], 0
	v_mfma_f32_16x16x32_bf16 v[84:87], v[172:175], v[212:215], 0
	v_mfma_f32_16x16x32_bf16 v[80:83], v[182:185], v[212:215], 0
	v_mfma_f32_16x16x32_bf16 v[68:71], v[172:175], v[220:223], 0
	v_mfma_f32_16x16x32_bf16 v[64:67], v[182:185], v[220:223], 0
	v_mfma_f32_16x16x32_bf16 v[116:119], v[176:179], v[194:197], v[116:119]
	v_mfma_f32_16x16x32_bf16 v[112:115], v[186:189], v[194:197], v[112:115]
	v_mfma_f32_16x16x32_bf16 v[100:103], v[176:179], v[208:211], v[100:103]
	v_mfma_f32_16x16x32_bf16 v[96:99], v[186:189], v[208:211], v[96:99]
	v_mfma_f32_16x16x32_bf16 v[84:87], v[176:179], v[216:219], v[84:87]
	v_mfma_f32_16x16x32_bf16 v[80:83], v[186:189], v[216:219], v[80:83]
	v_mfma_f32_16x16x32_bf16 v[68:71], v[176:179], v[224:227], v[68:71]
	v_mfma_f32_16x16x32_bf16 v[64:67], v[186:189], v[224:227], v[64:67]
	s_setprio 0
	s_barrier
	s_add_i32 s3, s63, s43
	v_lshl_add_u64 v[164:165], s[50:51], 0, v[132:133]
	s_mov_b32 m0, s3
	ds_read_b128 v[190:193], v157 offset:16384
	ds_read_b128 v[194:197], v157 offset:17408
	ds_read_b128 v[198:201], v157 offset:18432
	ds_read_b128 v[208:211], v157 offset:19456
	ds_read_b128 v[212:215], v157 offset:20480
	ds_read_b128 v[216:219], v157 offset:21504
	ds_read_b128 v[220:223], v157 offset:22528
	ds_read_b128 v[224:227], v157 offset:23552
	global_load_lds_dwordx4 v[164:165], off
	s_add_i32 m0, s3, 0x2000
	s_add_u32 s14, s50, 0x40000
	v_lshl_add_u64 v[202:203], s[50:51], 0, v[128:129]
	s_addc_u32 s15, s51, 0
	s_add_i32 s3, s64, s43
	global_load_lds_dwordx4 v[202:203], off
	v_lshl_add_u64 v[228:229], s[14:15], 0, v[132:133]
	s_mov_b32 m0, s3
	global_load_lds_dwordx4 v[228:229], off
	v_lshl_add_u64 v[228:229], s[14:15], 0, v[128:129]
	s_add_i32 m0, s3, 0x2000
	s_nop 0
	global_load_lds_dwordx4 v[228:229], off
	s_waitcnt vmcnt(6)
	s_waitcnt lgkmcnt(0)
	s_barrier
; #define PG8_STAGE(bufoff, gbase, voff) do { _Pragma("unroll") for (int _i = 0; _i < 2; ++_i) \
;         __builtin_amdgcn_global_load_lds((const unsigned*)((const char*)(gbase) + (voff)[_i]), (PG8_LAS unsigned*)(lds + (bufoff) + ldsw + _i * 8192), 16, 0, 0); } while (0)
; #define PG8_LDA(dst, b, h) do { _Pragma("unroll") for (int m = 0; m < 4; ++m) _Pragma("unroll") for (int k = 0; k < 2; ++k) dst[m][k] = *(const PG8_LAS bf16x8*)(lds + PG8_SA(b, h) + aoff + m * 2048 + k * 1024); } while (0)
; #define PG8_LDB(dst, b, h) do { _Pragma("unroll") for (int n = 0; n < 2; ++n) _Pragma("unroll") for (int k = 0; k < 2; ++k) dst[n][k] = *(const PG8_LAS bf16x8*)(lds + PG8_SB(b, h) + boff + n * 2048 + k * 1024); } while (0)
; #define PG8_MMA(ai, bj, At, Bt) do { __builtin_amdgcn_s_setprio(1); _Pragma("unroll") for (int m = 0; m < 4; ++m) _Pragma("unroll") for (int n = 0; n < 2; ++n) _Pragma("unroll") for (int k = 0; k < 2; ++k) \
;         acc[ai][bj][m][n] = __builtin_amdgcn_mfma_f32_16x16x32_bf16(Bt[n][k], At[m][k], acc[ai][bj][m][n], 0, 0, 0); __builtin_amdgcn_s_setprio(0); } while (0)
; #define PG8_WAIT_V(n) asm volatile("s_waitcnt vmcnt(" #n ")" ::: "memory")
; #define PG8_WAIT_L(n) asm volatile("s_waitcnt lgkmcnt(" #n ")" ::: "memory")
; #define PG8_BAR __builtin_amdgcn_s_barrier()
; #define PG8_SCHED __builtin_amdgcn_sched_barrier(0)
; template <class Epi, class Sched, bool ALIGN_EPI = false, bool SP2 = false>
; __device__ __forceinline__ void gemm_phase(PG8_LAS unsigned char* lds, const Gemm g, const Sched& S, const Epi& E) {
;     ...
;             PG8_LDB(B0, 0, 0); PG8_LDB(B1, 0, 1); PG8_SCHED; PG8_LDA(At, 0, 0); PG8_STAGE(PG8_SA(1, 1), a1 + hstep, voffA);
;             PG8_WAIT_V(8); PG8_WAIT_L(0); PG8_BAR; PG8_MMA(0, 0, At, B0); PG8_MMA(0, 1, At, B1); PG8_BAR; PG8_SCHED;
;             PG8_LDA(At, 0, 1); PG8_STAGE(PG8_SB(0, 0), b2, voffB); PG8_STAGE(PG8_SB(0, 1), b2 + hstep, voffB); PG8_STAGE(PG8_SA(0, 0), a2, voffA);
;             PG8_WAIT_V(8); PG8_WAIT_L(0); PG8_BAR; PG8_MMA(1, 0, At, B0); PG8_MMA(1, 1, At, B1); PG8_BAR; PG8_SCHED;
;             PG8_LDB(B0, 1, 0); PG8_LDB(B1, 1, 1); PG8_SCHED; PG8_LDA(At, 1, 0); PG8_STAGE(PG8_SA(0, 1), a2 + hstep, voffA);
;             PG8_WAIT_V(8); PG8_WAIT_L(0); PG8_BAR; PG8_MMA(0, 0, At, B0); PG8_MMA(0, 1, At, B1); PG8_BAR; PG8_SCHED;
	s_setprio 1
	s_waitcnt lgkmcnt(0)
	v_mfma_f32_16x16x32_bf16 v[60:63], v[144:147], v[190:193], 0
	v_mfma_f32_16x16x32_bf16 v[56:59], v[160:163], v[190:193], 0
	v_mfma_f32_16x16x32_bf16 v[44:47], v[144:147], v[198:201], 0
	v_mfma_f32_16x16x32_bf16 v[40:43], v[160:163], v[198:201], 0
	v_mfma_f32_16x16x32_bf16 v[28:31], v[144:147], v[212:215], 0
	v_mfma_f32_16x16x32_bf16 v[24:27], v[160:163], v[212:215], 0
	v_mfma_f32_16x16x32_bf16 v[12:15], v[144:147], v[220:223], 0
	v_mfma_f32_16x16x32_bf16 v[8:11], v[160:163], v[220:223], 0
	v_mfma_f32_16x16x32_bf16 v[60:63], v[148:151], v[194:197], v[60:63]
	v_mfma_f32_16x16x32_bf16 v[56:59], v[168:171], v[194:197], v[56:59]
	v_mfma_f32_16x16x32_bf16 v[44:47], v[148:151], v[208:211], v[44:47]
	v_mfma_f32_16x16x32_bf16 v[40:43], v[168:171], v[208:211], v[40:43]
	v_mfma_f32_16x16x32_bf16 v[28:31], v[148:151], v[216:219], v[28:31]
	v_mfma_f32_16x16x32_bf16 v[24:27], v[168:171], v[216:219], v[24:27]
	v_lshl_add_u64 v[228:229], s[54:55], 0, v[134:135]
	s_mov_b32 m0, s45
	s_nop 0
	global_load_lds_dwordx4 v[228:229], off
	v_mfma_f32_16x16x32_bf16 v[12:15], v[148:151], v[224:227], v[12:15]
	v_mfma_f32_16x16x32_bf16 v[8:11], v[168:171], v[224:227], v[8:11]
	s_setprio 0
	s_setprio 1
	v_mfma_f32_16x16x32_bf16 v[52:55], v[172:175], v[190:193], 0
	v_mfma_f32_16x16x32_bf16 v[48:51], v[182:185], v[190:193], 0
	v_mfma_f32_16x16x32_bf16 v[36:39], v[172:175], v[198:201], 0
	v_mfma_f32_16x16x32_bf16 v[32:35], v[182:185], v[198:201], 0
	v_mfma_f32_16x16x32_bf16 v[20:23], v[172:175], v[212:215], 0
	v_mfma_f32_16x16x32_bf16 v[16:19], v[182:185], v[212:215], 0
	v_mfma_f32_16x16x32_bf16 v[4:7], v[172:175], v[220:223], 0
	v_mfma_f32_16x16x32_bf16 v[0:3], v[182:185], v[220:223], 0
	v_mfma_f32_16x16x32_bf16 v[52:55], v[176:179], v[194:197], v[52:55]
	v_mfma_f32_16x16x32_bf16 v[48:51], v[186:189], v[194:197], v[48:51]
	v_mfma_f32_16x16x32_bf16 v[36:39], v[176:179], v[208:211], v[36:39]
	v_mfma_f32_16x16x32_bf16 v[32:35], v[186:189], v[208:211], v[32:35]
	v_mfma_f32_16x16x32_bf16 v[20:23], v[176:179], v[216:219], v[20:23]
	v_mfma_f32_16x16x32_bf16 v[16:19], v[186:189], v[216:219], v[16:19]
	v_lshl_add_u64 v[230:231], s[54:55], 0, v[130:131]
	s_mov_b32 m0, s57
	s_nop 0
	global_load_lds_dwordx4 v[230:231], off
	v_mfma_f32_16x16x32_bf16 v[4:7], v[176:179], v[224:227], v[4:7]
	v_mfma_f32_16x16x32_bf16 v[0:3], v[186:189], v[224:227], v[0:3]
	s_setprio 0
	s_barrier
	s_add_i32 s3, 0, 0x18000
	v_add_u32_e32 v159, s3, v153
	s_add_i32 s33, 0, 0x1c000
	ds_read_b128 v[144:147], v159
	ds_read_b128 v[148:151], v159 offset:1024
	ds_read_b128 v[160:163], v159 offset:2048
	ds_read_b128 v[168:171], v159 offset:3072
	v_add_u32_e32 v159, s33, v153
	ds_read_b128 v[172:175], v159
	ds_read_b128 v[176:179], v159 offset:1024
	ds_read_b128 v[182:185], v159 offset:2048
	ds_read_b128 v[186:189], v159 offset:3072
	s_add_u32 s14, s54, 0x40000
	s_addc_u32 s15, s55, 0
	s_mov_b32 m0, s58
	v_lshl_add_u64 v[232:233], s[14:15], 0, v[134:135]
	ds_read_b128 v[190:193], v157 offset:32768
	ds_read_b128 v[194:197], v157 offset:33792
	ds_read_b128 v[198:201], v157 offset:34816
	ds_read_b128 v[208:211], v157 offset:35840
	ds_read_b128 v[212:215], v157 offset:36864
	ds_read_b128 v[216:219], v157 offset:37888
	ds_read_b128 v[220:223], v157 offset:38912
	ds_read_b128 v[224:227], v157 offset:39936
	global_load_lds_dwordx4 v[232:233], off
	v_lshl_add_u64 v[232:233], s[14:15], 0, v[130:131]
	s_mov_b32 m0, s59
	s_nop 0
	global_load_lds_dwordx4 v[232:233], off
	s_waitcnt vmcnt(8)
	s_waitcnt lgkmcnt(0)
	s_barrier
	s_setprio 1
	s_waitcnt lgkmcnt(0)
	v_mfma_f32_16x16x32_bf16 v[124:127], v[144:147], v[190:193], v[124:127]
	v_mfma_f32_16x16x32_bf16 v[120:123], v[160:163], v[190:193], v[120:123]
	v_mfma_f32_16x16x32_bf16 v[108:111], v[144:147], v[198:201], v[108:111]
	v_mfma_f32_16x16x32_bf16 v[104:107], v[160:163], v[198:201], v[104:107]
	v_mfma_f32_16x16x32_bf16 v[92:95], v[144:147], v[212:215], v[92:95]
	v_mfma_f32_16x16x32_bf16 v[88:91], v[160:163], v[212:215], v[88:91]
	v_mfma_f32_16x16x32_bf16 v[76:79], v[144:147], v[220:223], v[76:79]
	v_mfma_f32_16x16x32_bf16 v[72:75], v[160:163], v[220:223], v[72:75]
	v_mfma_f32_16x16x32_bf16 v[124:127], v[148:151], v[194:197], v[124:127]
	v_mfma_f32_16x16x32_bf16 v[120:123], v[168:171], v[194:197], v[120:123]
	v_mfma_f32_16x16x32_bf16 v[108:111], v[148:151], v[208:211], v[108:111]
	v_mfma_f32_16x16x32_bf16 v[104:107], v[168:171], v[208:211], v[104:107]
	v_mfma_f32_16x16x32_bf16 v[92:95], v[148:151], v[216:219], v[92:95]
	v_mfma_f32_16x16x32_bf16 v[88:91], v[168:171], v[216:219], v[88:91]
	v_mfma_f32_16x16x32_bf16 v[76:79], v[148:151], v[224:227], v[76:79]
	v_mfma_f32_16x16x32_bf16 v[72:75], v[168:171], v[224:227], v[72:75]
	s_setprio 0
	s_setprio 1
	v_mfma_f32_16x16x32_bf16 v[116:119], v[172:175], v[190:193], v[116:119]
	v_mfma_f32_16x16x32_bf16 v[112:115], v[182:185], v[190:193], v[112:115]
	v_mfma_f32_16x16x32_bf16 v[100:103], v[172:175], v[198:201], v[100:103]
	v_mfma_f32_16x16x32_bf16 v[96:99], v[182:185], v[198:201], v[96:99]
	v_mfma_f32_16x16x32_bf16 v[84:87], v[172:175], v[212:215], v[84:87]
	v_mfma_f32_16x16x32_bf16 v[80:83], v[182:185], v[212:215], v[80:83]
	v_mfma_f32_16x16x32_bf16 v[68:71], v[172:175], v[220:223], v[68:71]
	v_mfma_f32_16x16x32_bf16 v[64:67], v[182:185], v[220:223], v[64:67]
	v_mfma_f32_16x16x32_bf16 v[116:119], v[176:179], v[194:197], v[116:119]
	v_mfma_f32_16x16x32_bf16 v[112:115], v[186:189], v[194:197], v[112:115]
	v_mfma_f32_16x16x32_bf16 v[100:103], v[176:179], v[208:211], v[100:103]
	v_mfma_f32_16x16x32_bf16 v[96:99], v[186:189], v[208:211], v[96:99]
	v_mfma_f32_16x16x32_bf16 v[84:87], v[176:179], v[216:219], v[84:87]
	v_mfma_f32_16x16x32_bf16 v[80:83], v[186:189], v[216:219], v[80:83]
	v_mfma_f32_16x16x32_bf16 v[68:71], v[176:179], v[224:227], v[68:71]
	v_mfma_f32_16x16x32_bf16 v[64:67], v[186:189], v[224:227], v[64:67]
	s_setprio 0
	s_barrier
; #define PG8_STAGE(bufoff, gbase, voff) do { _Pragma("unroll") for (int _i = 0; _i < 2; ++_i) \
;         __builtin_amdgcn_global_load_lds((const unsigned*)((const char*)(gbase) + (voff)[_i]), (PG8_LAS unsigned*)(lds + (bufoff) + ldsw + _i * 8192), 16, 0, 0); } while (0)
; #define PG8_LDA(dst, b, h) do { _Pragma("unroll") for (int m = 0; m < 4; ++m) _Pragma("unroll") for (int k = 0; k < 2; ++k) dst[m][k] = *(const PG8_LAS bf16x8*)(lds + PG8_SA(b, h) + aoff + m * 2048 + k * 1024); } while (0)
; #define PG8_LDB(dst, b, h) do { _Pragma("unroll") for (int n = 0; n < 2; ++n) _Pragma("unroll") for (int k = 0; k < 2; ++k) dst[n][k] = *(const PG8_LAS bf16x8*)(lds + PG8_SB(b, h) + boff + n * 2048 + k * 1024); } while (0)
; #define PG8_MMA(ai, bj, At, Bt) do { __builtin_amdgcn_s_setprio(1); _Pragma("unroll") for (int m = 0; m < 4; ++m) _Pragma("unroll") for (int n = 0; n < 2; ++n) _Pragma("unroll") for (int k = 0; k < 2; ++k) \
;         acc[ai][bj][m][n] = __builtin_amdgcn_mfma_f32_16x16x32_bf16(Bt[n][k], At[m][k], acc[ai][bj][m][n], 0, 0, 0); __builtin_amdgcn_s_setprio(0); } while (0)
; #define PG8_WAIT_V(n) asm volatile("s_waitcnt vmcnt(" #n ")" ::: "memory")
; #define PG8_WAIT_L(n) asm volatile("s_waitcnt lgkmcnt(" #n ")" ::: "memory")
; #define PG8_BAR __builtin_amdgcn_s_barrier()
; #define PG8_SCHED __builtin_amdgcn_sched_barrier(0)
; template <class Epi, class Sched, bool ALIGN_EPI = false, bool SP2 = false>
; __device__ __forceinline__ void gemm_phase(PG8_LAS unsigned char* lds, const Gemm g, const Sched& S, const Epi& E) {
;     ...
;             PG8_LDA(At, 0, 1); PG8_STAGE(PG8_SB(0, 0), b2, voffB); PG8_STAGE(PG8_SB(0, 1), b2 + hstep, voffB); PG8_STAGE(PG8_SA(0, 0), a2, voffA);
;             PG8_WAIT_V(8); PG8_WAIT_L(0); PG8_BAR; PG8_MMA(1, 0, At, B0); PG8_MMA(1, 1, At, B1); PG8_BAR; PG8_SCHED;
;             PG8_LDB(B0, 1, 0); PG8_LDB(B1, 1, 1); PG8_SCHED; PG8_LDA(At, 1, 0); PG8_STAGE(PG8_SA(0, 1), a2 + hstep, voffA);
;             PG8_WAIT_V(8); PG8_WAIT_L(0); PG8_BAR; PG8_MMA(0, 0, At, B0); PG8_MMA(0, 1, At, B1); PG8_BAR; PG8_SCHED;
;             PG8_LDA(At, 1, 1); PG8_STAGE(PG8_SB(1, 0), b3, voffB); PG8_STAGE(PG8_SB(1, 1), b3 + hstep, voffB); PG8_STAGE(PG8_SA(1, 0), a3, voffA);
;             PG8_WAIT_V(8); PG8_WAIT_L(0); PG8_BAR; PG8_MMA(1, 0, At, B0); PG8_MMA(1, 1, At, B1); PG8_BAR; PG8_SCHED;
	s_add_i32 s3, s3, s43
	v_lshl_add_u64 v[164:165], v[164:165], 0, s[10:11]
	s_mov_b32 m0, s3
	ds_read_b128 v[190:193], v157 offset:49152
	ds_read_b128 v[194:197], v157 offset:50176
	ds_read_b128 v[198:201], v157 offset:51200
	ds_read_b128 v[208:211], v157 offset:52224
	ds_read_b128 v[212:215], v157 offset:53248
	ds_read_b128 v[216:219], v157 offset:54272
	ds_read_b128 v[220:223], v157 offset:55296
	ds_read_b128 v[224:227], v157 offset:56320
	global_load_lds_dwordx4 v[164:165], off
	s_add_i32 m0, s3, 0x2000
	s_add_u32 s14, s50, 0x40080
	v_lshl_add_u64 v[164:165], v[202:203], 0, s[10:11]
	s_addc_u32 s15, s51, 0
	s_add_i32 s3, s33, s43
	global_load_lds_dwordx4 v[164:165], off
	v_lshl_add_u64 v[164:165], s[14:15], 0, v[132:133]
	s_mov_b32 m0, s3
	s_nop 0
	global_load_lds_dwordx4 v[164:165], off
	v_lshl_add_u64 v[164:165], s[14:15], 0, v[128:129]
	s_add_i32 m0, s3, 0x2000
	s_nop 0
	global_load_lds_dwordx4 v[164:165], off
	s_waitcnt vmcnt(6)
	s_waitcnt lgkmcnt(0)
	s_barrier
	s_setprio 1
	s_waitcnt lgkmcnt(0)
	v_mfma_f32_16x16x32_bf16 v[60:63], v[144:147], v[190:193], v[60:63]
	v_mfma_f32_16x16x32_bf16 v[56:59], v[160:163], v[190:193], v[56:59]
	v_mfma_f32_16x16x32_bf16 v[44:47], v[144:147], v[198:201], v[44:47]
	v_mfma_f32_16x16x32_bf16 v[40:43], v[160:163], v[198:201], v[40:43]
	v_mfma_f32_16x16x32_bf16 v[28:31], v[144:147], v[212:215], v[28:31]
	v_mfma_f32_16x16x32_bf16 v[24:27], v[160:163], v[212:215], v[24:27]
	v_mfma_f32_16x16x32_bf16 v[12:15], v[144:147], v[220:223], v[12:15]
	v_mfma_f32_16x16x32_bf16 v[8:11], v[160:163], v[220:223], v[8:11]
	v_mfma_f32_16x16x32_bf16 v[60:63], v[148:151], v[194:197], v[60:63]
	v_mfma_f32_16x16x32_bf16 v[56:59], v[168:171], v[194:197], v[56:59]
	v_mfma_f32_16x16x32_bf16 v[44:47], v[148:151], v[208:211], v[44:47]
	v_mfma_f32_16x16x32_bf16 v[40:43], v[168:171], v[208:211], v[40:43]
	v_mfma_f32_16x16x32_bf16 v[28:31], v[148:151], v[216:219], v[28:31]
	v_mfma_f32_16x16x32_bf16 v[24:27], v[168:171], v[216:219], v[24:27]
	v_lshl_add_u64 v[164:165], v[228:229], 0, s[10:11]
	s_mov_b32 m0, s61
	s_nop 0
	global_load_lds_dwordx4 v[164:165], off
	v_mfma_f32_16x16x32_bf16 v[12:15], v[148:151], v[224:227], v[12:15]
	v_mfma_f32_16x16x32_bf16 v[8:11], v[168:171], v[224:227], v[8:11]
	s_setprio 0
	s_setprio 1
	v_mfma_f32_16x16x32_bf16 v[52:55], v[172:175], v[190:193], v[52:55]
	v_mfma_f32_16x16x32_bf16 v[48:51], v[182:185], v[190:193], v[48:51]
	v_mfma_f32_16x16x32_bf16 v[36:39], v[172:175], v[198:201], v[36:39]
	v_mfma_f32_16x16x32_bf16 v[32:35], v[182:185], v[198:201], v[32:35]
	v_mfma_f32_16x16x32_bf16 v[20:23], v[172:175], v[212:215], v[20:23]
	v_mfma_f32_16x16x32_bf16 v[16:19], v[182:185], v[212:215], v[16:19]
	v_mfma_f32_16x16x32_bf16 v[4:7], v[172:175], v[220:223], v[4:7]
	v_mfma_f32_16x16x32_bf16 v[0:3], v[182:185], v[220:223], v[0:3]
	v_mfma_f32_16x16x32_bf16 v[52:55], v[176:179], v[194:197], v[52:55]
	v_mfma_f32_16x16x32_bf16 v[48:51], v[186:189], v[194:197], v[48:51]
	v_mfma_f32_16x16x32_bf16 v[36:39], v[176:179], v[208:211], v[36:39]
	v_mfma_f32_16x16x32_bf16 v[32:35], v[186:189], v[208:211], v[32:35]
	v_mfma_f32_16x16x32_bf16 v[20:23], v[176:179], v[216:219], v[20:23]
	v_mfma_f32_16x16x32_bf16 v[16:19], v[186:189], v[216:219], v[16:19]
	v_lshl_add_u64 v[164:165], v[230:231], 0, s[10:11]
	s_mov_b32 m0, s62
	s_nop 0
	global_load_lds_dwordx4 v[164:165], off
	v_mfma_f32_16x16x32_bf16 v[4:7], v[176:179], v[224:227], v[4:7]
	v_mfma_f32_16x16x32_bf16 v[0:3], v[186:189], v[224:227], v[0:3]
	s_setprio 0
	s_barrier
	s_add_i32 s89, s89, 2
	s_add_u32 s48, s48, 0x100
	s_addc_u32 s49, s49, 0
	s_add_u32 s87, s87, 0x100
	s_addc_u32 s88, s88, 0
.LBB0_191:
	ds_read_b128 v[144:147], v155
	ds_read_b128 v[148:151], v155 offset:1024
	ds_read_b128 v[160:163], v155 offset:2048
	ds_read_b128 v[168:171], v155 offset:3072
	ds_read_b128 v[172:175], v156
	ds_read_b128 v[176:179], v156 offset:1024
	ds_read_b128 v[182:185], v156 offset:2048
	ds_read_b128 v[186:189], v156 offset:3072
	s_add_u32 s3, s48, 0xfffc0080
	s_addc_u32 s14, s49, -1
	s_cmp_eq_u32 s89, 12
	s_cselect_b32 s55, s27, s14
	s_cselect_b32 s54, s67, s3
	s_cselect_b32 s51, s25, s88
	s_cselect_b32 s50, s86, s87
	v_lshl_add_u64 v[164:165], s[48:49], 0, v[136:137]
	s_add_i32 m0, s45, 0xc000
	ds_read_b128 v[190:193], v157
	ds_read_b128 v[194:197], v157 offset:1024
	ds_read_b128 v[198:201], v157 offset:2048
	ds_read_b128 v[208:211], v157 offset:3072
	ds_read_b128 v[212:215], v157 offset:4096
	ds_read_b128 v[216:219], v157 offset:5120
	ds_read_b128 v[220:223], v157 offset:6144
	ds_read_b128 v[224:227], v157 offset:7168
	global_load_lds_dwordx4 v[164:165], off
	v_lshl_add_u64 v[164:165], s[48:49], 0, v[138:139]
	s_add_i32 m0, s45, 0xe000
	s_nop 0
	global_load_lds_dwordx4 v[164:165], off
	s_waitcnt vmcnt(8)
	s_waitcnt lgkmcnt(0)
	s_barrier
; #define PG8_STAGE(bufoff, gbase, voff) do { _Pragma("unroll") for (int _i = 0; _i < 2; ++_i) \
;         __builtin_amdgcn_global_load_lds((const unsigned*)((const char*)(gbase) + (voff)[_i]), (PG8_LAS unsigned*)(lds + (bufoff) + ldsw + _i * 8192), 16, 0, 0); } while (0)
; #define PG8_LDA(dst, b, h) do { _Pragma("unroll") for (int m = 0; m < 4; ++m) _Pragma("unroll") for (int k = 0; k < 2; ++k) dst[m][k] = *(const PG8_LAS bf16x8*)(lds + PG8_SA(b, h) + aoff + m * 2048 + k * 1024); } while (0)
; #define PG8_LDB(dst, b, h) do { _Pragma("unroll") for (int n = 0; n < 2; ++n) _Pragma("unroll") for (int k = 0; k < 2; ++k) dst[n][k] = *(const PG8_LAS bf16x8*)(lds + PG8_SB(b, h) + boff + n * 2048 + k * 1024); } while (0)
; #define PG8_MMA(ai, bj, At, Bt) do { __builtin_amdgcn_s_setprio(1); _Pragma("unroll") for (int m = 0; m < 4; ++m) _Pragma("unroll") for (int n = 0; n < 2; ++n) _Pragma("unroll") for (int k = 0; k < 2; ++k) \
;         acc[ai][bj][m][n] = __builtin_amdgcn_mfma_f32_16x16x32_bf16(Bt[n][k], At[m][k], acc[ai][bj][m][n], 0, 0, 0); __builtin_amdgcn_s_setprio(0); } while (0)
; #define PG8_WAIT_V(n) asm volatile("s_waitcnt vmcnt(" #n ")" ::: "memory")
; template <class Epi, class Sched, bool ALIGN_EPI = false, bool SP2 = false>
; __device__ __forceinline__ void gemm_phase(PG8_LAS unsigned char* lds, const Gemm g, const Sched& S, const Epi& E) {
;     ...
;             PG8_LDB(B0, 0, 0); PG8_LDB(B1, 0, 1); PG8_SCHED; PG8_LDA(At, 0, 0); PG8_STAGE(PG8_SA(1, 1), a1 + hstep, voffA);
;             PG8_WAIT_V(8); PG8_WAIT_L(0); PG8_BAR; PG8_MMA(0, 0, At, B0); PG8_MMA(0, 1, At, B1); PG8_BAR; PG8_SCHED;
;             PG8_LDA(At, 0, 1); PG8_STAGE(PG8_SB(0, 0), b2, voffB); PG8_STAGE(PG8_SB(0, 1), b2 + hstep, voffB); PG8_STAGE(PG8_SA(0, 0), a2, voffA);
;             PG8_WAIT_V(8); PG8_WAIT_L(0); PG8_BAR; PG8_MMA(1, 0, At, B0); PG8_MMA(1, 1, At, B1); PG8_BAR; PG8_SCHED;
;             PG8_LDB(B0, 1, 0); PG8_LDB(B1, 1, 1); PG8_SCHED; PG8_LDA(At, 1, 0); PG8_STAGE(PG8_SA(0, 1), a2 + hstep, voffA);
;             PG8_WAIT_V(8); PG8_WAIT_L(0); PG8_BAR; PG8_MMA(0, 0, At, B0); PG8_MMA(0, 1, At, B1); PG8_BAR; PG8_SCHED;
;             PG8_LDA(At, 1, 1); PG8_STAGE(PG8_SB(1, 0), b3, voffB); PG8_STAGE(PG8_SB(1, 1), b3 + hstep, voffB); PG8_STAGE(PG8_SA(1, 0), a3, voffA);
;             PG8_WAIT_V(8); PG8_WAIT_L(0); PG8_BAR; PG8_MMA(1, 0, At, B0); PG8_MMA(1, 1, At, B1); PG8_BAR; PG8_SCHED;
	s_setprio 1
	s_waitcnt lgkmcnt(0)
	v_mfma_f32_16x16x32_bf16 v[124:127], v[144:147], v[190:193], v[124:127]
	v_mfma_f32_16x16x32_bf16 v[120:123], v[160:163], v[190:193], v[120:123]
	v_mfma_f32_16x16x32_bf16 v[108:111], v[144:147], v[198:201], v[108:111]
	v_mfma_f32_16x16x32_bf16 v[104:107], v[160:163], v[198:201], v[104:107]
	v_mfma_f32_16x16x32_bf16 v[92:95], v[144:147], v[212:215], v[92:95]
	v_mfma_f32_16x16x32_bf16 v[88:91], v[160:163], v[212:215], v[88:91]
	v_mfma_f32_16x16x32_bf16 v[76:79], v[144:147], v[220:223], v[76:79]
	v_mfma_f32_16x16x32_bf16 v[72:75], v[160:163], v[220:223], v[72:75]
	v_mfma_f32_16x16x32_bf16 v[124:127], v[148:151], v[194:197], v[124:127]
	v_mfma_f32_16x16x32_bf16 v[120:123], v[168:171], v[194:197], v[120:123]
	v_mfma_f32_16x16x32_bf16 v[108:111], v[148:151], v[208:211], v[108:111]
	v_mfma_f32_16x16x32_bf16 v[104:107], v[168:171], v[208:211], v[104:107]
	v_mfma_f32_16x16x32_bf16 v[92:95], v[148:151], v[216:219], v[92:95]
	v_mfma_f32_16x16x32_bf16 v[88:91], v[168:171], v[216:219], v[88:91]
	v_mfma_f32_16x16x32_bf16 v[76:79], v[148:151], v[224:227], v[76:79]
	v_mfma_f32_16x16x32_bf16 v[72:75], v[168:171], v[224:227], v[72:75]
	s_setprio 0
	s_setprio 1
	v_mfma_f32_16x16x32_bf16 v[116:119], v[172:175], v[190:193], v[116:119]
	v_mfma_f32_16x16x32_bf16 v[112:115], v[182:185], v[190:193], v[112:115]
	v_mfma_f32_16x16x32_bf16 v[100:103], v[172:175], v[198:201], v[100:103]
	v_mfma_f32_16x16x32_bf16 v[96:99], v[182:185], v[198:201], v[96:99]
	v_mfma_f32_16x16x32_bf16 v[84:87], v[172:175], v[212:215], v[84:87]
	v_mfma_f32_16x16x32_bf16 v[80:83], v[182:185], v[212:215], v[80:83]
	v_mfma_f32_16x16x32_bf16 v[68:71], v[172:175], v[220:223], v[68:71]
	v_mfma_f32_16x16x32_bf16 v[64:67], v[182:185], v[220:223], v[64:67]
	v_mfma_f32_16x16x32_bf16 v[116:119], v[176:179], v[194:197], v[116:119]
	v_mfma_f32_16x16x32_bf16 v[112:115], v[186:189], v[194:197], v[112:115]
	v_mfma_f32_16x16x32_bf16 v[100:103], v[176:179], v[208:211], v[100:103]
	v_mfma_f32_16x16x32_bf16 v[96:99], v[186:189], v[208:211], v[96:99]
	v_mfma_f32_16x16x32_bf16 v[84:87], v[176:179], v[216:219], v[84:87]
	v_mfma_f32_16x16x32_bf16 v[80:83], v[186:189], v[216:219], v[80:83]
	v_mfma_f32_16x16x32_bf16 v[68:71], v[176:179], v[224:227], v[68:71]
	v_mfma_f32_16x16x32_bf16 v[64:67], v[186:189], v[224:227], v[64:67]
	s_setprio 0
	s_barrier
	s_add_i32 s3, s63, s43
	v_lshl_add_u64 v[164:165], s[50:51], 0, v[132:133]
	s_mov_b32 m0, s3
	ds_read_b128 v[190:193], v157 offset:16384
	ds_read_b128 v[194:197], v157 offset:17408
	ds_read_b128 v[198:201], v157 offset:18432
	ds_read_b128 v[208:211], v157 offset:19456
	ds_read_b128 v[212:215], v157 offset:20480
	ds_read_b128 v[216:219], v157 offset:21504
	ds_read_b128 v[220:223], v157 offset:22528
	ds_read_b128 v[224:227], v157 offset:23552
	global_load_lds_dwordx4 v[164:165], off
	s_add_i32 m0, s3, 0x2000
	s_add_u32 s14, s50, 0x40000
	v_lshl_add_u64 v[202:203], s[50:51], 0, v[128:129]
	s_addc_u32 s15, s51, 0
	s_add_i32 s3, s64, s43
	global_load_lds_dwordx4 v[202:203], off
	v_lshl_add_u64 v[228:229], s[14:15], 0, v[132:133]
	s_mov_b32 m0, s3
	global_load_lds_dwordx4 v[228:229], off
	v_lshl_add_u64 v[228:229], s[14:15], 0, v[128:129]
	s_add_i32 m0, s3, 0x2000
	s_nop 0
	global_load_lds_dwordx4 v[228:229], off
	s_waitcnt vmcnt(6)
	s_waitcnt lgkmcnt(0)
	s_barrier
	s_setprio 1
	s_waitcnt lgkmcnt(0)
	v_mfma_f32_16x16x32_bf16 v[60:63], v[144:147], v[190:193], v[60:63]
	v_mfma_f32_16x16x32_bf16 v[56:59], v[160:163], v[190:193], v[56:59]
	v_mfma_f32_16x16x32_bf16 v[44:47], v[144:147], v[198:201], v[44:47]
	v_mfma_f32_16x16x32_bf16 v[40:43], v[160:163], v[198:201], v[40:43]
	v_mfma_f32_16x16x32_bf16 v[28:31], v[144:147], v[212:215], v[28:31]
	v_mfma_f32_16x16x32_bf16 v[24:27], v[160:163], v[212:215], v[24:27]
	v_mfma_f32_16x16x32_bf16 v[12:15], v[144:147], v[220:223], v[12:15]
	v_mfma_f32_16x16x32_bf16 v[8:11], v[160:163], v[220:223], v[8:11]
	v_mfma_f32_16x16x32_bf16 v[60:63], v[148:151], v[194:197], v[60:63]
	v_mfma_f32_16x16x32_bf16 v[56:59], v[168:171], v[194:197], v[56:59]
	v_mfma_f32_16x16x32_bf16 v[44:47], v[148:151], v[208:211], v[44:47]
	v_mfma_f32_16x16x32_bf16 v[40:43], v[168:171], v[208:211], v[40:43]
	v_mfma_f32_16x16x32_bf16 v[28:31], v[148:151], v[216:219], v[28:31]
	v_mfma_f32_16x16x32_bf16 v[24:27], v[168:171], v[216:219], v[24:27]
	v_lshl_add_u64 v[228:229], s[54:55], 0, v[134:135]
	s_mov_b32 m0, s45
	s_nop 0
	global_load_lds_dwordx4 v[228:229], off
	v_mfma_f32_16x16x32_bf16 v[12:15], v[148:151], v[224:227], v[12:15]
	v_mfma_f32_16x16x32_bf16 v[8:11], v[168:171], v[224:227], v[8:11]
	s_setprio 0
	s_setprio 1
	v_mfma_f32_16x16x32_bf16 v[52:55], v[172:175], v[190:193], v[52:55]
	v_mfma_f32_16x16x32_bf16 v[48:51], v[182:185], v[190:193], v[48:51]
	v_mfma_f32_16x16x32_bf16 v[36:39], v[172:175], v[198:201], v[36:39]
	v_mfma_f32_16x16x32_bf16 v[32:35], v[182:185], v[198:201], v[32:35]
	v_mfma_f32_16x16x32_bf16 v[20:23], v[172:175], v[212:215], v[20:23]
	v_mfma_f32_16x16x32_bf16 v[16:19], v[182:185], v[212:215], v[16:19]
	v_mfma_f32_16x16x32_bf16 v[4:7], v[172:175], v[220:223], v[4:7]
	v_mfma_f32_16x16x32_bf16 v[0:3], v[182:185], v[220:223], v[0:3]
	v_mfma_f32_16x16x32_bf16 v[52:55], v[176:179], v[194:197], v[52:55]
	v_mfma_f32_16x16x32_bf16 v[48:51], v[186:189], v[194:197], v[48:51]
	v_mfma_f32_16x16x32_bf16 v[36:39], v[176:179], v[208:211], v[36:39]
	v_mfma_f32_16x16x32_bf16 v[32:35], v[186:189], v[208:211], v[32:35]
	v_mfma_f32_16x16x32_bf16 v[20:23], v[176:179], v[216:219], v[20:23]
	v_mfma_f32_16x16x32_bf16 v[16:19], v[186:189], v[216:219], v[16:19]
	v_lshl_add_u64 v[230:231], s[54:55], 0, v[130:131]
	s_mov_b32 m0, s57
	s_nop 0
	global_load_lds_dwordx4 v[230:231], off
	v_mfma_f32_16x16x32_bf16 v[4:7], v[176:179], v[224:227], v[4:7]
	v_mfma_f32_16x16x32_bf16 v[0:3], v[186:189], v[224:227], v[0:3]
	s_setprio 0
	s_barrier
; #define PG8_STAGE(bufoff, gbase, voff) do { _Pragma("unroll") for (int _i = 0; _i < 2; ++_i) \
;         __builtin_amdgcn_global_load_lds((const unsigned*)((const char*)(gbase) + (voff)[_i]), (PG8_LAS unsigned*)(lds + (bufoff) + ldsw + _i * 8192), 16, 0, 0); } while (0)
; #define PG8_LDA(dst, b, h) do { _Pragma("unroll") for (int m = 0; m < 4; ++m) _Pragma("unroll") for (int k = 0; k < 2; ++k) dst[m][k] = *(const PG8_LAS bf16x8*)(lds + PG8_SA(b, h) + aoff + m * 2048 + k * 1024); } while (0)
; #define PG8_LDB(dst, b, h) do { _Pragma("unroll") for (int n = 0; n < 2; ++n) _Pragma("unroll") for (int k = 0; k < 2; ++k) dst[n][k] = *(const PG8_LAS bf16x8*)(lds + PG8_SB(b, h) + boff + n * 2048 + k * 1024); } while (0)
; #define PG8_MMA(ai, bj, At, Bt) do { __builtin_amdgcn_s_setprio(1); _Pragma("unroll") for (int m = 0; m < 4; ++m) _Pragma("unroll") for (int n = 0; n < 2; ++n) _Pragma("unroll") for (int k = 0; k < 2; ++k) \
;         acc[ai][bj][m][n] = __builtin_amdgcn_mfma_f32_16x16x32_bf16(Bt[n][k], At[m][k], acc[ai][bj][m][n], 0, 0, 0); __builtin_amdgcn_s_setprio(0); } while (0)
; #define PG8_WAIT_V(n) asm volatile("s_waitcnt vmcnt(" #n ")" ::: "memory")
; #define PG8_WAIT_L(n) asm volatile("s_waitcnt lgkmcnt(" #n ")" ::: "memory")
; #define PG8_BAR __builtin_amdgcn_s_barrier()
; #define PG8_SCHED __builtin_amdgcn_sched_barrier(0)
; template <class Epi, class Sched, bool ALIGN_EPI = false, bool SP2 = false>
; __device__ __forceinline__ void gemm_phase(PG8_LAS unsigned char* lds, const Gemm g, const Sched& S, const Epi& E) {
;     ...
;             PG8_LDB(B0, 1, 0); PG8_LDB(B1, 1, 1); PG8_SCHED; PG8_LDA(At, 1, 0); PG8_STAGE(PG8_SA(0, 1), a2 + hstep, voffA);
;             PG8_WAIT_V(8); PG8_WAIT_L(0); PG8_BAR; PG8_MMA(0, 0, At, B0); PG8_MMA(0, 1, At, B1); PG8_BAR; PG8_SCHED;
;             PG8_LDA(At, 1, 1); PG8_STAGE(PG8_SB(1, 0), b3, voffB); PG8_STAGE(PG8_SB(1, 1), b3 + hstep, voffB); PG8_STAGE(PG8_SA(1, 0), a3, voffA);
;             PG8_WAIT_V(8); PG8_WAIT_L(0); PG8_BAR; PG8_MMA(1, 0, At, B0); PG8_MMA(1, 1, At, B1); PG8_BAR; PG8_SCHED;
	s_add_i32 s3, 0, 0x18000
	v_add_u32_e32 v159, s3, v153
	s_add_i32 s33, 0, 0x1c000
	ds_read_b128 v[144:147], v159
	ds_read_b128 v[148:151], v159 offset:1024
	ds_read_b128 v[160:163], v159 offset:2048
	ds_read_b128 v[168:171], v159 offset:3072
	v_add_u32_e32 v159, s33, v153
	ds_read_b128 v[172:175], v159
	ds_read_b128 v[176:179], v159 offset:1024
	ds_read_b128 v[182:185], v159 offset:2048
	ds_read_b128 v[186:189], v159 offset:3072
	s_add_u32 s14, s54, 0x40000
	s_addc_u32 s15, s55, 0
	s_mov_b32 m0, s58
	v_lshl_add_u64 v[232:233], s[14:15], 0, v[134:135]
	ds_read_b128 v[190:193], v157 offset:32768
	ds_read_b128 v[194:197], v157 offset:33792
	ds_read_b128 v[198:201], v157 offset:34816
	ds_read_b128 v[208:211], v157 offset:35840
	ds_read_b128 v[212:215], v157 offset:36864
	ds_read_b128 v[216:219], v157 offset:37888
	ds_read_b128 v[220:223], v157 offset:38912
	ds_read_b128 v[224:227], v157 offset:39936
	global_load_lds_dwordx4 v[232:233], off
	v_lshl_add_u64 v[232:233], s[14:15], 0, v[130:131]
	s_mov_b32 m0, s59
	s_nop 0
	global_load_lds_dwordx4 v[232:233], off
	s_waitcnt vmcnt(8)
	s_waitcnt lgkmcnt(0)
	s_barrier
	s_setprio 1
	s_waitcnt lgkmcnt(0)
	v_mfma_f32_16x16x32_bf16 v[124:127], v[144:147], v[190:193], v[124:127]
	v_mfma_f32_16x16x32_bf16 v[120:123], v[160:163], v[190:193], v[120:123]
	v_mfma_f32_16x16x32_bf16 v[108:111], v[144:147], v[198:201], v[108:111]
	v_mfma_f32_16x16x32_bf16 v[104:107], v[160:163], v[198:201], v[104:107]
	v_mfma_f32_16x16x32_bf16 v[92:95], v[144:147], v[212:215], v[92:95]
	v_mfma_f32_16x16x32_bf16 v[88:91], v[160:163], v[212:215], v[88:91]
	v_mfma_f32_16x16x32_bf16 v[76:79], v[144:147], v[220:223], v[76:79]
	v_mfma_f32_16x16x32_bf16 v[72:75], v[160:163], v[220:223], v[72:75]
	v_mfma_f32_16x16x32_bf16 v[124:127], v[148:151], v[194:197], v[124:127]
	v_mfma_f32_16x16x32_bf16 v[120:123], v[168:171], v[194:197], v[120:123]
	v_mfma_f32_16x16x32_bf16 v[108:111], v[148:151], v[208:211], v[108:111]
	v_mfma_f32_16x16x32_bf16 v[104:107], v[168:171], v[208:211], v[104:107]
	v_mfma_f32_16x16x32_bf16 v[92:95], v[148:151], v[216:219], v[92:95]
	v_mfma_f32_16x16x32_bf16 v[88:91], v[168:171], v[216:219], v[88:91]
	v_mfma_f32_16x16x32_bf16 v[76:79], v[148:151], v[224:227], v[76:79]
	v_mfma_f32_16x16x32_bf16 v[72:75], v[168:171], v[224:227], v[72:75]
	s_setprio 0
	s_setprio 1
	v_mfma_f32_16x16x32_bf16 v[116:119], v[172:175], v[190:193], v[116:119]
	v_mfma_f32_16x16x32_bf16 v[112:115], v[182:185], v[190:193], v[112:115]
	v_mfma_f32_16x16x32_bf16 v[100:103], v[172:175], v[198:201], v[100:103]
	v_mfma_f32_16x16x32_bf16 v[96:99], v[182:185], v[198:201], v[96:99]
	v_mfma_f32_16x16x32_bf16 v[84:87], v[172:175], v[212:215], v[84:87]
	v_mfma_f32_16x16x32_bf16 v[80:83], v[182:185], v[212:215], v[80:83]
	v_mfma_f32_16x16x32_bf16 v[68:71], v[172:175], v[220:223], v[68:71]
	v_mfma_f32_16x16x32_bf16 v[64:67], v[182:185], v[220:223], v[64:67]
	v_mfma_f32_16x16x32_bf16 v[116:119], v[176:179], v[194:197], v[116:119]
	v_mfma_f32_16x16x32_bf16 v[112:115], v[186:189], v[194:197], v[112:115]
	v_mfma_f32_16x16x32_bf16 v[100:103], v[176:179], v[208:211], v[100:103]
	v_mfma_f32_16x16x32_bf16 v[96:99], v[186:189], v[208:211], v[96:99]
	v_mfma_f32_16x16x32_bf16 v[84:87], v[176:179], v[216:219], v[84:87]
	v_mfma_f32_16x16x32_bf16 v[80:83], v[186:189], v[216:219], v[80:83]
	v_mfma_f32_16x16x32_bf16 v[68:71], v[176:179], v[224:227], v[68:71]
	v_mfma_f32_16x16x32_bf16 v[64:67], v[186:189], v[224:227], v[64:67]
	s_setprio 0
	s_barrier
	s_add_i32 s3, s3, s43
	v_lshl_add_u64 v[164:165], v[164:165], 0, s[10:11]
	s_mov_b32 m0, s3
	ds_read_b128 v[190:193], v157 offset:49152
	ds_read_b128 v[194:197], v157 offset:50176
	ds_read_b128 v[198:201], v157 offset:51200
	ds_read_b128 v[208:211], v157 offset:52224
	ds_read_b128 v[212:215], v157 offset:53248
	ds_read_b128 v[216:219], v157 offset:54272
	ds_read_b128 v[220:223], v157 offset:55296
	ds_read_b128 v[224:227], v157 offset:56320
	global_load_lds_dwordx4 v[164:165], off
	s_add_i32 m0, s3, 0x2000
	s_add_u32 s14, s50, 0x40080
	v_lshl_add_u64 v[164:165], v[202:203], 0, s[10:11]
	s_addc_u32 s15, s51, 0
	s_add_i32 s3, s33, s43
	global_load_lds_dwordx4 v[164:165], off
	v_lshl_add_u64 v[164:165], s[14:15], 0, v[132:133]
	s_mov_b32 m0, s3
	s_nop 0
	global_load_lds_dwordx4 v[164:165], off
	v_lshl_add_u64 v[164:165], s[14:15], 0, v[128:129]
	s_add_i32 m0, s3, 0x2000
	s_nop 0
	global_load_lds_dwordx4 v[164:165], off
	s_waitcnt vmcnt(6)
	s_waitcnt lgkmcnt(0)
	s_barrier
; __device__ __forceinline__ unsigned cvtpk(float lo, float hi) { f32x2v_ v = {lo, hi}; bf16x2v_ b = __builtin_convertvector(v, bf16x2v_); return __builtin_bit_cast(unsigned, b); }
; #define PG8_STAGE(bufoff, gbase, voff) do { _Pragma("unroll") for (int _i = 0; _i < 2; ++_i) \
;         __builtin_amdgcn_global_load_lds((const unsigned*)((const char*)(gbase) + (voff)[_i]), (PG8_LAS unsigned*)(lds + (bufoff) + ldsw + _i * 8192), 16, 0, 0); } while (0)
; #define PG8_LDA(dst, b, h) do { _Pragma("unroll") for (int m = 0; m < 4; ++m) _Pragma("unroll") for (int k = 0; k < 2; ++k) dst[m][k] = *(const PG8_LAS bf16x8*)(lds + PG8_SA(b, h) + aoff + m * 2048 + k * 1024); } while (0)
; #define PG8_MMA(ai, bj, At, Bt) do { __builtin_amdgcn_s_setprio(1); _Pragma("unroll") for (int m = 0; m < 4; ++m) _Pragma("unroll") for (int n = 0; n < 2; ++n) _Pragma("unroll") for (int k = 0; k < 2; ++k) \
;         acc[ai][bj][m][n] = __builtin_amdgcn_mfma_f32_16x16x32_bf16(Bt[n][k], At[m][k], acc[ai][bj][m][n], 0, 0, 0); __builtin_amdgcn_s_setprio(0); } while (0)
; #define PG8_WAIT_V(n) asm volatile("s_waitcnt vmcnt(" #n ")" ::: "memory")
;     __device__ __forceinline__ void operator()(const f32x4 (&acc)[2][2][4][2], const Unit& u, int wr, int wc, int fr, int fq) const {
;     ...
;             for (int m = 0; m < 4; ++m) { const int row = row0 + ai * HALF + m * 16; const float rs = row_rs(ss, row);
;                 float hv[8];
; #pragma unroll
;                 for (int n = 0; n < 2; ++n)
; #pragma unroll
;                     for (int i = 0; i < 4; ++i) { const float g = acc[ai][0][m][n][i] * rs, uu = acc[ai][1][m][n][i] * rs;
;                         hv[n * 4 + i] = g * __builtin_amdgcn_rcpf(1.0f + __expf(-g)) * uu; }
;                 u32x4 w; w.x = cvtpk(hv[0], hv[1]); w.y = cvtpk(hv[2], hv[3]); w.z = cvtpk(hv[4], hv[5]); w.w = cvtpk(hv[6], hv[7]);
;                 *(u32x4*)(H + (size_t)row * ldh + col0) = w; }
; template <class Epi, class Sched, bool ALIGN_EPI = false, bool SP2 = false>
; __device__ __forceinline__ void gemm_phase(PG8_LAS unsigned char* lds, const Gemm g, const Sched& S, const Epi& E) {
;     ...
;             PG8_LDA(At, 1, 1); PG8_STAGE(PG8_SB(1, 0), b3, voffB); PG8_STAGE(PG8_SB(1, 1), b3 + hstep, voffB); PG8_STAGE(PG8_SA(1, 0), a3, voffA);
;             PG8_WAIT_V(8); PG8_WAIT_L(0); PG8_BAR; PG8_MMA(1, 0, At, B0); PG8_MMA(1, 1, At, B1); PG8_BAR; PG8_SCHED;
	s_setprio 1
	s_waitcnt lgkmcnt(0)
	v_mfma_f32_16x16x32_bf16 v[60:63], v[144:147], v[190:193], v[60:63]
	v_mfma_f32_16x16x32_bf16 v[56:59], v[160:163], v[190:193], v[56:59]
	v_mfma_f32_16x16x32_bf16 v[44:47], v[144:147], v[198:201], v[44:47]
	v_mfma_f32_16x16x32_bf16 v[40:43], v[160:163], v[198:201], v[40:43]
	v_mfma_f32_16x16x32_bf16 v[28:31], v[144:147], v[212:215], v[28:31]
	v_mfma_f32_16x16x32_bf16 v[24:27], v[160:163], v[212:215], v[24:27]
	v_mfma_f32_16x16x32_bf16 v[12:15], v[144:147], v[220:223], v[12:15]
	v_mfma_f32_16x16x32_bf16 v[8:11], v[160:163], v[220:223], v[8:11]
	v_mfma_f32_16x16x32_bf16 v[60:63], v[148:151], v[194:197], v[60:63]
	v_mfma_f32_16x16x32_bf16 v[56:59], v[168:171], v[194:197], v[56:59]
	v_mfma_f32_16x16x32_bf16 v[44:47], v[148:151], v[208:211], v[44:47]
	v_mfma_f32_16x16x32_bf16 v[40:43], v[168:171], v[208:211], v[40:43]
	v_mfma_f32_16x16x32_bf16 v[28:31], v[148:151], v[216:219], v[28:31]
	v_mfma_f32_16x16x32_bf16 v[24:27], v[168:171], v[216:219], v[24:27]
	v_lshl_add_u64 v[164:165], v[228:229], 0, s[10:11]
	s_mov_b32 m0, s61
	s_nop 0
	global_load_lds_dwordx4 v[164:165], off
	v_mfma_f32_16x16x32_bf16 v[12:15], v[148:151], v[224:227], v[12:15]
	v_mfma_f32_16x16x32_bf16 v[8:11], v[168:171], v[224:227], v[8:11]
	s_setprio 0
	s_setprio 1
	v_mfma_f32_16x16x32_bf16 v[52:55], v[172:175], v[190:193], v[52:55]
	v_mfma_f32_16x16x32_bf16 v[48:51], v[182:185], v[190:193], v[48:51]
	v_mfma_f32_16x16x32_bf16 v[36:39], v[172:175], v[198:201], v[36:39]
	v_mfma_f32_16x16x32_bf16 v[32:35], v[182:185], v[198:201], v[32:35]
	v_mfma_f32_16x16x32_bf16 v[20:23], v[172:175], v[212:215], v[20:23]
	v_mfma_f32_16x16x32_bf16 v[16:19], v[182:185], v[212:215], v[16:19]
	v_mfma_f32_16x16x32_bf16 v[4:7], v[172:175], v[220:223], v[4:7]
	v_mfma_f32_16x16x32_bf16 v[0:3], v[182:185], v[220:223], v[0:3]
	v_mfma_f32_16x16x32_bf16 v[52:55], v[176:179], v[194:197], v[52:55]
	v_mfma_f32_16x16x32_bf16 v[48:51], v[186:189], v[194:197], v[48:51]
	v_mfma_f32_16x16x32_bf16 v[36:39], v[176:179], v[208:211], v[36:39]
	v_mfma_f32_16x16x32_bf16 v[32:35], v[186:189], v[208:211], v[32:35]
	v_mfma_f32_16x16x32_bf16 v[20:23], v[176:179], v[216:219], v[20:23]
	v_mfma_f32_16x16x32_bf16 v[16:19], v[186:189], v[216:219], v[16:19]
	v_lshl_add_u64 v[164:165], v[230:231], 0, s[10:11]
	s_mov_b32 m0, s62
	s_nop 0
	global_load_lds_dwordx4 v[164:165], off
	v_mfma_f32_16x16x32_bf16 v[4:7], v[176:179], v[224:227], v[4:7]
	v_mfma_f32_16x16x32_bf16 v[0:3], v[186:189], v[224:227], v[0:3]
	s_setprio 0
	s_barrier
	s_add_i32 s89, s89, 2
	s_add_u32 s48, s48, 0x100
	s_addc_u32 s49, s49, 0
	s_add_u32 s87, s87, 0x100
	s_addc_u32 s88, s88, 0
	s_cmp_gt_u32 s89, 13
	s_cbranch_scc0 .LBB0_191
	v_lshl_add_u32 v144, s44, 8, v152
	v_ashrrev_i32_e32 v145, 31, v144
	s_and_b64 vcc, exec, s[16:17]
	s_cbranch_vccz .LBB0_194
	s_barrier
.LBB0_194:
	v_lshl_or_b32 v160, s66, 7, v154
	v_ashrrev_i32_e32 v161, 31, v160
	v_or_b32_e32 v164, 16, v144
	v_ashrrev_i32_e32 v165, 31, v164
	v_lshl_add_u64 v[168:169], v[164:165], 3, s[6:7]
	v_mov_b64_e32 v[146:147], s[20:21]
	v_mad_i64_i32 v[162:163], s[14:15], v144, s65, v[146:147]
	s_andn2_b64 vcc, exec, s[0:1]
	s_mov_b64 s[0:1], -1
	s_waitcnt vmcnt(20)
	v_cvt_f32_u32_e32 v159, v235
	v_cvt_f32_u32_e32 v145, v234
	v_lshlrev_b64 v[148:149], 1, v[160:161]
	v_lshl_add_u64 v[162:163], v[162:163], 0, v[148:149]
	v_fmamk_f32 v145, v145, 0x2f800000, v159
	v_fmamk_f32 v145, v145, 0x3a800000, v158
	v_rsq_f32_e32 v160, v145
	s_nop 0
	v_mul_f32_e32 v234, 0xbfb8aa3b, v160
	v_mul_f32_e32 v235, v160, v160
	v_pk_mul_f32 v[160:161], v[124:125], v[234:235] op_sel_hi:[1,0]
	v_pk_mul_f32 v[170:171], v[126:127], v[234:235] op_sel_hi:[1,0]
	v_pk_mul_f32 v[172:173], v[120:121], v[234:235] op_sel_hi:[1,0]
	v_pk_mul_f32 v[174:175], v[122:123], v[234:235] op_sel_hi:[1,0]
	v_pk_mul_f32 v[116:117], v[116:117], v[124:125]
	v_pk_mul_f32 v[118:119], v[118:119], v[126:127]
	v_pk_mul_f32 v[120:121], v[112:113], v[120:121]
	v_pk_mul_f32 v[122:123], v[114:115], v[122:123]
	v_exp_f32_e32 v160, v160
	v_exp_f32_e32 v161, v161
	v_exp_f32_e32 v170, v170
	v_exp_f32_e32 v171, v171
	v_exp_f32_e32 v172, v172
	v_exp_f32_e32 v173, v173
	v_exp_f32_e32 v174, v174
	v_exp_f32_e32 v175, v175
	v_pk_mul_f32 v[116:117], v[116:117], v[234:235] op_sel:[0,1] op_sel_hi:[1,1]
	v_pk_mul_f32 v[118:119], v[118:119], v[234:235] op_sel:[0,1] op_sel_hi:[1,1]
	v_pk_mul_f32 v[120:121], v[120:121], v[234:235] op_sel:[0,1] op_sel_hi:[1,1]
	v_pk_mul_f32 v[122:123], v[122:123], v[234:235] op_sel:[0,1] op_sel_hi:[1,1]
	v_pk_add_f32 v[160:161], v[160:161], 1.0 op_sel_hi:[1,0]
	v_pk_add_f32 v[170:171], v[170:171], 1.0 op_sel_hi:[1,0]
	v_pk_add_f32 v[172:173], v[172:173], 1.0 op_sel_hi:[1,0]
	v_pk_add_f32 v[174:175], v[174:175], 1.0 op_sel_hi:[1,0]
	v_rcp_f32_e32 v160, v160
	v_rcp_f32_e32 v161, v161
	v_rcp_f32_e32 v170, v170
	v_rcp_f32_e32 v171, v171
	v_rcp_f32_e32 v172, v172
	v_rcp_f32_e32 v173, v173
	v_rcp_f32_e32 v174, v174
	v_rcp_f32_e32 v175, v175
	v_pk_mul_f32 v[116:117], v[116:117], v[160:161]
	v_pk_mul_f32 v[118:119], v[118:119], v[170:171]
	v_pk_mul_f32 v[120:121], v[120:121], v[172:173]
	v_pk_mul_f32 v[122:123], v[122:123], v[174:175]
	v_cvt_pk_bf16_f32 v112, v116, v117
	v_cvt_pk_bf16_f32 v113, v118, v119
	v_cvt_pk_bf16_f32 v114, v120, v121
	v_cvt_pk_bf16_f32 v115, v122, v123
	global_store_dwordx4 v[162:163], v[112:115], off
	s_nop 0
	s_nop 0
	v_or_b32_e32 v114, 32, v144
	s_waitcnt vmcnt(7)
; __device__ __forceinline__ unsigned cvtpk(float lo, float hi) { f32x2v_ v = {lo, hi}; bf16x2v_ b = __builtin_convertvector(v, bf16x2v_); return __builtin_bit_cast(unsigned, b); }
; __device__ __forceinline__ float row_rs(const float* ssp, int row) { const unsigned long long v = ((const unsigned long long*)ssp)[row];
;     return __builtin_amdgcn_rsqf((float)v * (1.0f / 4294967296.0f) * (1.0f / 1024.0f) + RMS_EPS); }
;     __device__ __forceinline__ void operator()(const f32x4 (&acc)[2][2][4][2], const Unit& u, int wr, int wc, int fr, int fq) const {
;     ...
;             for (int m = 0; m < 4; ++m) { const int row = row0 + ai * HALF + m * 16; const float rs = row_rs(ss, row);
;                 float hv[8];
; #pragma unroll
;                 for (int n = 0; n < 2; ++n)
; #pragma unroll
;                     for (int i = 0; i < 4; ++i) { const float g = acc[ai][0][m][n][i] * rs, uu = acc[ai][1][m][n][i] * rs;
;                         hv[n * 4 + i] = g * __builtin_amdgcn_rcpf(1.0f + __expf(-g)) * uu; }
;                 u32x4 w; w.x = cvtpk(hv[0], hv[1]); w.y = cvtpk(hv[2], hv[3]); w.z = cvtpk(hv[4], hv[5]); w.w = cvtpk(hv[6], hv[7]);
;                 *(u32x4*)(H + (size_t)row * ldh + col0) = w; }
	v_cvt_f32_u32_e32 v116, v237
	v_cvt_f32_u32_e32 v115, v236
	v_mad_i64_i32 v[112:113], s[14:15], v164, s65, v[146:147]
	v_fmamk_f32 v115, v115, 0x2f800000, v116
	v_fmamk_f32 v115, v115, 0x3a800000, v158
	v_rsq_f32_e32 v116, v115
	v_ashrrev_i32_e32 v115, 31, v114
	v_lshl_add_u64 v[118:119], v[114:115], 3, s[6:7]
	v_lshl_add_u64 v[112:113], v[112:113], 0, v[148:149]
	v_mul_f32_e32 v236, 0xbfb8aa3b, v116
	v_mul_f32_e32 v237, v116, v116
	v_pk_mul_f32 v[116:117], v[108:109], v[236:237] op_sel_hi:[1,0]
	v_pk_mul_f32 v[120:121], v[110:111], v[236:237] op_sel_hi:[1,0]
	v_pk_mul_f32 v[122:123], v[104:105], v[236:237] op_sel_hi:[1,0]
	v_pk_mul_f32 v[124:125], v[106:107], v[236:237] op_sel_hi:[1,0]
	v_pk_mul_f32 v[100:101], v[100:101], v[108:109]
	v_pk_mul_f32 v[102:103], v[102:103], v[110:111]
	v_pk_mul_f32 v[104:105], v[96:97], v[104:105]
	v_pk_mul_f32 v[106:107], v[98:99], v[106:107]
	v_exp_f32_e32 v116, v116
	v_exp_f32_e32 v117, v117
	v_exp_f32_e32 v120, v120
	v_exp_f32_e32 v121, v121
	v_exp_f32_e32 v122, v122
	v_exp_f32_e32 v123, v123
	v_exp_f32_e32 v124, v124
	v_exp_f32_e32 v125, v125
	v_pk_mul_f32 v[100:101], v[100:101], v[236:237] op_sel:[0,1] op_sel_hi:[1,1]
	v_pk_mul_f32 v[102:103], v[102:103], v[236:237] op_sel:[0,1] op_sel_hi:[1,1]
	v_pk_mul_f32 v[104:105], v[104:105], v[236:237] op_sel:[0,1] op_sel_hi:[1,1]
	v_pk_mul_f32 v[106:107], v[106:107], v[236:237] op_sel:[0,1] op_sel_hi:[1,1]
	v_pk_add_f32 v[116:117], v[116:117], 1.0 op_sel_hi:[1,0]
	v_pk_add_f32 v[120:121], v[120:121], 1.0 op_sel_hi:[1,0]
	v_pk_add_f32 v[122:123], v[122:123], 1.0 op_sel_hi:[1,0]
	v_pk_add_f32 v[124:125], v[124:125], 1.0 op_sel_hi:[1,0]
	v_rcp_f32_e32 v116, v116
	v_rcp_f32_e32 v117, v117
	v_rcp_f32_e32 v120, v120
	v_rcp_f32_e32 v121, v121
	v_rcp_f32_e32 v122, v122
	v_rcp_f32_e32 v123, v123
	v_rcp_f32_e32 v124, v124
	v_rcp_f32_e32 v125, v125
	v_pk_mul_f32 v[100:101], v[100:101], v[116:117]
	v_pk_mul_f32 v[102:103], v[102:103], v[120:121]
	v_pk_mul_f32 v[104:105], v[104:105], v[122:123]
	v_pk_mul_f32 v[106:107], v[106:107], v[124:125]
	v_cvt_pk_bf16_f32 v96, v100, v101
	v_cvt_pk_bf16_f32 v97, v102, v103
	v_cvt_pk_bf16_f32 v98, v104, v105
	v_cvt_pk_bf16_f32 v99, v106, v107
	global_store_dwordx4 v[112:113], v[96:99], off
	s_nop 0
	s_nop 0
	v_or_b32_e32 v98, 48, v144
	s_waitcnt vmcnt(7)
	v_cvt_f32_u32_e32 v100, v239
	v_cvt_f32_u32_e32 v99, v238
	v_mad_i64_i32 v[96:97], s[14:15], v114, s65, v[146:147]
	v_fmamk_f32 v99, v99, 0x2f800000, v100
	v_fmamk_f32 v99, v99, 0x3a800000, v158
	v_rsq_f32_e32 v100, v99
	v_ashrrev_i32_e32 v99, 31, v98
	v_lshl_add_u64 v[102:103], v[98:99], 3, s[6:7]
	v_lshl_add_u64 v[96:97], v[96:97], 0, v[148:149]
	v_mul_f32_e32 v238, 0xbfb8aa3b, v100
	v_mul_f32_e32 v239, v100, v100
	v_pk_mul_f32 v[100:101], v[92:93], v[238:239] op_sel_hi:[1,0]
	v_pk_mul_f32 v[104:105], v[94:95], v[238:239] op_sel_hi:[1,0]
	v_pk_mul_f32 v[106:107], v[88:89], v[238:239] op_sel_hi:[1,0]
	v_pk_mul_f32 v[108:109], v[90:91], v[238:239] op_sel_hi:[1,0]
	v_pk_mul_f32 v[84:85], v[84:85], v[92:93]
	v_pk_mul_f32 v[86:87], v[86:87], v[94:95]
	v_pk_mul_f32 v[88:89], v[80:81], v[88:89]
	v_pk_mul_f32 v[90:91], v[82:83], v[90:91]
	v_exp_f32_e32 v100, v100
	v_exp_f32_e32 v101, v101
	v_exp_f32_e32 v104, v104
	v_exp_f32_e32 v105, v105
	v_exp_f32_e32 v106, v106
	v_exp_f32_e32 v107, v107
	v_exp_f32_e32 v108, v108
	v_exp_f32_e32 v109, v109
	v_pk_mul_f32 v[84:85], v[84:85], v[238:239] op_sel:[0,1] op_sel_hi:[1,1]
	v_pk_mul_f32 v[86:87], v[86:87], v[238:239] op_sel:[0,1] op_sel_hi:[1,1]
	v_pk_mul_f32 v[88:89], v[88:89], v[238:239] op_sel:[0,1] op_sel_hi:[1,1]
	v_pk_mul_f32 v[90:91], v[90:91], v[238:239] op_sel:[0,1] op_sel_hi:[1,1]
	v_pk_add_f32 v[100:101], v[100:101], 1.0 op_sel_hi:[1,0]
	v_pk_add_f32 v[104:105], v[104:105], 1.0 op_sel_hi:[1,0]
	v_pk_add_f32 v[106:107], v[106:107], 1.0 op_sel_hi:[1,0]
	v_pk_add_f32 v[108:109], v[108:109], 1.0 op_sel_hi:[1,0]
	v_rcp_f32_e32 v100, v100
	v_rcp_f32_e32 v101, v101
	v_rcp_f32_e32 v104, v104
	v_rcp_f32_e32 v105, v105
	v_rcp_f32_e32 v106, v106
	v_rcp_f32_e32 v107, v107
	v_rcp_f32_e32 v108, v108
	v_rcp_f32_e32 v109, v109
	v_pk_mul_f32 v[84:85], v[84:85], v[100:101]
	v_pk_mul_f32 v[86:87], v[86:87], v[104:105]
	v_pk_mul_f32 v[88:89], v[88:89], v[106:107]
	v_pk_mul_f32 v[90:91], v[90:91], v[108:109]
	v_cvt_pk_bf16_f32 v80, v84, v85
	v_cvt_pk_bf16_f32 v81, v86, v87
	v_cvt_pk_bf16_f32 v82, v88, v89
	v_cvt_pk_bf16_f32 v83, v90, v91
	global_store_dwordx4 v[96:97], v[80:83], off
	s_nop 0
	s_waitcnt vmcnt(7)
	v_cvt_f32_u32_e32 v80, v241
	v_cvt_f32_u32_e32 v81, v240
	v_mad_i64_i32 v[82:83], s[14:15], v98, s65, v[146:147]
	v_fmamk_f32 v80, v81, 0x2f800000, v80
	v_fmamk_f32 v80, v80, 0x3a800000, v158
	v_rsq_f32_e32 v80, v80
	v_lshl_add_u64 v[82:83], v[82:83], 0, v[148:149]
	v_mul_f32_e32 v240, 0xbfb8aa3b, v80
	v_mul_f32_e32 v241, v80, v80
	v_pk_mul_f32 v[80:81], v[76:77], v[240:241] op_sel_hi:[1,0]
	v_pk_mul_f32 v[84:85], v[78:79], v[240:241] op_sel_hi:[1,0]
	v_pk_mul_f32 v[86:87], v[72:73], v[240:241] op_sel_hi:[1,0]
	v_pk_mul_f32 v[88:89], v[74:75], v[240:241] op_sel_hi:[1,0]
	v_pk_mul_f32 v[68:69], v[68:69], v[76:77]
	v_pk_mul_f32 v[70:71], v[70:71], v[78:79]
	v_pk_mul_f32 v[72:73], v[64:65], v[72:73]
	v_pk_mul_f32 v[74:75], v[66:67], v[74:75]
	v_exp_f32_e32 v80, v80
	v_exp_f32_e32 v81, v81
	v_exp_f32_e32 v84, v84
	v_exp_f32_e32 v85, v85
	v_exp_f32_e32 v86, v86
	v_exp_f32_e32 v87, v87
	v_exp_f32_e32 v88, v88
	v_exp_f32_e32 v89, v89
	v_pk_mul_f32 v[68:69], v[68:69], v[240:241] op_sel:[0,1] op_sel_hi:[1,1]
	v_pk_mul_f32 v[70:71], v[70:71], v[240:241] op_sel:[0,1] op_sel_hi:[1,1]
	v_pk_mul_f32 v[72:73], v[72:73], v[240:241] op_sel:[0,1] op_sel_hi:[1,1]
	v_pk_mul_f32 v[74:75], v[74:75], v[240:241] op_sel:[0,1] op_sel_hi:[1,1]
	v_pk_add_f32 v[80:81], v[80:81], 1.0 op_sel_hi:[1,0]
	v_pk_add_f32 v[84:85], v[84:85], 1.0 op_sel_hi:[1,0]
	v_pk_add_f32 v[86:87], v[86:87], 1.0 op_sel_hi:[1,0]
	v_pk_add_f32 v[88:89], v[88:89], 1.0 op_sel_hi:[1,0]
	v_rcp_f32_e32 v80, v80
	v_rcp_f32_e32 v81, v81
	v_rcp_f32_e32 v84, v84
	v_rcp_f32_e32 v85, v85
	v_rcp_f32_e32 v86, v86
	v_rcp_f32_e32 v87, v87
	v_rcp_f32_e32 v88, v88
	v_rcp_f32_e32 v89, v89
	v_pk_mul_f32 v[68:69], v[68:69], v[80:81]
	v_pk_mul_f32 v[70:71], v[70:71], v[84:85]
	v_pk_mul_f32 v[72:73], v[72:73], v[86:87]
	v_pk_mul_f32 v[74:75], v[74:75], v[88:89]
	v_cvt_pk_bf16_f32 v64, v68, v69
	v_cvt_pk_bf16_f32 v65, v70, v71
	v_cvt_pk_bf16_f32 v66, v72, v73
	v_cvt_pk_bf16_f32 v67, v74, v75
	global_store_dwordx4 v[82:83], v[64:67], off
	s_nop 0
	s_waitcnt vmcnt(7)
; __device__ __forceinline__ unsigned cvtpk(float lo, float hi) { f32x2v_ v = {lo, hi}; bf16x2v_ b = __builtin_convertvector(v, bf16x2v_); return __builtin_bit_cast(unsigned, b); }
;     __device__ __forceinline__ void operator()(const f32x4 (&acc)[2][2][4][2], const Unit& u, int wr, int wc, int fr, int fq) const {
;     ...
;             for (int m = 0; m < 4; ++m) { const int row = row0 + ai * HALF + m * 16; const float rs = row_rs(ss, row);
;                 float hv[8];
; #pragma unroll
;                 for (int n = 0; n < 2; ++n)
; #pragma unroll
;                     for (int i = 0; i < 4; ++i) { const float g = acc[ai][0][m][n][i] * rs, uu = acc[ai][1][m][n][i] * rs;
;                         hv[n * 4 + i] = g * __builtin_amdgcn_rcpf(1.0f + __expf(-g)) * uu; }
;                 u32x4 w; w.x = cvtpk(hv[0], hv[1]); w.y = cvtpk(hv[2], hv[3]); w.z = cvtpk(hv[4], hv[5]); w.w = cvtpk(hv[6], hv[7]);
;                 *(u32x4*)(H + (size_t)row * ldh + col0) = w; }
	v_cvt_f32_u32_e32 v64, v243
	v_cvt_f32_u32_e32 v66, v242
	v_add_u32_e32 v65, 0x80, v144
	v_fmamk_f32 v64, v66, 0x2f800000, v64
	v_fmamk_f32 v64, v64, 0x3a800000, v158
	v_rsq_f32_e32 v64, v64
	v_mad_i64_i32 v[66:67], s[14:15], v65, s65, v[146:147]
	v_lshl_add_u64 v[66:67], v[66:67], 0, v[148:149]
	v_mul_f32_e32 v242, 0xbfb8aa3b, v64
	v_mul_f32_e32 v243, v64, v64
	v_pk_mul_f32 v[64:65], v[60:61], v[242:243] op_sel_hi:[1,0]
	v_pk_mul_f32 v[68:69], v[62:63], v[242:243] op_sel_hi:[1,0]
	v_pk_mul_f32 v[70:71], v[56:57], v[242:243] op_sel_hi:[1,0]
	v_pk_mul_f32 v[72:73], v[58:59], v[242:243] op_sel_hi:[1,0]
	v_pk_mul_f32 v[52:53], v[52:53], v[60:61]
	v_pk_mul_f32 v[54:55], v[54:55], v[62:63]
	v_pk_mul_f32 v[56:57], v[48:49], v[56:57]
	v_pk_mul_f32 v[58:59], v[50:51], v[58:59]
	v_exp_f32_e32 v64, v64
	v_exp_f32_e32 v65, v65
	v_exp_f32_e32 v68, v68
	v_exp_f32_e32 v69, v69
	v_exp_f32_e32 v70, v70
	v_exp_f32_e32 v71, v71
	v_exp_f32_e32 v72, v72
	v_exp_f32_e32 v73, v73
	v_pk_mul_f32 v[52:53], v[52:53], v[242:243] op_sel:[0,1] op_sel_hi:[1,1]
	v_pk_mul_f32 v[54:55], v[54:55], v[242:243] op_sel:[0,1] op_sel_hi:[1,1]
	v_pk_mul_f32 v[56:57], v[56:57], v[242:243] op_sel:[0,1] op_sel_hi:[1,1]
	v_pk_mul_f32 v[58:59], v[58:59], v[242:243] op_sel:[0,1] op_sel_hi:[1,1]
	v_pk_add_f32 v[64:65], v[64:65], 1.0 op_sel_hi:[1,0]
	v_pk_add_f32 v[68:69], v[68:69], 1.0 op_sel_hi:[1,0]
	v_pk_add_f32 v[70:71], v[70:71], 1.0 op_sel_hi:[1,0]
	v_pk_add_f32 v[72:73], v[72:73], 1.0 op_sel_hi:[1,0]
	v_rcp_f32_e32 v64, v64
	v_rcp_f32_e32 v65, v65
	v_rcp_f32_e32 v68, v68
	v_rcp_f32_e32 v69, v69
	v_rcp_f32_e32 v70, v70
	v_rcp_f32_e32 v71, v71
	v_rcp_f32_e32 v72, v72
	v_rcp_f32_e32 v73, v73
	v_pk_mul_f32 v[52:53], v[52:53], v[64:65]
	v_pk_mul_f32 v[54:55], v[54:55], v[68:69]
	v_pk_mul_f32 v[56:57], v[56:57], v[70:71]
	v_pk_mul_f32 v[58:59], v[58:59], v[72:73]
	v_cvt_pk_bf16_f32 v48, v52, v53
	v_cvt_pk_bf16_f32 v49, v54, v55
	v_cvt_pk_bf16_f32 v50, v56, v57
	v_cvt_pk_bf16_f32 v51, v58, v59
	global_store_dwordx4 v[66:67], v[48:51], off
	s_nop 0
	s_waitcnt vmcnt(7)
	v_cvt_f32_u32_e32 v48, v245
	v_cvt_f32_u32_e32 v50, v244
	v_add_u32_e32 v49, 0x90, v144
	v_fmamk_f32 v48, v50, 0x2f800000, v48
	v_fmamk_f32 v48, v48, 0x3a800000, v158
	v_rsq_f32_e32 v48, v48
	v_mad_i64_i32 v[50:51], s[14:15], v49, s65, v[146:147]
	v_lshl_add_u64 v[50:51], v[50:51], 0, v[148:149]
	v_mul_f32_e32 v244, 0xbfb8aa3b, v48
	v_mul_f32_e32 v245, v48, v48
	v_pk_mul_f32 v[48:49], v[44:45], v[244:245] op_sel_hi:[1,0]
	v_pk_mul_f32 v[52:53], v[46:47], v[244:245] op_sel_hi:[1,0]
	v_pk_mul_f32 v[54:55], v[40:41], v[244:245] op_sel_hi:[1,0]
	v_pk_mul_f32 v[56:57], v[42:43], v[244:245] op_sel_hi:[1,0]
	v_pk_mul_f32 v[36:37], v[36:37], v[44:45]
	v_pk_mul_f32 v[38:39], v[38:39], v[46:47]
	v_pk_mul_f32 v[40:41], v[32:33], v[40:41]
	v_pk_mul_f32 v[42:43], v[34:35], v[42:43]
	v_exp_f32_e32 v48, v48
	v_exp_f32_e32 v49, v49
	v_exp_f32_e32 v52, v52
	v_exp_f32_e32 v53, v53
	v_exp_f32_e32 v54, v54
	v_exp_f32_e32 v55, v55
	v_exp_f32_e32 v56, v56
	v_exp_f32_e32 v57, v57
	v_pk_mul_f32 v[36:37], v[36:37], v[244:245] op_sel:[0,1] op_sel_hi:[1,1]
	v_pk_mul_f32 v[38:39], v[38:39], v[244:245] op_sel:[0,1] op_sel_hi:[1,1]
	v_pk_mul_f32 v[40:41], v[40:41], v[244:245] op_sel:[0,1] op_sel_hi:[1,1]
	v_pk_mul_f32 v[42:43], v[42:43], v[244:245] op_sel:[0,1] op_sel_hi:[1,1]
	v_pk_add_f32 v[48:49], v[48:49], 1.0 op_sel_hi:[1,0]
	v_pk_add_f32 v[52:53], v[52:53], 1.0 op_sel_hi:[1,0]
	v_pk_add_f32 v[54:55], v[54:55], 1.0 op_sel_hi:[1,0]
	v_pk_add_f32 v[56:57], v[56:57], 1.0 op_sel_hi:[1,0]
	v_rcp_f32_e32 v48, v48
	v_rcp_f32_e32 v49, v49
	v_rcp_f32_e32 v52, v52
	v_rcp_f32_e32 v53, v53
	v_rcp_f32_e32 v54, v54
	v_rcp_f32_e32 v55, v55
	v_rcp_f32_e32 v56, v56
	v_rcp_f32_e32 v57, v57
	v_pk_mul_f32 v[36:37], v[36:37], v[48:49]
	v_pk_mul_f32 v[38:39], v[38:39], v[52:53]
	v_pk_mul_f32 v[40:41], v[40:41], v[54:55]
	v_pk_mul_f32 v[42:43], v[42:43], v[56:57]
	v_cvt_pk_bf16_f32 v32, v36, v37
	v_cvt_pk_bf16_f32 v33, v38, v39
	v_cvt_pk_bf16_f32 v34, v40, v41
	v_cvt_pk_bf16_f32 v35, v42, v43
	global_store_dwordx4 v[50:51], v[32:35], off
	s_nop 0
	s_waitcnt vmcnt(7)
; __device__ __forceinline__ unsigned cvtpk(float lo, float hi) { f32x2v_ v = {lo, hi}; bf16x2v_ b = __builtin_convertvector(v, bf16x2v_); return __builtin_bit_cast(unsigned, b); }
;     __device__ __forceinline__ void operator()(const f32x4 (&acc)[2][2][4][2], const Unit& u, int wr, int wc, int fr, int fq) const {
;     ...
;             for (int m = 0; m < 4; ++m) { const int row = row0 + ai * HALF + m * 16; const float rs = row_rs(ss, row);
;                 float hv[8];
; #pragma unroll
;                 for (int n = 0; n < 2; ++n)
; #pragma unroll
;                     for (int i = 0; i < 4; ++i) { const float g = acc[ai][0][m][n][i] * rs, uu = acc[ai][1][m][n][i] * rs;
;                         hv[n * 4 + i] = g * __builtin_amdgcn_rcpf(1.0f + __expf(-g)) * uu; }
;                 u32x4 w; w.x = cvtpk(hv[0], hv[1]); w.y = cvtpk(hv[2], hv[3]); w.z = cvtpk(hv[4], hv[5]); w.w = cvtpk(hv[6], hv[7]);
;                 *(u32x4*)(H + (size_t)row * ldh + col0) = w; }
	v_cvt_f32_u32_e32 v32, v247
	v_cvt_f32_u32_e32 v34, v246
	v_add_u32_e32 v33, 0xa0, v144
	v_fmamk_f32 v32, v34, 0x2f800000, v32
	v_fmamk_f32 v32, v32, 0x3a800000, v158
	v_rsq_f32_e32 v32, v32
	v_mad_i64_i32 v[34:35], s[14:15], v33, s65, v[146:147]
	v_lshl_add_u64 v[34:35], v[34:35], 0, v[148:149]
	v_mul_f32_e32 v246, 0xbfb8aa3b, v32
	v_mul_f32_e32 v247, v32, v32
	v_pk_mul_f32 v[32:33], v[28:29], v[246:247] op_sel_hi:[1,0]
	v_pk_mul_f32 v[36:37], v[30:31], v[246:247] op_sel_hi:[1,0]
	v_pk_mul_f32 v[38:39], v[24:25], v[246:247] op_sel_hi:[1,0]
	v_pk_mul_f32 v[40:41], v[26:27], v[246:247] op_sel_hi:[1,0]
	v_pk_mul_f32 v[20:21], v[20:21], v[28:29]
	v_pk_mul_f32 v[22:23], v[22:23], v[30:31]
	v_pk_mul_f32 v[24:25], v[16:17], v[24:25]
	v_pk_mul_f32 v[26:27], v[18:19], v[26:27]
	v_exp_f32_e32 v32, v32
	v_exp_f32_e32 v33, v33
	v_exp_f32_e32 v36, v36
	v_exp_f32_e32 v37, v37
	v_exp_f32_e32 v38, v38
	v_exp_f32_e32 v39, v39
	v_exp_f32_e32 v40, v40
	v_exp_f32_e32 v41, v41
	v_pk_mul_f32 v[20:21], v[20:21], v[246:247] op_sel:[0,1] op_sel_hi:[1,1]
	v_pk_mul_f32 v[22:23], v[22:23], v[246:247] op_sel:[0,1] op_sel_hi:[1,1]
	v_pk_mul_f32 v[24:25], v[24:25], v[246:247] op_sel:[0,1] op_sel_hi:[1,1]
	v_pk_mul_f32 v[26:27], v[26:27], v[246:247] op_sel:[0,1] op_sel_hi:[1,1]
	v_pk_add_f32 v[32:33], v[32:33], 1.0 op_sel_hi:[1,0]
	v_pk_add_f32 v[36:37], v[36:37], 1.0 op_sel_hi:[1,0]
	v_pk_add_f32 v[38:39], v[38:39], 1.0 op_sel_hi:[1,0]
	v_pk_add_f32 v[40:41], v[40:41], 1.0 op_sel_hi:[1,0]
	v_rcp_f32_e32 v32, v32
	v_rcp_f32_e32 v33, v33
	v_rcp_f32_e32 v36, v36
	v_rcp_f32_e32 v37, v37
	v_rcp_f32_e32 v38, v38
	v_rcp_f32_e32 v39, v39
	v_rcp_f32_e32 v40, v40
	v_rcp_f32_e32 v41, v41
	v_pk_mul_f32 v[20:21], v[20:21], v[32:33]
	v_pk_mul_f32 v[22:23], v[22:23], v[36:37]
	v_pk_mul_f32 v[24:25], v[24:25], v[38:39]
	v_pk_mul_f32 v[26:27], v[26:27], v[40:41]
	v_cvt_pk_bf16_f32 v16, v20, v21
	v_cvt_pk_bf16_f32 v17, v22, v23
	v_cvt_pk_bf16_f32 v18, v24, v25
	v_cvt_pk_bf16_f32 v19, v26, v27
	global_store_dwordx4 v[34:35], v[16:19], off
	s_nop 0
	s_waitcnt vmcnt(7)
	v_cvt_f32_u32_e32 v16, v249
	v_cvt_f32_u32_e32 v18, v248
	v_add_u32_e32 v17, 0xb0, v144
	v_fmamk_f32 v16, v18, 0x2f800000, v16
	v_fmamk_f32 v16, v16, 0x3a800000, v158
	v_rsq_f32_e32 v16, v16
	v_mad_i64_i32 v[18:19], s[14:15], v17, s65, v[146:147]
	v_lshl_add_u64 v[18:19], v[18:19], 0, v[148:149]
	v_mul_f32_e32 v248, 0xbfb8aa3b, v16
	v_mul_f32_e32 v249, v16, v16
	v_pk_mul_f32 v[16:17], v[12:13], v[248:249] op_sel_hi:[1,0]
	v_pk_mul_f32 v[20:21], v[14:15], v[248:249] op_sel_hi:[1,0]
	v_pk_mul_f32 v[22:23], v[8:9], v[248:249] op_sel_hi:[1,0]
	v_pk_mul_f32 v[24:25], v[10:11], v[248:249] op_sel_hi:[1,0]
	v_pk_mul_f32 v[4:5], v[4:5], v[12:13]
	v_pk_mul_f32 v[6:7], v[6:7], v[14:15]
	v_pk_mul_f32 v[8:9], v[0:1], v[8:9]
	v_pk_mul_f32 v[10:11], v[2:3], v[10:11]
	v_exp_f32_e32 v16, v16
	v_exp_f32_e32 v17, v17
	v_exp_f32_e32 v20, v20
	v_exp_f32_e32 v21, v21
	v_exp_f32_e32 v22, v22
	v_exp_f32_e32 v23, v23
	v_exp_f32_e32 v24, v24
	v_exp_f32_e32 v25, v25
	v_pk_mul_f32 v[4:5], v[4:5], v[248:249] op_sel:[0,1] op_sel_hi:[1,1]
	v_pk_mul_f32 v[6:7], v[6:7], v[248:249] op_sel:[0,1] op_sel_hi:[1,1]
	v_pk_mul_f32 v[8:9], v[8:9], v[248:249] op_sel:[0,1] op_sel_hi:[1,1]
	v_pk_mul_f32 v[10:11], v[10:11], v[248:249] op_sel:[0,1] op_sel_hi:[1,1]
	v_pk_add_f32 v[16:17], v[16:17], 1.0 op_sel_hi:[1,0]
	v_pk_add_f32 v[20:21], v[20:21], 1.0 op_sel_hi:[1,0]
	v_pk_add_f32 v[22:23], v[22:23], 1.0 op_sel_hi:[1,0]
	v_pk_add_f32 v[24:25], v[24:25], 1.0 op_sel_hi:[1,0]
	v_rcp_f32_e32 v16, v16
	v_rcp_f32_e32 v17, v17
	v_rcp_f32_e32 v20, v20
	v_rcp_f32_e32 v21, v21
	v_rcp_f32_e32 v22, v22
	v_rcp_f32_e32 v23, v23
	v_rcp_f32_e32 v24, v24
	v_rcp_f32_e32 v25, v25
	v_pk_mul_f32 v[4:5], v[4:5], v[16:17]
	v_pk_mul_f32 v[6:7], v[6:7], v[20:21]
	v_pk_mul_f32 v[8:9], v[8:9], v[22:23]
	v_pk_mul_f32 v[10:11], v[10:11], v[24:25]
	v_cvt_pk_bf16_f32 v0, v4, v5
	v_cvt_pk_bf16_f32 v1, v6, v7
	v_cvt_pk_bf16_f32 v2, v8, v9
	v_cvt_pk_bf16_f32 v3, v10, v11
	global_store_dwordx4 v[18:19], v[0:3], off
	s_cbranch_vccnz .LBB0_187
	s_andn2_b64 vcc, exec, s[8:9]
	s_cbranch_vccnz .LBB0_186
	s_barrier
	s_branch .LBB0_186

; #define PG8_STAGE(bufoff, gbase, voff) do { _Pragma("unroll") for (int _i = 0; _i < 2; ++_i) \
;         __builtin_amdgcn_global_load_lds((const unsigned*)((const char*)(gbase) + (voff)[_i]), (PG8_LAS unsigned*)(lds + (bufoff) + ldsw + _i * 8192), 16, 0, 0); } while (0)
; #define PG8_LDA(dst, b, h) do { _Pragma("unroll") for (int m = 0; m < 4; ++m) _Pragma("unroll") for (int k = 0; k < 2; ++k) dst[m][k] = *(const PG8_LAS bf16x8*)(lds + PG8_SA(b, h) + aoff + m * 2048 + k * 1024); } while (0)
; #define PG8_LDB(dst, b, h) do { _Pragma("unroll") for (int n = 0; n < 2; ++n) _Pragma("unroll") for (int k = 0; k < 2; ++k) dst[n][k] = *(const PG8_LAS bf16x8*)(lds + PG8_SB(b, h) + boff + n * 2048 + k * 1024); } while (0)
; #define PG8_WAIT_V(n) asm volatile("s_waitcnt vmcnt(" #n ")" ::: "memory")
; __device__ __forceinline__ float row_rs(const float* ssp, int row) { const unsigned long long v = ((const unsigned long long*)ssp)[row];
;     return __builtin_amdgcn_rsqf((float)v * (1.0f / 4294967296.0f) * (1.0f / 1024.0f) + RMS_EPS); }
; template <class Epi, class Sched, bool ALIGN_EPI = false, bool SP2 = false>
; __device__ __forceinline__ void gemm_phase(PG8_LAS unsigned char* lds, const Gemm g, const Sched& S, const Epi& E) {
;     ...
;         const char* nA = has_next ? (const char*)g.A + (size_t)nxt.pm * tstep : cA; const char* nB = has_next ? (const char*)g.Bt + (size_t)nxt.pn * tstep : cB;
;         for (int t = 0; t < nt; t += 2) {
;             const bool last = (t == nt - 2);
;             const char* a1 = cA + (size_t)(t + 1) * kstep;
;             const char* a2 = last ? nA : cA + (size_t)(t + 2) * kstep; const char* b2 = last ? nB : cB + (size_t)(t + 2) * kstep;
;             const char* a3 = a2 + kstep; const char* b3 = b2 + kstep;
;             if (last && has_next) S.a_ready(nxt);
;             if constexpr (SP2) {
;             PG8_LDB(B0, 0, 0); PG8_LDB(B1, 0, 1); PG8_SCHED; PG8_LDA(At, 0, 0); PG8_STAGE(PG8_SA(1, 1), a1 + hstep, voffA);
;             PG8_WAIT_V(8); PG8_WAIT_L(0); PG8_BAR; PG8_MMA(0, 0, At, B0); PG8_MMA(0, 1, At, B1); PG8_BAR; PG8_SCHED;
;             PG8_LDA(At, 0, 1); PG8_STAGE(PG8_SB(0, 0), b2, voffB); PG8_STAGE(PG8_SB(0, 1), b2 + hstep, voffB); PG8_STAGE(PG8_SA(0, 0), a2, voffA);
;             PG8_WAIT_V(8); PG8_WAIT_L(0); PG8_BAR; PG8_MMA(1, 0, At, B0); PG8_MMA(1, 1, At, B1); PG8_BAR; PG8_SCHED;
.LBB0_956:
	v_lshl_add_u32 v144, s52, 8, v152
	v_ashrrev_i32_e32 v145, 31, v144
	v_lshl_add_u64 v[150:151], v[144:145], 3, s[0:1]
	global_load_dwordx2 v[234:235], v[150:151], off
	global_load_dwordx2 v[236:237], v[150:151], off offset:128
	global_load_dwordx2 v[238:239], v[150:151], off offset:256
	global_load_dwordx2 v[240:241], v[150:151], off offset:384
	global_load_dwordx2 v[242:243], v[150:151], off offset:1024
	global_load_dwordx2 v[244:245], v[150:151], off offset:1152
	global_load_dwordx2 v[246:247], v[150:151], off offset:1280
	global_load_dwordx2 v[248:249], v[150:151], off offset:1408
	s_ashr_i32 s45, s44, 31
	s_lshl_b64 s[48:49], s[44:45], 19
	s_add_u32 s48, s22, s48
	s_addc_u32 s49, s23, s49
	s_and_b64 s[50:51], s[10:11], exec
	s_cselect_b32 s45, s49, s55
	s_cselect_b32 s75, s48, s54
	s_ashr_i32 s43, s42, 31
	s_lshl_b64 s[50:51], s[42:43], 19
	v_readlane_b32 s3, v250, 18
	s_add_u32 s50, s3, s50
	v_readlane_b32 s3, v250, 19
	s_addc_u32 s51, s3, s51
	s_and_b64 s[58:59], s[10:11], exec
	s_cselect_b32 s43, s51, s57
	s_cselect_b32 s76, s50, s56
	s_add_u32 s54, s54, 0x40080
	s_addc_u32 s55, s55, 0
	s_add_u32 s77, s56, 0x100
	s_addc_u32 s82, s57, 0
	s_mov_b32 s83, -2
	ds_read_b128 v[144:147], v155
	ds_read_b128 v[148:151], v155 offset:1024
	ds_read_b128 v[160:163], v155 offset:2048
	ds_read_b128 v[164:167], v155 offset:3072
	ds_read_b128 v[168:171], v156
	ds_read_b128 v[172:175], v156 offset:1024
	ds_read_b128 v[176:179], v156 offset:2048
	ds_read_b128 v[182:185], v156 offset:3072
	s_add_u32 s3, s54, 0xfffc0080
	s_addc_u32 s33, s55, -1
	s_cmp_eq_u32 s83, 12
	s_cselect_b32 s59, s45, s33
	s_cselect_b32 s58, s75, s3
	s_cselect_b32 s57, s43, s82
	s_cselect_b32 s56, s76, s77
	v_lshl_add_u64 v[202:203], s[54:55], 0, v[136:137]
	s_add_i32 m0, s34, 0xc000
	ds_read_b128 v[186:189], v157
	ds_read_b128 v[190:193], v157 offset:1024
	ds_read_b128 v[194:197], v157 offset:2048
	ds_read_b128 v[198:201], v157 offset:3072
	ds_read_b128 v[208:211], v157 offset:4096
	ds_read_b128 v[212:215], v157 offset:5120
	ds_read_b128 v[216:219], v157 offset:6144
	ds_read_b128 v[220:223], v157 offset:7168
	global_load_lds_dwordx4 v[202:203], off
	v_lshl_add_u64 v[202:203], s[54:55], 0, v[138:139]
	s_add_i32 m0, s34, 0xe000
	s_nop 0
	global_load_lds_dwordx4 v[202:203], off
	s_waitcnt vmcnt(8)
	s_waitcnt lgkmcnt(0)
	s_barrier
	s_setprio 1
	s_waitcnt lgkmcnt(0)
	v_mfma_f32_16x16x32_bf16 v[124:127], v[144:147], v[186:189], 0
	v_mfma_f32_16x16x32_bf16 v[120:123], v[160:163], v[186:189], 0
	v_mfma_f32_16x16x32_bf16 v[108:111], v[144:147], v[194:197], 0
	v_mfma_f32_16x16x32_bf16 v[104:107], v[160:163], v[194:197], 0
	v_mfma_f32_16x16x32_bf16 v[92:95], v[144:147], v[208:211], 0
	v_mfma_f32_16x16x32_bf16 v[88:91], v[160:163], v[208:211], 0
	v_mfma_f32_16x16x32_bf16 v[76:79], v[144:147], v[216:219], 0
	v_mfma_f32_16x16x32_bf16 v[72:75], v[160:163], v[216:219], 0
	v_mfma_f32_16x16x32_bf16 v[124:127], v[148:151], v[190:193], v[124:127]
	v_mfma_f32_16x16x32_bf16 v[120:123], v[164:167], v[190:193], v[120:123]
	v_mfma_f32_16x16x32_bf16 v[108:111], v[148:151], v[198:201], v[108:111]
	v_mfma_f32_16x16x32_bf16 v[104:107], v[164:167], v[198:201], v[104:107]
	v_mfma_f32_16x16x32_bf16 v[92:95], v[148:151], v[212:215], v[92:95]
	v_mfma_f32_16x16x32_bf16 v[88:91], v[164:167], v[212:215], v[88:91]
	v_mfma_f32_16x16x32_bf16 v[76:79], v[148:151], v[220:223], v[76:79]
	v_mfma_f32_16x16x32_bf16 v[72:75], v[164:167], v[220:223], v[72:75]
	s_setprio 0
	s_setprio 1
	v_mfma_f32_16x16x32_bf16 v[116:119], v[168:171], v[186:189], 0
	v_mfma_f32_16x16x32_bf16 v[112:115], v[176:179], v[186:189], 0
	v_mfma_f32_16x16x32_bf16 v[100:103], v[168:171], v[194:197], 0
	v_mfma_f32_16x16x32_bf16 v[96:99], v[176:179], v[194:197], 0
	v_mfma_f32_16x16x32_bf16 v[84:87], v[168:171], v[208:211], 0
	v_mfma_f32_16x16x32_bf16 v[80:83], v[176:179], v[208:211], 0
	v_mfma_f32_16x16x32_bf16 v[68:71], v[168:171], v[216:219], 0
	v_mfma_f32_16x16x32_bf16 v[64:67], v[176:179], v[216:219], 0
	v_mfma_f32_16x16x32_bf16 v[116:119], v[172:175], v[190:193], v[116:119]
	v_mfma_f32_16x16x32_bf16 v[112:115], v[182:185], v[190:193], v[112:115]
	v_mfma_f32_16x16x32_bf16 v[100:103], v[172:175], v[198:201], v[100:103]
	v_mfma_f32_16x16x32_bf16 v[96:99], v[182:185], v[198:201], v[96:99]
	v_mfma_f32_16x16x32_bf16 v[84:87], v[172:175], v[212:215], v[84:87]
	v_mfma_f32_16x16x32_bf16 v[80:83], v[182:185], v[212:215], v[80:83]
	v_mfma_f32_16x16x32_bf16 v[68:71], v[172:175], v[220:223], v[68:71]
	v_mfma_f32_16x16x32_bf16 v[64:67], v[182:185], v[220:223], v[64:67]
	s_setprio 0
	s_barrier
	s_add_i32 s3, s65, s14
	v_lshl_add_u64 v[202:203], s[56:57], 0, v[132:133]
	s_mov_b32 m0, s3
	ds_read_b128 v[186:189], v157 offset:16384
	ds_read_b128 v[190:193], v157 offset:17408
	ds_read_b128 v[194:197], v157 offset:18432
	ds_read_b128 v[198:201], v157 offset:19456
	ds_read_b128 v[208:211], v157 offset:20480
	ds_read_b128 v[212:215], v157 offset:21504
	ds_read_b128 v[216:219], v157 offset:22528
	ds_read_b128 v[220:223], v157 offset:23552
	global_load_lds_dwordx4 v[202:203], off
	s_add_i32 m0, s3, 0x2000
	s_add_u32 s78, s56, 0x40000
	v_lshl_add_u64 v[224:225], s[56:57], 0, v[128:129]
	s_addc_u32 s79, s57, 0
	s_add_i32 s3, s66, s14
	global_load_lds_dwordx4 v[224:225], off
	v_lshl_add_u64 v[226:227], s[78:79], 0, v[132:133]
	s_mov_b32 m0, s3
	global_load_lds_dwordx4 v[226:227], off
	v_lshl_add_u64 v[226:227], s[78:79], 0, v[128:129]
	s_add_i32 m0, s3, 0x2000
	s_nop 0
	global_load_lds_dwordx4 v[226:227], off
	s_waitcnt vmcnt(6)
	s_waitcnt lgkmcnt(0)
	s_barrier
; #define PG8_STAGE(bufoff, gbase, voff) do { _Pragma("unroll") for (int _i = 0; _i < 2; ++_i) \
;         __builtin_amdgcn_global_load_lds((const unsigned*)((const char*)(gbase) + (voff)[_i]), (PG8_LAS unsigned*)(lds + (bufoff) + ldsw + _i * 8192), 16, 0, 0); } while (0)
; #define PG8_LDA(dst, b, h) do { _Pragma("unroll") for (int m = 0; m < 4; ++m) _Pragma("unroll") for (int k = 0; k < 2; ++k) dst[m][k] = *(const PG8_LAS bf16x8*)(lds + PG8_SA(b, h) + aoff + m * 2048 + k * 1024); } while (0)
; #define PG8_LDB(dst, b, h) do { _Pragma("unroll") for (int n = 0; n < 2; ++n) _Pragma("unroll") for (int k = 0; k < 2; ++k) dst[n][k] = *(const PG8_LAS bf16x8*)(lds + PG8_SB(b, h) + boff + n * 2048 + k * 1024); } while (0)
; #define PG8_MMA(ai, bj, At, Bt) do { __builtin_amdgcn_s_setprio(1); _Pragma("unroll") for (int m = 0; m < 4; ++m) _Pragma("unroll") for (int n = 0; n < 2; ++n) _Pragma("unroll") for (int k = 0; k < 2; ++k) \
;         acc[ai][bj][m][n] = __builtin_amdgcn_mfma_f32_16x16x32_bf16(Bt[n][k], At[m][k], acc[ai][bj][m][n], 0, 0, 0); __builtin_amdgcn_s_setprio(0); } while (0)
; #define PG8_WAIT_V(n) asm volatile("s_waitcnt vmcnt(" #n ")" ::: "memory")
; #define PG8_WAIT_L(n) asm volatile("s_waitcnt lgkmcnt(" #n ")" ::: "memory")
; #define PG8_BAR __builtin_amdgcn_s_barrier()
; #define PG8_SCHED __builtin_amdgcn_sched_barrier(0)
; template <class Epi, class Sched, bool ALIGN_EPI = false, bool SP2 = false>
; __device__ __forceinline__ void gemm_phase(PG8_LAS unsigned char* lds, const Gemm g, const Sched& S, const Epi& E) {
;     ...
;             PG8_LDB(B0, 0, 0); PG8_LDB(B1, 0, 1); PG8_SCHED; PG8_LDA(At, 0, 0); PG8_STAGE(PG8_SA(1, 1), a1 + hstep, voffA);
;             PG8_WAIT_V(8); PG8_WAIT_L(0); PG8_BAR; PG8_MMA(0, 0, At, B0); PG8_MMA(0, 1, At, B1); PG8_BAR; PG8_SCHED;
;             PG8_LDA(At, 0, 1); PG8_STAGE(PG8_SB(0, 0), b2, voffB); PG8_STAGE(PG8_SB(0, 1), b2 + hstep, voffB); PG8_STAGE(PG8_SA(0, 0), a2, voffA);
;             PG8_WAIT_V(8); PG8_WAIT_L(0); PG8_BAR; PG8_MMA(1, 0, At, B0); PG8_MMA(1, 1, At, B1); PG8_BAR; PG8_SCHED;
;             PG8_LDB(B0, 1, 0); PG8_LDB(B1, 1, 1); PG8_SCHED; PG8_LDA(At, 1, 0); PG8_STAGE(PG8_SA(0, 1), a2 + hstep, voffA);
;             PG8_WAIT_V(8); PG8_WAIT_L(0); PG8_BAR; PG8_MMA(0, 0, At, B0); PG8_MMA(0, 1, At, B1); PG8_BAR; PG8_SCHED;
	s_setprio 1
	s_waitcnt lgkmcnt(0)
	v_mfma_f32_16x16x32_bf16 v[60:63], v[144:147], v[186:189], 0
	v_mfma_f32_16x16x32_bf16 v[56:59], v[160:163], v[186:189], 0
	v_mfma_f32_16x16x32_bf16 v[44:47], v[144:147], v[194:197], 0
	v_mfma_f32_16x16x32_bf16 v[40:43], v[160:163], v[194:197], 0
	v_mfma_f32_16x16x32_bf16 v[28:31], v[144:147], v[208:211], 0
	v_mfma_f32_16x16x32_bf16 v[24:27], v[160:163], v[208:211], 0
	v_mfma_f32_16x16x32_bf16 v[12:15], v[144:147], v[216:219], 0
	v_mfma_f32_16x16x32_bf16 v[8:11], v[160:163], v[216:219], 0
	v_mfma_f32_16x16x32_bf16 v[60:63], v[148:151], v[190:193], v[60:63]
	v_mfma_f32_16x16x32_bf16 v[56:59], v[164:167], v[190:193], v[56:59]
	v_mfma_f32_16x16x32_bf16 v[44:47], v[148:151], v[198:201], v[44:47]
	v_mfma_f32_16x16x32_bf16 v[40:43], v[164:167], v[198:201], v[40:43]
	v_mfma_f32_16x16x32_bf16 v[28:31], v[148:151], v[212:215], v[28:31]
	v_mfma_f32_16x16x32_bf16 v[24:27], v[164:167], v[212:215], v[24:27]
	v_lshl_add_u64 v[226:227], s[58:59], 0, v[134:135]
	s_mov_b32 m0, s34
	s_nop 0
	global_load_lds_dwordx4 v[226:227], off
	v_mfma_f32_16x16x32_bf16 v[12:15], v[148:151], v[220:223], v[12:15]
	v_mfma_f32_16x16x32_bf16 v[8:11], v[164:167], v[220:223], v[8:11]
	s_setprio 0
	s_setprio 1
	v_mfma_f32_16x16x32_bf16 v[52:55], v[168:171], v[186:189], 0
	v_mfma_f32_16x16x32_bf16 v[48:51], v[176:179], v[186:189], 0
	v_mfma_f32_16x16x32_bf16 v[36:39], v[168:171], v[194:197], 0
	v_mfma_f32_16x16x32_bf16 v[32:35], v[176:179], v[194:197], 0
	v_mfma_f32_16x16x32_bf16 v[20:23], v[168:171], v[208:211], 0
	v_mfma_f32_16x16x32_bf16 v[16:19], v[176:179], v[208:211], 0
	v_mfma_f32_16x16x32_bf16 v[4:7], v[168:171], v[216:219], 0
	v_mfma_f32_16x16x32_bf16 v[0:3], v[176:179], v[216:219], 0
	v_mfma_f32_16x16x32_bf16 v[52:55], v[172:175], v[190:193], v[52:55]
	v_mfma_f32_16x16x32_bf16 v[48:51], v[182:185], v[190:193], v[48:51]
	v_mfma_f32_16x16x32_bf16 v[36:39], v[172:175], v[198:201], v[36:39]
	v_mfma_f32_16x16x32_bf16 v[32:35], v[182:185], v[198:201], v[32:35]
	v_mfma_f32_16x16x32_bf16 v[20:23], v[172:175], v[212:215], v[20:23]
	v_mfma_f32_16x16x32_bf16 v[16:19], v[182:185], v[212:215], v[16:19]
	v_lshl_add_u64 v[228:229], s[58:59], 0, v[130:131]
	s_mov_b32 m0, s53
	s_nop 0
	global_load_lds_dwordx4 v[228:229], off
	v_mfma_f32_16x16x32_bf16 v[4:7], v[172:175], v[220:223], v[4:7]
	v_mfma_f32_16x16x32_bf16 v[0:3], v[182:185], v[220:223], v[0:3]
	s_setprio 0
	s_barrier
	s_add_i32 s3, 0, 0x18000
	v_add_u32_e32 v159, s3, v153
	s_add_i32 s33, 0, 0x1c000
	ds_read_b128 v[144:147], v159
	ds_read_b128 v[148:151], v159 offset:1024
	ds_read_b128 v[160:163], v159 offset:2048
	ds_read_b128 v[164:167], v159 offset:3072
	v_add_u32_e32 v159, s33, v153
	ds_read_b128 v[168:171], v159
	ds_read_b128 v[172:175], v159 offset:1024
	ds_read_b128 v[176:179], v159 offset:2048
	ds_read_b128 v[182:185], v159 offset:3072
	s_add_u32 s58, s58, 0x40000
	s_addc_u32 s59, s59, 0
	s_mov_b32 m0, s60
	v_lshl_add_u64 v[230:231], s[58:59], 0, v[134:135]
	ds_read_b128 v[186:189], v157 offset:32768
	ds_read_b128 v[190:193], v157 offset:33792
	ds_read_b128 v[194:197], v157 offset:34816
	ds_read_b128 v[198:201], v157 offset:35840
	ds_read_b128 v[208:211], v157 offset:36864
	ds_read_b128 v[212:215], v157 offset:37888
	ds_read_b128 v[216:219], v157 offset:38912
	ds_read_b128 v[220:223], v157 offset:39936
	global_load_lds_dwordx4 v[230:231], off
	v_lshl_add_u64 v[230:231], s[58:59], 0, v[130:131]
	s_mov_b32 m0, s61
	s_nop 0
	global_load_lds_dwordx4 v[230:231], off
	s_waitcnt vmcnt(8)
	s_waitcnt lgkmcnt(0)
	s_barrier
	s_setprio 1
	s_waitcnt lgkmcnt(0)
	v_mfma_f32_16x16x32_bf16 v[124:127], v[144:147], v[186:189], v[124:127]
	v_mfma_f32_16x16x32_bf16 v[120:123], v[160:163], v[186:189], v[120:123]
	v_mfma_f32_16x16x32_bf16 v[108:111], v[144:147], v[194:197], v[108:111]
	v_mfma_f32_16x16x32_bf16 v[104:107], v[160:163], v[194:197], v[104:107]
	v_mfma_f32_16x16x32_bf16 v[92:95], v[144:147], v[208:211], v[92:95]
	v_mfma_f32_16x16x32_bf16 v[88:91], v[160:163], v[208:211], v[88:91]
	v_mfma_f32_16x16x32_bf16 v[76:79], v[144:147], v[216:219], v[76:79]
	v_mfma_f32_16x16x32_bf16 v[72:75], v[160:163], v[216:219], v[72:75]
	v_mfma_f32_16x16x32_bf16 v[124:127], v[148:151], v[190:193], v[124:127]
	v_mfma_f32_16x16x32_bf16 v[120:123], v[164:167], v[190:193], v[120:123]
	v_mfma_f32_16x16x32_bf16 v[108:111], v[148:151], v[198:201], v[108:111]
	v_mfma_f32_16x16x32_bf16 v[104:107], v[164:167], v[198:201], v[104:107]
	v_mfma_f32_16x16x32_bf16 v[92:95], v[148:151], v[212:215], v[92:95]
	v_mfma_f32_16x16x32_bf16 v[88:91], v[164:167], v[212:215], v[88:91]
	v_mfma_f32_16x16x32_bf16 v[76:79], v[148:151], v[220:223], v[76:79]
	v_mfma_f32_16x16x32_bf16 v[72:75], v[164:167], v[220:223], v[72:75]
	s_setprio 0
	s_setprio 1
	v_mfma_f32_16x16x32_bf16 v[116:119], v[168:171], v[186:189], v[116:119]
	v_mfma_f32_16x16x32_bf16 v[112:115], v[176:179], v[186:189], v[112:115]
	v_mfma_f32_16x16x32_bf16 v[100:103], v[168:171], v[194:197], v[100:103]
	v_mfma_f32_16x16x32_bf16 v[96:99], v[176:179], v[194:197], v[96:99]
	v_mfma_f32_16x16x32_bf16 v[84:87], v[168:171], v[208:211], v[84:87]
	v_mfma_f32_16x16x32_bf16 v[80:83], v[176:179], v[208:211], v[80:83]
	v_mfma_f32_16x16x32_bf16 v[68:71], v[168:171], v[216:219], v[68:71]
	v_mfma_f32_16x16x32_bf16 v[64:67], v[176:179], v[216:219], v[64:67]
	v_mfma_f32_16x16x32_bf16 v[116:119], v[172:175], v[190:193], v[116:119]
	v_mfma_f32_16x16x32_bf16 v[112:115], v[182:185], v[190:193], v[112:115]
	v_mfma_f32_16x16x32_bf16 v[100:103], v[172:175], v[198:201], v[100:103]
	v_mfma_f32_16x16x32_bf16 v[96:99], v[182:185], v[198:201], v[96:99]
	v_mfma_f32_16x16x32_bf16 v[84:87], v[172:175], v[212:215], v[84:87]
	v_mfma_f32_16x16x32_bf16 v[80:83], v[182:185], v[212:215], v[80:83]
	v_mfma_f32_16x16x32_bf16 v[68:71], v[172:175], v[220:223], v[68:71]
	v_mfma_f32_16x16x32_bf16 v[64:67], v[182:185], v[220:223], v[64:67]
	s_setprio 0
	s_barrier
; #define PG8_STAGE(bufoff, gbase, voff) do { _Pragma("unroll") for (int _i = 0; _i < 2; ++_i) \
;         __builtin_amdgcn_global_load_lds((const unsigned*)((const char*)(gbase) + (voff)[_i]), (PG8_LAS unsigned*)(lds + (bufoff) + ldsw + _i * 8192), 16, 0, 0); } while (0)
; #define PG8_LDA(dst, b, h) do { _Pragma("unroll") for (int m = 0; m < 4; ++m) _Pragma("unroll") for (int k = 0; k < 2; ++k) dst[m][k] = *(const PG8_LAS bf16x8*)(lds + PG8_SA(b, h) + aoff + m * 2048 + k * 1024); } while (0)
; #define PG8_LDB(dst, b, h) do { _Pragma("unroll") for (int n = 0; n < 2; ++n) _Pragma("unroll") for (int k = 0; k < 2; ++k) dst[n][k] = *(const PG8_LAS bf16x8*)(lds + PG8_SB(b, h) + boff + n * 2048 + k * 1024); } while (0)
; #define PG8_MMA(ai, bj, At, Bt) do { __builtin_amdgcn_s_setprio(1); _Pragma("unroll") for (int m = 0; m < 4; ++m) _Pragma("unroll") for (int n = 0; n < 2; ++n) _Pragma("unroll") for (int k = 0; k < 2; ++k) \
;         acc[ai][bj][m][n] = __builtin_amdgcn_mfma_f32_16x16x32_bf16(Bt[n][k], At[m][k], acc[ai][bj][m][n], 0, 0, 0); __builtin_amdgcn_s_setprio(0); } while (0)
; #define PG8_WAIT_V(n) asm volatile("s_waitcnt vmcnt(" #n ")" ::: "memory")
; #define PG8_WAIT_L(n) asm volatile("s_waitcnt lgkmcnt(" #n ")" ::: "memory")
; #define PG8_BAR __builtin_amdgcn_s_barrier()
; #define PG8_SCHED __builtin_amdgcn_sched_barrier(0)
; template <class Epi, class Sched, bool ALIGN_EPI = false, bool SP2 = false>
; __device__ __forceinline__ void gemm_phase(PG8_LAS unsigned char* lds, const Gemm g, const Sched& S, const Epi& E) {
;     ...
;             PG8_LDA(At, 0, 1); PG8_STAGE(PG8_SB(0, 0), b2, voffB); PG8_STAGE(PG8_SB(0, 1), b2 + hstep, voffB); PG8_STAGE(PG8_SA(0, 0), a2, voffA);
;             PG8_WAIT_V(8); PG8_WAIT_L(0); PG8_BAR; PG8_MMA(1, 0, At, B0); PG8_MMA(1, 1, At, B1); PG8_BAR; PG8_SCHED;
;             PG8_LDB(B0, 1, 0); PG8_LDB(B1, 1, 1); PG8_SCHED; PG8_LDA(At, 1, 0); PG8_STAGE(PG8_SA(0, 1), a2 + hstep, voffA);
;             PG8_WAIT_V(8); PG8_WAIT_L(0); PG8_BAR; PG8_MMA(0, 0, At, B0); PG8_MMA(0, 1, At, B1); PG8_BAR; PG8_SCHED;
;             PG8_LDA(At, 1, 1); PG8_STAGE(PG8_SB(1, 0), b3, voffB); PG8_STAGE(PG8_SB(1, 1), b3 + hstep, voffB); PG8_STAGE(PG8_SA(1, 0), a3, voffA);
;             PG8_WAIT_V(8); PG8_WAIT_L(0); PG8_BAR; PG8_MMA(1, 0, At, B0); PG8_MMA(1, 1, At, B1); PG8_BAR; PG8_SCHED;
	s_add_i32 s3, s3, s14
	v_lshl_add_u64 v[202:203], v[202:203], 0, s[36:37]
	s_mov_b32 m0, s3
	ds_read_b128 v[186:189], v157 offset:49152
	ds_read_b128 v[190:193], v157 offset:50176
	ds_read_b128 v[194:197], v157 offset:51200
	ds_read_b128 v[198:201], v157 offset:52224
	ds_read_b128 v[208:211], v157 offset:53248
	ds_read_b128 v[212:215], v157 offset:54272
	ds_read_b128 v[216:219], v157 offset:55296
	ds_read_b128 v[220:223], v157 offset:56320
	global_load_lds_dwordx4 v[202:203], off
	s_add_i32 m0, s3, 0x2000
	s_add_u32 s56, s56, 0x40080
	v_lshl_add_u64 v[202:203], v[224:225], 0, s[36:37]
	s_addc_u32 s57, s57, 0
	s_add_i32 s3, s33, s14
	global_load_lds_dwordx4 v[202:203], off
	v_lshl_add_u64 v[202:203], s[56:57], 0, v[132:133]
	s_mov_b32 m0, s3
	s_nop 0
	global_load_lds_dwordx4 v[202:203], off
	v_lshl_add_u64 v[202:203], s[56:57], 0, v[128:129]
	s_add_i32 m0, s3, 0x2000
	s_nop 0
	global_load_lds_dwordx4 v[202:203], off
	s_waitcnt vmcnt(6)
	s_waitcnt lgkmcnt(0)
	s_barrier
	s_setprio 1
	s_waitcnt lgkmcnt(0)
	v_mfma_f32_16x16x32_bf16 v[60:63], v[144:147], v[186:189], v[60:63]
	v_mfma_f32_16x16x32_bf16 v[56:59], v[160:163], v[186:189], v[56:59]
	v_mfma_f32_16x16x32_bf16 v[44:47], v[144:147], v[194:197], v[44:47]
	v_mfma_f32_16x16x32_bf16 v[40:43], v[160:163], v[194:197], v[40:43]
	v_mfma_f32_16x16x32_bf16 v[28:31], v[144:147], v[208:211], v[28:31]
	v_mfma_f32_16x16x32_bf16 v[24:27], v[160:163], v[208:211], v[24:27]
	v_mfma_f32_16x16x32_bf16 v[12:15], v[144:147], v[216:219], v[12:15]
	v_mfma_f32_16x16x32_bf16 v[8:11], v[160:163], v[216:219], v[8:11]
	v_mfma_f32_16x16x32_bf16 v[60:63], v[148:151], v[190:193], v[60:63]
	v_mfma_f32_16x16x32_bf16 v[56:59], v[164:167], v[190:193], v[56:59]
	v_mfma_f32_16x16x32_bf16 v[44:47], v[148:151], v[198:201], v[44:47]
	v_mfma_f32_16x16x32_bf16 v[40:43], v[164:167], v[198:201], v[40:43]
	v_mfma_f32_16x16x32_bf16 v[28:31], v[148:151], v[212:215], v[28:31]
	v_mfma_f32_16x16x32_bf16 v[24:27], v[164:167], v[212:215], v[24:27]
	v_lshl_add_u64 v[202:203], v[226:227], 0, s[36:37]
	s_mov_b32 m0, s63
	s_nop 0
	global_load_lds_dwordx4 v[202:203], off
	v_mfma_f32_16x16x32_bf16 v[12:15], v[148:151], v[220:223], v[12:15]
	v_mfma_f32_16x16x32_bf16 v[8:11], v[164:167], v[220:223], v[8:11]
	s_setprio 0
	s_setprio 1
	v_mfma_f32_16x16x32_bf16 v[52:55], v[168:171], v[186:189], v[52:55]
	v_mfma_f32_16x16x32_bf16 v[48:51], v[176:179], v[186:189], v[48:51]
	v_mfma_f32_16x16x32_bf16 v[36:39], v[168:171], v[194:197], v[36:39]
	v_mfma_f32_16x16x32_bf16 v[32:35], v[176:179], v[194:197], v[32:35]
	v_mfma_f32_16x16x32_bf16 v[20:23], v[168:171], v[208:211], v[20:23]
	v_mfma_f32_16x16x32_bf16 v[16:19], v[176:179], v[208:211], v[16:19]
	v_mfma_f32_16x16x32_bf16 v[4:7], v[168:171], v[216:219], v[4:7]
	v_mfma_f32_16x16x32_bf16 v[0:3], v[176:179], v[216:219], v[0:3]
	v_mfma_f32_16x16x32_bf16 v[52:55], v[172:175], v[190:193], v[52:55]
	v_mfma_f32_16x16x32_bf16 v[48:51], v[182:185], v[190:193], v[48:51]
	v_mfma_f32_16x16x32_bf16 v[36:39], v[172:175], v[198:201], v[36:39]
	v_mfma_f32_16x16x32_bf16 v[32:35], v[182:185], v[198:201], v[32:35]
	v_mfma_f32_16x16x32_bf16 v[20:23], v[172:175], v[212:215], v[20:23]
	v_mfma_f32_16x16x32_bf16 v[16:19], v[182:185], v[212:215], v[16:19]
	v_lshl_add_u64 v[202:203], v[228:229], 0, s[36:37]
	s_mov_b32 m0, s64
	s_nop 0
	global_load_lds_dwordx4 v[202:203], off
	v_mfma_f32_16x16x32_bf16 v[4:7], v[172:175], v[220:223], v[4:7]
	v_mfma_f32_16x16x32_bf16 v[0:3], v[182:185], v[220:223], v[0:3]
	s_setprio 0
	s_barrier
	s_add_i32 s83, s83, 2
	s_add_u32 s54, s54, 0x100
	s_addc_u32 s55, s55, 0
	s_add_u32 s77, s77, 0x100
	s_addc_u32 s82, s82, 0
.LBB0_957:
	ds_read_b128 v[144:147], v155
	ds_read_b128 v[148:151], v155 offset:1024
	ds_read_b128 v[160:163], v155 offset:2048
	ds_read_b128 v[164:167], v155 offset:3072
	ds_read_b128 v[168:171], v156
	ds_read_b128 v[172:175], v156 offset:1024
	ds_read_b128 v[176:179], v156 offset:2048
	ds_read_b128 v[182:185], v156 offset:3072
	s_add_u32 s3, s54, 0xfffc0080
	s_addc_u32 s33, s55, -1
	s_cmp_eq_u32 s83, 12
	s_cselect_b32 s59, s45, s33
	s_cselect_b32 s58, s75, s3
	s_cselect_b32 s57, s43, s82
	s_cselect_b32 s56, s76, s77
	v_lshl_add_u64 v[202:203], s[54:55], 0, v[136:137]
	s_add_i32 m0, s34, 0xc000
	ds_read_b128 v[186:189], v157
	ds_read_b128 v[190:193], v157 offset:1024
	ds_read_b128 v[194:197], v157 offset:2048
	ds_read_b128 v[198:201], v157 offset:3072
	ds_read_b128 v[208:211], v157 offset:4096
	ds_read_b128 v[212:215], v157 offset:5120
	ds_read_b128 v[216:219], v157 offset:6144
	ds_read_b128 v[220:223], v157 offset:7168
	global_load_lds_dwordx4 v[202:203], off
	v_lshl_add_u64 v[202:203], s[54:55], 0, v[138:139]
	s_add_i32 m0, s34, 0xe000
	s_nop 0
	global_load_lds_dwordx4 v[202:203], off
	s_waitcnt vmcnt(8)
	s_waitcnt lgkmcnt(0)
	s_barrier
; #define PG8_STAGE(bufoff, gbase, voff) do { _Pragma("unroll") for (int _i = 0; _i < 2; ++_i) \
;         __builtin_amdgcn_global_load_lds((const unsigned*)((const char*)(gbase) + (voff)[_i]), (PG8_LAS unsigned*)(lds + (bufoff) + ldsw + _i * 8192), 16, 0, 0); } while (0)
; #define PG8_LDA(dst, b, h) do { _Pragma("unroll") for (int m = 0; m < 4; ++m) _Pragma("unroll") for (int k = 0; k < 2; ++k) dst[m][k] = *(const PG8_LAS bf16x8*)(lds + PG8_SA(b, h) + aoff + m * 2048 + k * 1024); } while (0)
; #define PG8_LDB(dst, b, h) do { _Pragma("unroll") for (int n = 0; n < 2; ++n) _Pragma("unroll") for (int k = 0; k < 2; ++k) dst[n][k] = *(const PG8_LAS bf16x8*)(lds + PG8_SB(b, h) + boff + n * 2048 + k * 1024); } while (0)
; #define PG8_MMA(ai, bj, At, Bt) do { __builtin_amdgcn_s_setprio(1); _Pragma("unroll") for (int m = 0; m < 4; ++m) _Pragma("unroll") for (int n = 0; n < 2; ++n) _Pragma("unroll") for (int k = 0; k < 2; ++k) \
;         acc[ai][bj][m][n] = __builtin_amdgcn_mfma_f32_16x16x32_bf16(Bt[n][k], At[m][k], acc[ai][bj][m][n], 0, 0, 0); __builtin_amdgcn_s_setprio(0); } while (0)
; #define PG8_WAIT_V(n) asm volatile("s_waitcnt vmcnt(" #n ")" ::: "memory")
; template <class Epi, class Sched, bool ALIGN_EPI = false, bool SP2 = false>
; __device__ __forceinline__ void gemm_phase(PG8_LAS unsigned char* lds, const Gemm g, const Sched& S, const Epi& E) {
;     ...
;             PG8_LDB(B0, 0, 0); PG8_LDB(B1, 0, 1); PG8_SCHED; PG8_LDA(At, 0, 0); PG8_STAGE(PG8_SA(1, 1), a1 + hstep, voffA);
;             PG8_WAIT_V(8); PG8_WAIT_L(0); PG8_BAR; PG8_MMA(0, 0, At, B0); PG8_MMA(0, 1, At, B1); PG8_BAR; PG8_SCHED;
;             PG8_LDA(At, 0, 1); PG8_STAGE(PG8_SB(0, 0), b2, voffB); PG8_STAGE(PG8_SB(0, 1), b2 + hstep, voffB); PG8_STAGE(PG8_SA(0, 0), a2, voffA);
;             PG8_WAIT_V(8); PG8_WAIT_L(0); PG8_BAR; PG8_MMA(1, 0, At, B0); PG8_MMA(1, 1, At, B1); PG8_BAR; PG8_SCHED;
;             PG8_LDB(B0, 1, 0); PG8_LDB(B1, 1, 1); PG8_SCHED; PG8_LDA(At, 1, 0); PG8_STAGE(PG8_SA(0, 1), a2 + hstep, voffA);
;             PG8_WAIT_V(8); PG8_WAIT_L(0); PG8_BAR; PG8_MMA(0, 0, At, B0); PG8_MMA(0, 1, At, B1); PG8_BAR; PG8_SCHED;
;             PG8_LDA(At, 1, 1); PG8_STAGE(PG8_SB(1, 0), b3, voffB); PG8_STAGE(PG8_SB(1, 1), b3 + hstep, voffB); PG8_STAGE(PG8_SA(1, 0), a3, voffA);
;             PG8_WAIT_V(8); PG8_WAIT_L(0); PG8_BAR; PG8_MMA(1, 0, At, B0); PG8_MMA(1, 1, At, B1); PG8_BAR; PG8_SCHED;
	s_setprio 1
	s_waitcnt lgkmcnt(0)
	v_mfma_f32_16x16x32_bf16 v[124:127], v[144:147], v[186:189], v[124:127]
	v_mfma_f32_16x16x32_bf16 v[120:123], v[160:163], v[186:189], v[120:123]
	v_mfma_f32_16x16x32_bf16 v[108:111], v[144:147], v[194:197], v[108:111]
	v_mfma_f32_16x16x32_bf16 v[104:107], v[160:163], v[194:197], v[104:107]
	v_mfma_f32_16x16x32_bf16 v[92:95], v[144:147], v[208:211], v[92:95]
	v_mfma_f32_16x16x32_bf16 v[88:91], v[160:163], v[208:211], v[88:91]
	v_mfma_f32_16x16x32_bf16 v[76:79], v[144:147], v[216:219], v[76:79]
	v_mfma_f32_16x16x32_bf16 v[72:75], v[160:163], v[216:219], v[72:75]
	v_mfma_f32_16x16x32_bf16 v[124:127], v[148:151], v[190:193], v[124:127]
	v_mfma_f32_16x16x32_bf16 v[120:123], v[164:167], v[190:193], v[120:123]
	v_mfma_f32_16x16x32_bf16 v[108:111], v[148:151], v[198:201], v[108:111]
	v_mfma_f32_16x16x32_bf16 v[104:107], v[164:167], v[198:201], v[104:107]
	v_mfma_f32_16x16x32_bf16 v[92:95], v[148:151], v[212:215], v[92:95]
	v_mfma_f32_16x16x32_bf16 v[88:91], v[164:167], v[212:215], v[88:91]
	v_mfma_f32_16x16x32_bf16 v[76:79], v[148:151], v[220:223], v[76:79]
	v_mfma_f32_16x16x32_bf16 v[72:75], v[164:167], v[220:223], v[72:75]
	s_setprio 0
	s_setprio 1
	v_mfma_f32_16x16x32_bf16 v[116:119], v[168:171], v[186:189], v[116:119]
	v_mfma_f32_16x16x32_bf16 v[112:115], v[176:179], v[186:189], v[112:115]
	v_mfma_f32_16x16x32_bf16 v[100:103], v[168:171], v[194:197], v[100:103]
	v_mfma_f32_16x16x32_bf16 v[96:99], v[176:179], v[194:197], v[96:99]
	v_mfma_f32_16x16x32_bf16 v[84:87], v[168:171], v[208:211], v[84:87]
	v_mfma_f32_16x16x32_bf16 v[80:83], v[176:179], v[208:211], v[80:83]
	v_mfma_f32_16x16x32_bf16 v[68:71], v[168:171], v[216:219], v[68:71]
	v_mfma_f32_16x16x32_bf16 v[64:67], v[176:179], v[216:219], v[64:67]
	v_mfma_f32_16x16x32_bf16 v[116:119], v[172:175], v[190:193], v[116:119]
	v_mfma_f32_16x16x32_bf16 v[112:115], v[182:185], v[190:193], v[112:115]
	v_mfma_f32_16x16x32_bf16 v[100:103], v[172:175], v[198:201], v[100:103]
	v_mfma_f32_16x16x32_bf16 v[96:99], v[182:185], v[198:201], v[96:99]
	v_mfma_f32_16x16x32_bf16 v[84:87], v[172:175], v[212:215], v[84:87]
	v_mfma_f32_16x16x32_bf16 v[80:83], v[182:185], v[212:215], v[80:83]
	v_mfma_f32_16x16x32_bf16 v[68:71], v[172:175], v[220:223], v[68:71]
	v_mfma_f32_16x16x32_bf16 v[64:67], v[182:185], v[220:223], v[64:67]
	s_setprio 0
	s_barrier
	s_add_i32 s3, s65, s14
	v_lshl_add_u64 v[202:203], s[56:57], 0, v[132:133]
	s_mov_b32 m0, s3
	ds_read_b128 v[186:189], v157 offset:16384
	ds_read_b128 v[190:193], v157 offset:17408
	ds_read_b128 v[194:197], v157 offset:18432
	ds_read_b128 v[198:201], v157 offset:19456
	ds_read_b128 v[208:211], v157 offset:20480
	ds_read_b128 v[212:215], v157 offset:21504
	ds_read_b128 v[216:219], v157 offset:22528
	ds_read_b128 v[220:223], v157 offset:23552
	global_load_lds_dwordx4 v[202:203], off
	s_add_i32 m0, s3, 0x2000
	s_add_u32 s78, s56, 0x40000
	v_lshl_add_u64 v[224:225], s[56:57], 0, v[128:129]
	s_addc_u32 s79, s57, 0
	s_add_i32 s3, s66, s14
	global_load_lds_dwordx4 v[224:225], off
	v_lshl_add_u64 v[226:227], s[78:79], 0, v[132:133]
	s_mov_b32 m0, s3
	global_load_lds_dwordx4 v[226:227], off
	v_lshl_add_u64 v[226:227], s[78:79], 0, v[128:129]
	s_add_i32 m0, s3, 0x2000
	s_nop 0
	global_load_lds_dwordx4 v[226:227], off
	s_waitcnt vmcnt(6)
	s_waitcnt lgkmcnt(0)
	s_barrier
	s_setprio 1
	s_waitcnt lgkmcnt(0)
	v_mfma_f32_16x16x32_bf16 v[60:63], v[144:147], v[186:189], v[60:63]
	v_mfma_f32_16x16x32_bf16 v[56:59], v[160:163], v[186:189], v[56:59]
	v_mfma_f32_16x16x32_bf16 v[44:47], v[144:147], v[194:197], v[44:47]
	v_mfma_f32_16x16x32_bf16 v[40:43], v[160:163], v[194:197], v[40:43]
	v_mfma_f32_16x16x32_bf16 v[28:31], v[144:147], v[208:211], v[28:31]
	v_mfma_f32_16x16x32_bf16 v[24:27], v[160:163], v[208:211], v[24:27]
	v_mfma_f32_16x16x32_bf16 v[12:15], v[144:147], v[216:219], v[12:15]
	v_mfma_f32_16x16x32_bf16 v[8:11], v[160:163], v[216:219], v[8:11]
	v_mfma_f32_16x16x32_bf16 v[60:63], v[148:151], v[190:193], v[60:63]
	v_mfma_f32_16x16x32_bf16 v[56:59], v[164:167], v[190:193], v[56:59]
	v_mfma_f32_16x16x32_bf16 v[44:47], v[148:151], v[198:201], v[44:47]
	v_mfma_f32_16x16x32_bf16 v[40:43], v[164:167], v[198:201], v[40:43]
	v_mfma_f32_16x16x32_bf16 v[28:31], v[148:151], v[212:215], v[28:31]
	v_mfma_f32_16x16x32_bf16 v[24:27], v[164:167], v[212:215], v[24:27]
	v_lshl_add_u64 v[226:227], s[58:59], 0, v[134:135]
	s_mov_b32 m0, s34
	s_nop 0
	global_load_lds_dwordx4 v[226:227], off
	v_mfma_f32_16x16x32_bf16 v[12:15], v[148:151], v[220:223], v[12:15]
	v_mfma_f32_16x16x32_bf16 v[8:11], v[164:167], v[220:223], v[8:11]
	s_setprio 0
	s_setprio 1
	v_mfma_f32_16x16x32_bf16 v[52:55], v[168:171], v[186:189], v[52:55]
	v_mfma_f32_16x16x32_bf16 v[48:51], v[176:179], v[186:189], v[48:51]
	v_mfma_f32_16x16x32_bf16 v[36:39], v[168:171], v[194:197], v[36:39]
	v_mfma_f32_16x16x32_bf16 v[32:35], v[176:179], v[194:197], v[32:35]
	v_mfma_f32_16x16x32_bf16 v[20:23], v[168:171], v[208:211], v[20:23]
	v_mfma_f32_16x16x32_bf16 v[16:19], v[176:179], v[208:211], v[16:19]
	v_mfma_f32_16x16x32_bf16 v[4:7], v[168:171], v[216:219], v[4:7]
	v_mfma_f32_16x16x32_bf16 v[0:3], v[176:179], v[216:219], v[0:3]
	v_mfma_f32_16x16x32_bf16 v[52:55], v[172:175], v[190:193], v[52:55]
	v_mfma_f32_16x16x32_bf16 v[48:51], v[182:185], v[190:193], v[48:51]
	v_mfma_f32_16x16x32_bf16 v[36:39], v[172:175], v[198:201], v[36:39]
	v_mfma_f32_16x16x32_bf16 v[32:35], v[182:185], v[198:201], v[32:35]
	v_mfma_f32_16x16x32_bf16 v[20:23], v[172:175], v[212:215], v[20:23]
	v_mfma_f32_16x16x32_bf16 v[16:19], v[182:185], v[212:215], v[16:19]
	v_lshl_add_u64 v[228:229], s[58:59], 0, v[130:131]
	s_mov_b32 m0, s53
	s_nop 0
	global_load_lds_dwordx4 v[228:229], off
	v_mfma_f32_16x16x32_bf16 v[4:7], v[172:175], v[220:223], v[4:7]
	v_mfma_f32_16x16x32_bf16 v[0:3], v[182:185], v[220:223], v[0:3]
	s_setprio 0
	s_barrier
; #define PG8_STAGE(bufoff, gbase, voff) do { _Pragma("unroll") for (int _i = 0; _i < 2; ++_i) \
;         __builtin_amdgcn_global_load_lds((const unsigned*)((const char*)(gbase) + (voff)[_i]), (PG8_LAS unsigned*)(lds + (bufoff) + ldsw + _i * 8192), 16, 0, 0); } while (0)
; #define PG8_LDA(dst, b, h) do { _Pragma("unroll") for (int m = 0; m < 4; ++m) _Pragma("unroll") for (int k = 0; k < 2; ++k) dst[m][k] = *(const PG8_LAS bf16x8*)(lds + PG8_SA(b, h) + aoff + m * 2048 + k * 1024); } while (0)
; #define PG8_LDB(dst, b, h) do { _Pragma("unroll") for (int n = 0; n < 2; ++n) _Pragma("unroll") for (int k = 0; k < 2; ++k) dst[n][k] = *(const PG8_LAS bf16x8*)(lds + PG8_SB(b, h) + boff + n * 2048 + k * 1024); } while (0)
; #define PG8_MMA(ai, bj, At, Bt) do { __builtin_amdgcn_s_setprio(1); _Pragma("unroll") for (int m = 0; m < 4; ++m) _Pragma("unroll") for (int n = 0; n < 2; ++n) _Pragma("unroll") for (int k = 0; k < 2; ++k) \
;         acc[ai][bj][m][n] = __builtin_amdgcn_mfma_f32_16x16x32_bf16(Bt[n][k], At[m][k], acc[ai][bj][m][n], 0, 0, 0); __builtin_amdgcn_s_setprio(0); } while (0)
; #define PG8_WAIT_V(n) asm volatile("s_waitcnt vmcnt(" #n ")" ::: "memory")
; #define PG8_WAIT_L(n) asm volatile("s_waitcnt lgkmcnt(" #n ")" ::: "memory")
; #define PG8_BAR __builtin_amdgcn_s_barrier()
; #define PG8_SCHED __builtin_amdgcn_sched_barrier(0)
; template <class Epi, class Sched, bool ALIGN_EPI = false, bool SP2 = false>
; __device__ __forceinline__ void gemm_phase(PG8_LAS unsigned char* lds, const Gemm g, const Sched& S, const Epi& E) {
;     ...
;             PG8_LDB(B0, 1, 0); PG8_LDB(B1, 1, 1); PG8_SCHED; PG8_LDA(At, 1, 0); PG8_STAGE(PG8_SA(0, 1), a2 + hstep, voffA);
;             PG8_WAIT_V(8); PG8_WAIT_L(0); PG8_BAR; PG8_MMA(0, 0, At, B0); PG8_MMA(0, 1, At, B1); PG8_BAR; PG8_SCHED;
;             PG8_LDA(At, 1, 1); PG8_STAGE(PG8_SB(1, 0), b3, voffB); PG8_STAGE(PG8_SB(1, 1), b3 + hstep, voffB); PG8_STAGE(PG8_SA(1, 0), a3, voffA);
;             PG8_WAIT_V(8); PG8_WAIT_L(0); PG8_BAR; PG8_MMA(1, 0, At, B0); PG8_MMA(1, 1, At, B1); PG8_BAR; PG8_SCHED;
	s_add_i32 s3, 0, 0x18000
	v_add_u32_e32 v159, s3, v153
	s_add_i32 s33, 0, 0x1c000
	ds_read_b128 v[144:147], v159
	ds_read_b128 v[148:151], v159 offset:1024
	ds_read_b128 v[160:163], v159 offset:2048
	ds_read_b128 v[164:167], v159 offset:3072
	v_add_u32_e32 v159, s33, v153
	ds_read_b128 v[168:171], v159
	ds_read_b128 v[172:175], v159 offset:1024
	ds_read_b128 v[176:179], v159 offset:2048
	ds_read_b128 v[182:185], v159 offset:3072
	s_add_u32 s58, s58, 0x40000
	s_addc_u32 s59, s59, 0
	s_mov_b32 m0, s60
	v_lshl_add_u64 v[230:231], s[58:59], 0, v[134:135]
	ds_read_b128 v[186:189], v157 offset:32768
	ds_read_b128 v[190:193], v157 offset:33792
	ds_read_b128 v[194:197], v157 offset:34816
	ds_read_b128 v[198:201], v157 offset:35840
	ds_read_b128 v[208:211], v157 offset:36864
	ds_read_b128 v[212:215], v157 offset:37888
	ds_read_b128 v[216:219], v157 offset:38912
	ds_read_b128 v[220:223], v157 offset:39936
	global_load_lds_dwordx4 v[230:231], off
	v_lshl_add_u64 v[230:231], s[58:59], 0, v[130:131]
	s_mov_b32 m0, s61
	s_nop 0
	global_load_lds_dwordx4 v[230:231], off
	s_waitcnt vmcnt(8)
	s_waitcnt lgkmcnt(0)
	s_barrier
	s_setprio 1
	s_waitcnt lgkmcnt(0)
	v_mfma_f32_16x16x32_bf16 v[124:127], v[144:147], v[186:189], v[124:127]
	v_mfma_f32_16x16x32_bf16 v[120:123], v[160:163], v[186:189], v[120:123]
	v_mfma_f32_16x16x32_bf16 v[108:111], v[144:147], v[194:197], v[108:111]
	v_mfma_f32_16x16x32_bf16 v[104:107], v[160:163], v[194:197], v[104:107]
	v_mfma_f32_16x16x32_bf16 v[92:95], v[144:147], v[208:211], v[92:95]
	v_mfma_f32_16x16x32_bf16 v[88:91], v[160:163], v[208:211], v[88:91]
	v_mfma_f32_16x16x32_bf16 v[76:79], v[144:147], v[216:219], v[76:79]
	v_mfma_f32_16x16x32_bf16 v[72:75], v[160:163], v[216:219], v[72:75]
	v_mfma_f32_16x16x32_bf16 v[124:127], v[148:151], v[190:193], v[124:127]
	v_mfma_f32_16x16x32_bf16 v[120:123], v[164:167], v[190:193], v[120:123]
	v_mfma_f32_16x16x32_bf16 v[108:111], v[148:151], v[198:201], v[108:111]
	v_mfma_f32_16x16x32_bf16 v[104:107], v[164:167], v[198:201], v[104:107]
	v_mfma_f32_16x16x32_bf16 v[92:95], v[148:151], v[212:215], v[92:95]
	v_mfma_f32_16x16x32_bf16 v[88:91], v[164:167], v[212:215], v[88:91]
	v_mfma_f32_16x16x32_bf16 v[76:79], v[148:151], v[220:223], v[76:79]
	v_mfma_f32_16x16x32_bf16 v[72:75], v[164:167], v[220:223], v[72:75]
	s_setprio 0
	s_setprio 1
	v_mfma_f32_16x16x32_bf16 v[116:119], v[168:171], v[186:189], v[116:119]
	v_mfma_f32_16x16x32_bf16 v[112:115], v[176:179], v[186:189], v[112:115]
	v_mfma_f32_16x16x32_bf16 v[100:103], v[168:171], v[194:197], v[100:103]
	v_mfma_f32_16x16x32_bf16 v[96:99], v[176:179], v[194:197], v[96:99]
	v_mfma_f32_16x16x32_bf16 v[84:87], v[168:171], v[208:211], v[84:87]
	v_mfma_f32_16x16x32_bf16 v[80:83], v[176:179], v[208:211], v[80:83]
	v_mfma_f32_16x16x32_bf16 v[68:71], v[168:171], v[216:219], v[68:71]
	v_mfma_f32_16x16x32_bf16 v[64:67], v[176:179], v[216:219], v[64:67]
	v_mfma_f32_16x16x32_bf16 v[116:119], v[172:175], v[190:193], v[116:119]
	v_mfma_f32_16x16x32_bf16 v[112:115], v[182:185], v[190:193], v[112:115]
	v_mfma_f32_16x16x32_bf16 v[100:103], v[172:175], v[198:201], v[100:103]
	v_mfma_f32_16x16x32_bf16 v[96:99], v[182:185], v[198:201], v[96:99]
	v_mfma_f32_16x16x32_bf16 v[84:87], v[172:175], v[212:215], v[84:87]
	v_mfma_f32_16x16x32_bf16 v[80:83], v[182:185], v[212:215], v[80:83]
	v_mfma_f32_16x16x32_bf16 v[68:71], v[172:175], v[220:223], v[68:71]
	v_mfma_f32_16x16x32_bf16 v[64:67], v[182:185], v[220:223], v[64:67]
	s_setprio 0
	s_barrier
	s_add_i32 s3, s3, s14
	v_lshl_add_u64 v[202:203], v[202:203], 0, s[36:37]
	s_mov_b32 m0, s3
	ds_read_b128 v[186:189], v157 offset:49152
	ds_read_b128 v[190:193], v157 offset:50176
	ds_read_b128 v[194:197], v157 offset:51200
	ds_read_b128 v[198:201], v157 offset:52224
	ds_read_b128 v[208:211], v157 offset:53248
	ds_read_b128 v[212:215], v157 offset:54272
	ds_read_b128 v[216:219], v157 offset:55296
	ds_read_b128 v[220:223], v157 offset:56320
	global_load_lds_dwordx4 v[202:203], off
	s_add_i32 m0, s3, 0x2000
	s_add_u32 s56, s56, 0x40080
	v_lshl_add_u64 v[202:203], v[224:225], 0, s[36:37]
	s_addc_u32 s57, s57, 0
	s_add_i32 s3, s33, s14
	global_load_lds_dwordx4 v[202:203], off
	v_lshl_add_u64 v[202:203], s[56:57], 0, v[132:133]
	s_mov_b32 m0, s3
	s_nop 0
	global_load_lds_dwordx4 v[202:203], off
	v_lshl_add_u64 v[202:203], s[56:57], 0, v[128:129]
	s_add_i32 m0, s3, 0x2000
	s_nop 0
	global_load_lds_dwordx4 v[202:203], off
	s_waitcnt vmcnt(6)
	s_waitcnt lgkmcnt(0)
	s_barrier
; __device__ __forceinline__ unsigned cvtpk(float lo, float hi) { f32x2v_ v = {lo, hi}; bf16x2v_ b = __builtin_convertvector(v, bf16x2v_); return __builtin_bit_cast(unsigned, b); }
; #define PG8_STAGE(bufoff, gbase, voff) do { _Pragma("unroll") for (int _i = 0; _i < 2; ++_i) \
;         __builtin_amdgcn_global_load_lds((const unsigned*)((const char*)(gbase) + (voff)[_i]), (PG8_LAS unsigned*)(lds + (bufoff) + ldsw + _i * 8192), 16, 0, 0); } while (0)
; #define PG8_LDA(dst, b, h) do { _Pragma("unroll") for (int m = 0; m < 4; ++m) _Pragma("unroll") for (int k = 0; k < 2; ++k) dst[m][k] = *(const PG8_LAS bf16x8*)(lds + PG8_SA(b, h) + aoff + m * 2048 + k * 1024); } while (0)
; #define PG8_MMA(ai, bj, At, Bt) do { __builtin_amdgcn_s_setprio(1); _Pragma("unroll") for (int m = 0; m < 4; ++m) _Pragma("unroll") for (int n = 0; n < 2; ++n) _Pragma("unroll") for (int k = 0; k < 2; ++k) \
;         acc[ai][bj][m][n] = __builtin_amdgcn_mfma_f32_16x16x32_bf16(Bt[n][k], At[m][k], acc[ai][bj][m][n], 0, 0, 0); __builtin_amdgcn_s_setprio(0); } while (0)
; #define PG8_WAIT_V(n) asm volatile("s_waitcnt vmcnt(" #n ")" ::: "memory")
;     __device__ __forceinline__ void operator()(const f32x4 (&acc)[2][2][4][2], const Unit& u, int wr, int wc, int fr, int fq) const {
;     ...
;             for (int m = 0; m < 4; ++m) { const int row = row0 + ai * HALF + m * 16; const float rs = row_rs(ss, row);
;                 float hv[8];
; #pragma unroll
;                 for (int n = 0; n < 2; ++n)
; #pragma unroll
;                     for (int i = 0; i < 4; ++i) { const float g = acc[ai][0][m][n][i] * rs, uu = acc[ai][1][m][n][i] * rs;
;                         hv[n * 4 + i] = g * __builtin_amdgcn_rcpf(1.0f + __expf(-g)) * uu; }
;                 u32x4 w; w.x = cvtpk(hv[0], hv[1]); w.y = cvtpk(hv[2], hv[3]); w.z = cvtpk(hv[4], hv[5]); w.w = cvtpk(hv[6], hv[7]);
;                 *(u32x4*)(H + (size_t)row * ldh + col0) = w; }
; template <class Epi, class Sched, bool ALIGN_EPI = false, bool SP2 = false>
; __device__ __forceinline__ void gemm_phase(PG8_LAS unsigned char* lds, const Gemm g, const Sched& S, const Epi& E) {
;     ...
;             PG8_LDA(At, 1, 1); PG8_STAGE(PG8_SB(1, 0), b3, voffB); PG8_STAGE(PG8_SB(1, 1), b3 + hstep, voffB); PG8_STAGE(PG8_SA(1, 0), a3, voffA);
;             PG8_WAIT_V(8); PG8_WAIT_L(0); PG8_BAR; PG8_MMA(1, 0, At, B0); PG8_MMA(1, 1, At, B1); PG8_BAR; PG8_SCHED;
	s_setprio 1
	s_waitcnt lgkmcnt(0)
	v_mfma_f32_16x16x32_bf16 v[60:63], v[144:147], v[186:189], v[60:63]
	v_mfma_f32_16x16x32_bf16 v[56:59], v[160:163], v[186:189], v[56:59]
	v_mfma_f32_16x16x32_bf16 v[44:47], v[144:147], v[194:197], v[44:47]
	v_mfma_f32_16x16x32_bf16 v[40:43], v[160:163], v[194:197], v[40:43]
	v_mfma_f32_16x16x32_bf16 v[28:31], v[144:147], v[208:211], v[28:31]
	v_mfma_f32_16x16x32_bf16 v[24:27], v[160:163], v[208:211], v[24:27]
	v_mfma_f32_16x16x32_bf16 v[12:15], v[144:147], v[216:219], v[12:15]
	v_mfma_f32_16x16x32_bf16 v[8:11], v[160:163], v[216:219], v[8:11]
	v_mfma_f32_16x16x32_bf16 v[60:63], v[148:151], v[190:193], v[60:63]
	v_mfma_f32_16x16x32_bf16 v[56:59], v[164:167], v[190:193], v[56:59]
	v_mfma_f32_16x16x32_bf16 v[44:47], v[148:151], v[198:201], v[44:47]
	v_mfma_f32_16x16x32_bf16 v[40:43], v[164:167], v[198:201], v[40:43]
	v_mfma_f32_16x16x32_bf16 v[28:31], v[148:151], v[212:215], v[28:31]
	v_mfma_f32_16x16x32_bf16 v[24:27], v[164:167], v[212:215], v[24:27]
	v_lshl_add_u64 v[202:203], v[226:227], 0, s[36:37]
	s_mov_b32 m0, s63
	s_nop 0
	global_load_lds_dwordx4 v[202:203], off
	v_mfma_f32_16x16x32_bf16 v[12:15], v[148:151], v[220:223], v[12:15]
	v_mfma_f32_16x16x32_bf16 v[8:11], v[164:167], v[220:223], v[8:11]
	s_setprio 0
	s_setprio 1
	v_mfma_f32_16x16x32_bf16 v[52:55], v[168:171], v[186:189], v[52:55]
	v_mfma_f32_16x16x32_bf16 v[48:51], v[176:179], v[186:189], v[48:51]
	v_mfma_f32_16x16x32_bf16 v[36:39], v[168:171], v[194:197], v[36:39]
	v_mfma_f32_16x16x32_bf16 v[32:35], v[176:179], v[194:197], v[32:35]
	v_mfma_f32_16x16x32_bf16 v[20:23], v[168:171], v[208:211], v[20:23]
	v_mfma_f32_16x16x32_bf16 v[16:19], v[176:179], v[208:211], v[16:19]
	v_mfma_f32_16x16x32_bf16 v[4:7], v[168:171], v[216:219], v[4:7]
	v_mfma_f32_16x16x32_bf16 v[0:3], v[176:179], v[216:219], v[0:3]
	v_mfma_f32_16x16x32_bf16 v[52:55], v[172:175], v[190:193], v[52:55]
	v_mfma_f32_16x16x32_bf16 v[48:51], v[182:185], v[190:193], v[48:51]
	v_mfma_f32_16x16x32_bf16 v[36:39], v[172:175], v[198:201], v[36:39]
	v_mfma_f32_16x16x32_bf16 v[32:35], v[182:185], v[198:201], v[32:35]
	v_mfma_f32_16x16x32_bf16 v[20:23], v[172:175], v[212:215], v[20:23]
	v_mfma_f32_16x16x32_bf16 v[16:19], v[182:185], v[212:215], v[16:19]
	v_lshl_add_u64 v[202:203], v[228:229], 0, s[36:37]
	s_mov_b32 m0, s64
	s_nop 0
	global_load_lds_dwordx4 v[202:203], off
	v_mfma_f32_16x16x32_bf16 v[4:7], v[172:175], v[220:223], v[4:7]
	v_mfma_f32_16x16x32_bf16 v[0:3], v[182:185], v[220:223], v[0:3]
	s_setprio 0
	s_barrier
	s_add_i32 s83, s83, 2
	s_add_u32 s54, s54, 0x100
	s_addc_u32 s55, s55, 0
	s_add_u32 s77, s77, 0x100
	s_addc_u32 s82, s82, 0
	s_cmp_gt_u32 s83, 13
	s_cbranch_scc0 .LBB0_957
	v_lshl_add_u32 v144, s52, 8, v152
	v_ashrrev_i32_e32 v145, 31, v144
	s_and_b64 vcc, exec, s[38:39]
	s_cbranch_vccz .LBB0_960
	s_barrier
.LBB0_960:
	v_lshl_or_b32 v160, s74, 7, v154
	v_ashrrev_i32_e32 v161, 31, v160
	v_or_b32_e32 v164, 16, v144
	v_ashrrev_i32_e32 v165, 31, v164
	v_lshl_add_u64 v[166:167], v[164:165], 3, s[0:1]
	v_mov_b64_e32 v[146:147], s[20:21]
	v_mad_i64_i32 v[162:163], s[54:55], v144, s67, v[146:147]
	s_andn2_b64 vcc, exec, s[10:11]
	s_mov_b64 s[10:11], -1
	s_waitcnt vmcnt(20)
	v_cvt_f32_u32_e32 v159, v235
	v_cvt_f32_u32_e32 v145, v234
	v_lshlrev_b64 v[148:149], 1, v[160:161]
	v_lshl_add_u64 v[162:163], v[162:163], 0, v[148:149]
	v_fmamk_f32 v145, v145, 0x2f800000, v159
	v_fmamk_f32 v145, v145, 0x3a800000, v158
	v_rsq_f32_e32 v160, v145
	s_nop 0
	v_mul_f32_e32 v234, 0xbfb8aa3b, v160
	v_mul_f32_e32 v235, v160, v160
	v_pk_mul_f32 v[160:161], v[124:125], v[234:235] op_sel_hi:[1,0]
	v_pk_mul_f32 v[168:169], v[126:127], v[234:235] op_sel_hi:[1,0]
	v_pk_mul_f32 v[170:171], v[120:121], v[234:235] op_sel_hi:[1,0]
	v_pk_mul_f32 v[172:173], v[122:123], v[234:235] op_sel_hi:[1,0]
	v_pk_mul_f32 v[116:117], v[116:117], v[124:125]
	v_pk_mul_f32 v[118:119], v[118:119], v[126:127]
	v_pk_mul_f32 v[120:121], v[112:113], v[120:121]
	v_pk_mul_f32 v[122:123], v[114:115], v[122:123]
	v_exp_f32_e32 v160, v160
	v_exp_f32_e32 v161, v161
	v_exp_f32_e32 v168, v168
	v_exp_f32_e32 v169, v169
	v_exp_f32_e32 v170, v170
	v_exp_f32_e32 v171, v171
	v_exp_f32_e32 v172, v172
	v_exp_f32_e32 v173, v173
	v_pk_mul_f32 v[116:117], v[116:117], v[234:235] op_sel:[0,1] op_sel_hi:[1,1]
	v_pk_mul_f32 v[118:119], v[118:119], v[234:235] op_sel:[0,1] op_sel_hi:[1,1]
	v_pk_mul_f32 v[120:121], v[120:121], v[234:235] op_sel:[0,1] op_sel_hi:[1,1]
	v_pk_mul_f32 v[122:123], v[122:123], v[234:235] op_sel:[0,1] op_sel_hi:[1,1]
	v_pk_add_f32 v[160:161], v[160:161], 1.0 op_sel_hi:[1,0]
	v_pk_add_f32 v[168:169], v[168:169], 1.0 op_sel_hi:[1,0]
	v_pk_add_f32 v[170:171], v[170:171], 1.0 op_sel_hi:[1,0]
	v_pk_add_f32 v[172:173], v[172:173], 1.0 op_sel_hi:[1,0]
	v_rcp_f32_e32 v160, v160
	v_rcp_f32_e32 v161, v161
	v_rcp_f32_e32 v168, v168
	v_rcp_f32_e32 v169, v169
	v_rcp_f32_e32 v170, v170
	v_rcp_f32_e32 v171, v171
	v_rcp_f32_e32 v172, v172
	v_rcp_f32_e32 v173, v173
	v_pk_mul_f32 v[116:117], v[116:117], v[160:161]
	v_pk_mul_f32 v[118:119], v[118:119], v[168:169]
	v_pk_mul_f32 v[120:121], v[120:121], v[170:171]
	v_pk_mul_f32 v[122:123], v[122:123], v[172:173]
	v_cvt_pk_bf16_f32 v112, v116, v117
	v_cvt_pk_bf16_f32 v113, v118, v119
	v_cvt_pk_bf16_f32 v114, v120, v121
	v_cvt_pk_bf16_f32 v115, v122, v123
	global_store_dwordx4 v[162:163], v[112:115], off
	s_nop 0
	s_nop 0
	v_or_b32_e32 v114, 32, v144
	s_waitcnt vmcnt(7)
; __device__ __forceinline__ unsigned cvtpk(float lo, float hi) { f32x2v_ v = {lo, hi}; bf16x2v_ b = __builtin_convertvector(v, bf16x2v_); return __builtin_bit_cast(unsigned, b); }
; __device__ __forceinline__ float row_rs(const float* ssp, int row) { const unsigned long long v = ((const unsigned long long*)ssp)[row];
;     return __builtin_amdgcn_rsqf((float)v * (1.0f / 4294967296.0f) * (1.0f / 1024.0f) + RMS_EPS); }
;     __device__ __forceinline__ void operator()(const f32x4 (&acc)[2][2][4][2], const Unit& u, int wr, int wc, int fr, int fq) const {
;     ...
;             for (int m = 0; m < 4; ++m) { const int row = row0 + ai * HALF + m * 16; const float rs = row_rs(ss, row);
;                 float hv[8];
; #pragma unroll
;                 for (int n = 0; n < 2; ++n)
; #pragma unroll
;                     for (int i = 0; i < 4; ++i) { const float g = acc[ai][0][m][n][i] * rs, uu = acc[ai][1][m][n][i] * rs;
;                         hv[n * 4 + i] = g * __builtin_amdgcn_rcpf(1.0f + __expf(-g)) * uu; }
;                 u32x4 w; w.x = cvtpk(hv[0], hv[1]); w.y = cvtpk(hv[2], hv[3]); w.z = cvtpk(hv[4], hv[5]); w.w = cvtpk(hv[6], hv[7]);
;                 *(u32x4*)(H + (size_t)row * ldh + col0) = w; }
	v_cvt_f32_u32_e32 v116, v237
	v_cvt_f32_u32_e32 v115, v236
	v_mad_i64_i32 v[112:113], s[54:55], v164, s67, v[146:147]
	v_fmamk_f32 v115, v115, 0x2f800000, v116
	v_fmamk_f32 v115, v115, 0x3a800000, v158
	v_rsq_f32_e32 v116, v115
	v_ashrrev_i32_e32 v115, 31, v114
	v_lshl_add_u64 v[118:119], v[114:115], 3, s[0:1]
	v_lshl_add_u64 v[112:113], v[112:113], 0, v[148:149]
	v_mul_f32_e32 v236, 0xbfb8aa3b, v116
	v_mul_f32_e32 v237, v116, v116
	v_pk_mul_f32 v[116:117], v[108:109], v[236:237] op_sel_hi:[1,0]
	v_pk_mul_f32 v[120:121], v[110:111], v[236:237] op_sel_hi:[1,0]
	v_pk_mul_f32 v[122:123], v[104:105], v[236:237] op_sel_hi:[1,0]
	v_pk_mul_f32 v[124:125], v[106:107], v[236:237] op_sel_hi:[1,0]
	v_pk_mul_f32 v[100:101], v[100:101], v[108:109]
	v_pk_mul_f32 v[102:103], v[102:103], v[110:111]
	v_pk_mul_f32 v[104:105], v[96:97], v[104:105]
	v_pk_mul_f32 v[106:107], v[98:99], v[106:107]
	v_exp_f32_e32 v116, v116
	v_exp_f32_e32 v117, v117
	v_exp_f32_e32 v120, v120
	v_exp_f32_e32 v121, v121
	v_exp_f32_e32 v122, v122
	v_exp_f32_e32 v123, v123
	v_exp_f32_e32 v124, v124
	v_exp_f32_e32 v125, v125
	v_pk_mul_f32 v[100:101], v[100:101], v[236:237] op_sel:[0,1] op_sel_hi:[1,1]
	v_pk_mul_f32 v[102:103], v[102:103], v[236:237] op_sel:[0,1] op_sel_hi:[1,1]
	v_pk_mul_f32 v[104:105], v[104:105], v[236:237] op_sel:[0,1] op_sel_hi:[1,1]
	v_pk_mul_f32 v[106:107], v[106:107], v[236:237] op_sel:[0,1] op_sel_hi:[1,1]
	v_pk_add_f32 v[116:117], v[116:117], 1.0 op_sel_hi:[1,0]
	v_pk_add_f32 v[120:121], v[120:121], 1.0 op_sel_hi:[1,0]
	v_pk_add_f32 v[122:123], v[122:123], 1.0 op_sel_hi:[1,0]
	v_pk_add_f32 v[124:125], v[124:125], 1.0 op_sel_hi:[1,0]
	v_rcp_f32_e32 v116, v116
	v_rcp_f32_e32 v117, v117
	v_rcp_f32_e32 v120, v120
	v_rcp_f32_e32 v121, v121
	v_rcp_f32_e32 v122, v122
	v_rcp_f32_e32 v123, v123
	v_rcp_f32_e32 v124, v124
	v_rcp_f32_e32 v125, v125
	v_pk_mul_f32 v[100:101], v[100:101], v[116:117]
	v_pk_mul_f32 v[102:103], v[102:103], v[120:121]
	v_pk_mul_f32 v[104:105], v[104:105], v[122:123]
	v_pk_mul_f32 v[106:107], v[106:107], v[124:125]
	v_cvt_pk_bf16_f32 v96, v100, v101
	v_cvt_pk_bf16_f32 v97, v102, v103
	v_cvt_pk_bf16_f32 v98, v104, v105
	v_cvt_pk_bf16_f32 v99, v106, v107
	global_store_dwordx4 v[112:113], v[96:99], off
	s_nop 0
	s_nop 0
	v_or_b32_e32 v98, 48, v144
	s_waitcnt vmcnt(7)
	v_cvt_f32_u32_e32 v100, v239
	v_cvt_f32_u32_e32 v99, v238
	v_mad_i64_i32 v[96:97], s[54:55], v114, s67, v[146:147]
	v_fmamk_f32 v99, v99, 0x2f800000, v100
	v_fmamk_f32 v99, v99, 0x3a800000, v158
	v_rsq_f32_e32 v100, v99
	v_ashrrev_i32_e32 v99, 31, v98
	v_lshl_add_u64 v[102:103], v[98:99], 3, s[0:1]
	v_lshl_add_u64 v[96:97], v[96:97], 0, v[148:149]
	v_mul_f32_e32 v238, 0xbfb8aa3b, v100
	v_mul_f32_e32 v239, v100, v100
	v_pk_mul_f32 v[100:101], v[92:93], v[238:239] op_sel_hi:[1,0]
	v_pk_mul_f32 v[104:105], v[94:95], v[238:239] op_sel_hi:[1,0]
	v_pk_mul_f32 v[106:107], v[88:89], v[238:239] op_sel_hi:[1,0]
	v_pk_mul_f32 v[108:109], v[90:91], v[238:239] op_sel_hi:[1,0]
	v_pk_mul_f32 v[84:85], v[84:85], v[92:93]
	v_pk_mul_f32 v[86:87], v[86:87], v[94:95]
	v_pk_mul_f32 v[88:89], v[80:81], v[88:89]
	v_pk_mul_f32 v[90:91], v[82:83], v[90:91]
	v_exp_f32_e32 v100, v100
	v_exp_f32_e32 v101, v101
	v_exp_f32_e32 v104, v104
	v_exp_f32_e32 v105, v105
	v_exp_f32_e32 v106, v106
	v_exp_f32_e32 v107, v107
	v_exp_f32_e32 v108, v108
	v_exp_f32_e32 v109, v109
	v_pk_mul_f32 v[84:85], v[84:85], v[238:239] op_sel:[0,1] op_sel_hi:[1,1]
	v_pk_mul_f32 v[86:87], v[86:87], v[238:239] op_sel:[0,1] op_sel_hi:[1,1]
	v_pk_mul_f32 v[88:89], v[88:89], v[238:239] op_sel:[0,1] op_sel_hi:[1,1]
	v_pk_mul_f32 v[90:91], v[90:91], v[238:239] op_sel:[0,1] op_sel_hi:[1,1]
	v_pk_add_f32 v[100:101], v[100:101], 1.0 op_sel_hi:[1,0]
	v_pk_add_f32 v[104:105], v[104:105], 1.0 op_sel_hi:[1,0]
	v_pk_add_f32 v[106:107], v[106:107], 1.0 op_sel_hi:[1,0]
	v_pk_add_f32 v[108:109], v[108:109], 1.0 op_sel_hi:[1,0]
	v_rcp_f32_e32 v100, v100
	v_rcp_f32_e32 v101, v101
	v_rcp_f32_e32 v104, v104
	v_rcp_f32_e32 v105, v105
	v_rcp_f32_e32 v106, v106
	v_rcp_f32_e32 v107, v107
	v_rcp_f32_e32 v108, v108
	v_rcp_f32_e32 v109, v109
	v_pk_mul_f32 v[84:85], v[84:85], v[100:101]
	v_pk_mul_f32 v[86:87], v[86:87], v[104:105]
	v_pk_mul_f32 v[88:89], v[88:89], v[106:107]
	v_pk_mul_f32 v[90:91], v[90:91], v[108:109]
	v_cvt_pk_bf16_f32 v80, v84, v85
	v_cvt_pk_bf16_f32 v81, v86, v87
	v_cvt_pk_bf16_f32 v82, v88, v89
	v_cvt_pk_bf16_f32 v83, v90, v91
	global_store_dwordx4 v[96:97], v[80:83], off
	s_nop 0
	s_waitcnt vmcnt(7)
	v_cvt_f32_u32_e32 v80, v241
	v_cvt_f32_u32_e32 v81, v240
	v_mad_i64_i32 v[82:83], s[54:55], v98, s67, v[146:147]
	v_fmamk_f32 v80, v81, 0x2f800000, v80
	v_fmamk_f32 v80, v80, 0x3a800000, v158
	v_rsq_f32_e32 v80, v80
	v_lshl_add_u64 v[82:83], v[82:83], 0, v[148:149]
	v_mul_f32_e32 v240, 0xbfb8aa3b, v80
	v_mul_f32_e32 v241, v80, v80
	v_pk_mul_f32 v[80:81], v[76:77], v[240:241] op_sel_hi:[1,0]
	v_pk_mul_f32 v[84:85], v[78:79], v[240:241] op_sel_hi:[1,0]
	v_pk_mul_f32 v[86:87], v[72:73], v[240:241] op_sel_hi:[1,0]
	v_pk_mul_f32 v[88:89], v[74:75], v[240:241] op_sel_hi:[1,0]
	v_pk_mul_f32 v[68:69], v[68:69], v[76:77]
	v_pk_mul_f32 v[70:71], v[70:71], v[78:79]
	v_pk_mul_f32 v[72:73], v[64:65], v[72:73]
	v_pk_mul_f32 v[74:75], v[66:67], v[74:75]
	v_exp_f32_e32 v80, v80
	v_exp_f32_e32 v81, v81
	v_exp_f32_e32 v84, v84
	v_exp_f32_e32 v85, v85
	v_exp_f32_e32 v86, v86
	v_exp_f32_e32 v87, v87
	v_exp_f32_e32 v88, v88
	v_exp_f32_e32 v89, v89
	v_pk_mul_f32 v[68:69], v[68:69], v[240:241] op_sel:[0,1] op_sel_hi:[1,1]
	v_pk_mul_f32 v[70:71], v[70:71], v[240:241] op_sel:[0,1] op_sel_hi:[1,1]
	v_pk_mul_f32 v[72:73], v[72:73], v[240:241] op_sel:[0,1] op_sel_hi:[1,1]
	v_pk_mul_f32 v[74:75], v[74:75], v[240:241] op_sel:[0,1] op_sel_hi:[1,1]
	v_pk_add_f32 v[80:81], v[80:81], 1.0 op_sel_hi:[1,0]
	v_pk_add_f32 v[84:85], v[84:85], 1.0 op_sel_hi:[1,0]
	v_pk_add_f32 v[86:87], v[86:87], 1.0 op_sel_hi:[1,0]
	v_pk_add_f32 v[88:89], v[88:89], 1.0 op_sel_hi:[1,0]
	v_rcp_f32_e32 v80, v80
	v_rcp_f32_e32 v81, v81
	v_rcp_f32_e32 v84, v84
	v_rcp_f32_e32 v85, v85
	v_rcp_f32_e32 v86, v86
	v_rcp_f32_e32 v87, v87
	v_rcp_f32_e32 v88, v88
	v_rcp_f32_e32 v89, v89
	v_pk_mul_f32 v[68:69], v[68:69], v[80:81]
	v_pk_mul_f32 v[70:71], v[70:71], v[84:85]
	v_pk_mul_f32 v[72:73], v[72:73], v[86:87]
	v_pk_mul_f32 v[74:75], v[74:75], v[88:89]
	v_cvt_pk_bf16_f32 v64, v68, v69
	v_cvt_pk_bf16_f32 v65, v70, v71
	v_cvt_pk_bf16_f32 v66, v72, v73
	v_cvt_pk_bf16_f32 v67, v74, v75
	global_store_dwordx4 v[82:83], v[64:67], off
	s_nop 0
	s_waitcnt vmcnt(7)
; __device__ __forceinline__ unsigned cvtpk(float lo, float hi) { f32x2v_ v = {lo, hi}; bf16x2v_ b = __builtin_convertvector(v, bf16x2v_); return __builtin_bit_cast(unsigned, b); }
;     __device__ __forceinline__ void operator()(const f32x4 (&acc)[2][2][4][2], const Unit& u, int wr, int wc, int fr, int fq) const {
;     ...
;             for (int m = 0; m < 4; ++m) { const int row = row0 + ai * HALF + m * 16; const float rs = row_rs(ss, row);
;                 float hv[8];
; #pragma unroll
;                 for (int n = 0; n < 2; ++n)
; #pragma unroll
;                     for (int i = 0; i < 4; ++i) { const float g = acc[ai][0][m][n][i] * rs, uu = acc[ai][1][m][n][i] * rs;
;                         hv[n * 4 + i] = g * __builtin_amdgcn_rcpf(1.0f + __expf(-g)) * uu; }
;                 u32x4 w; w.x = cvtpk(hv[0], hv[1]); w.y = cvtpk(hv[2], hv[3]); w.z = cvtpk(hv[4], hv[5]); w.w = cvtpk(hv[6], hv[7]);
;                 *(u32x4*)(H + (size_t)row * ldh + col0) = w; }
	v_cvt_f32_u32_e32 v64, v243
	v_cvt_f32_u32_e32 v66, v242
	v_add_u32_e32 v65, 0x80, v144
	v_fmamk_f32 v64, v66, 0x2f800000, v64
	v_fmamk_f32 v64, v64, 0x3a800000, v158
	v_rsq_f32_e32 v64, v64
	v_mad_i64_i32 v[66:67], s[54:55], v65, s67, v[146:147]
	v_lshl_add_u64 v[66:67], v[66:67], 0, v[148:149]
	v_mul_f32_e32 v242, 0xbfb8aa3b, v64
	v_mul_f32_e32 v243, v64, v64
	v_pk_mul_f32 v[64:65], v[60:61], v[242:243] op_sel_hi:[1,0]
	v_pk_mul_f32 v[68:69], v[62:63], v[242:243] op_sel_hi:[1,0]
	v_pk_mul_f32 v[70:71], v[56:57], v[242:243] op_sel_hi:[1,0]
	v_pk_mul_f32 v[72:73], v[58:59], v[242:243] op_sel_hi:[1,0]
	v_pk_mul_f32 v[52:53], v[52:53], v[60:61]
	v_pk_mul_f32 v[54:55], v[54:55], v[62:63]
	v_pk_mul_f32 v[56:57], v[48:49], v[56:57]
	v_pk_mul_f32 v[58:59], v[50:51], v[58:59]
	v_exp_f32_e32 v64, v64
	v_exp_f32_e32 v65, v65
	v_exp_f32_e32 v68, v68
	v_exp_f32_e32 v69, v69
	v_exp_f32_e32 v70, v70
	v_exp_f32_e32 v71, v71
	v_exp_f32_e32 v72, v72
	v_exp_f32_e32 v73, v73
	v_pk_mul_f32 v[52:53], v[52:53], v[242:243] op_sel:[0,1] op_sel_hi:[1,1]
	v_pk_mul_f32 v[54:55], v[54:55], v[242:243] op_sel:[0,1] op_sel_hi:[1,1]
	v_pk_mul_f32 v[56:57], v[56:57], v[242:243] op_sel:[0,1] op_sel_hi:[1,1]
	v_pk_mul_f32 v[58:59], v[58:59], v[242:243] op_sel:[0,1] op_sel_hi:[1,1]
	v_pk_add_f32 v[64:65], v[64:65], 1.0 op_sel_hi:[1,0]
	v_pk_add_f32 v[68:69], v[68:69], 1.0 op_sel_hi:[1,0]
	v_pk_add_f32 v[70:71], v[70:71], 1.0 op_sel_hi:[1,0]
	v_pk_add_f32 v[72:73], v[72:73], 1.0 op_sel_hi:[1,0]
	v_rcp_f32_e32 v64, v64
	v_rcp_f32_e32 v65, v65
	v_rcp_f32_e32 v68, v68
	v_rcp_f32_e32 v69, v69
	v_rcp_f32_e32 v70, v70
	v_rcp_f32_e32 v71, v71
	v_rcp_f32_e32 v72, v72
	v_rcp_f32_e32 v73, v73
	v_pk_mul_f32 v[52:53], v[52:53], v[64:65]
	v_pk_mul_f32 v[54:55], v[54:55], v[68:69]
	v_pk_mul_f32 v[56:57], v[56:57], v[70:71]
	v_pk_mul_f32 v[58:59], v[58:59], v[72:73]
	v_cvt_pk_bf16_f32 v48, v52, v53
	v_cvt_pk_bf16_f32 v49, v54, v55
	v_cvt_pk_bf16_f32 v50, v56, v57
	v_cvt_pk_bf16_f32 v51, v58, v59
	global_store_dwordx4 v[66:67], v[48:51], off
	s_nop 0
	s_waitcnt vmcnt(7)
	v_cvt_f32_u32_e32 v48, v245
	v_cvt_f32_u32_e32 v50, v244
	v_add_u32_e32 v49, 0x90, v144
	v_fmamk_f32 v48, v50, 0x2f800000, v48
	v_fmamk_f32 v48, v48, 0x3a800000, v158
	v_rsq_f32_e32 v48, v48
	v_mad_i64_i32 v[50:51], s[54:55], v49, s67, v[146:147]
	v_lshl_add_u64 v[50:51], v[50:51], 0, v[148:149]
	v_mul_f32_e32 v244, 0xbfb8aa3b, v48
	v_mul_f32_e32 v245, v48, v48
	v_pk_mul_f32 v[48:49], v[44:45], v[244:245] op_sel_hi:[1,0]
	v_pk_mul_f32 v[52:53], v[46:47], v[244:245] op_sel_hi:[1,0]
	v_pk_mul_f32 v[54:55], v[40:41], v[244:245] op_sel_hi:[1,0]
	v_pk_mul_f32 v[56:57], v[42:43], v[244:245] op_sel_hi:[1,0]
	v_pk_mul_f32 v[36:37], v[36:37], v[44:45]
	v_pk_mul_f32 v[38:39], v[38:39], v[46:47]
	v_pk_mul_f32 v[40:41], v[32:33], v[40:41]
	v_pk_mul_f32 v[42:43], v[34:35], v[42:43]
	v_exp_f32_e32 v48, v48
	v_exp_f32_e32 v49, v49
	v_exp_f32_e32 v52, v52
	v_exp_f32_e32 v53, v53
	v_exp_f32_e32 v54, v54
	v_exp_f32_e32 v55, v55
	v_exp_f32_e32 v56, v56
	v_exp_f32_e32 v57, v57
	v_pk_mul_f32 v[36:37], v[36:37], v[244:245] op_sel:[0,1] op_sel_hi:[1,1]
	v_pk_mul_f32 v[38:39], v[38:39], v[244:245] op_sel:[0,1] op_sel_hi:[1,1]
	v_pk_mul_f32 v[40:41], v[40:41], v[244:245] op_sel:[0,1] op_sel_hi:[1,1]
	v_pk_mul_f32 v[42:43], v[42:43], v[244:245] op_sel:[0,1] op_sel_hi:[1,1]
	v_pk_add_f32 v[48:49], v[48:49], 1.0 op_sel_hi:[1,0]
	v_pk_add_f32 v[52:53], v[52:53], 1.0 op_sel_hi:[1,0]
	v_pk_add_f32 v[54:55], v[54:55], 1.0 op_sel_hi:[1,0]
	v_pk_add_f32 v[56:57], v[56:57], 1.0 op_sel_hi:[1,0]
	v_rcp_f32_e32 v48, v48
	v_rcp_f32_e32 v49, v49
	v_rcp_f32_e32 v52, v52
	v_rcp_f32_e32 v53, v53
	v_rcp_f32_e32 v54, v54
	v_rcp_f32_e32 v55, v55
	v_rcp_f32_e32 v56, v56
	v_rcp_f32_e32 v57, v57
	v_pk_mul_f32 v[36:37], v[36:37], v[48:49]
	v_pk_mul_f32 v[38:39], v[38:39], v[52:53]
	v_pk_mul_f32 v[40:41], v[40:41], v[54:55]
	v_pk_mul_f32 v[42:43], v[42:43], v[56:57]
	v_cvt_pk_bf16_f32 v32, v36, v37
	v_cvt_pk_bf16_f32 v33, v38, v39
	v_cvt_pk_bf16_f32 v34, v40, v41
	v_cvt_pk_bf16_f32 v35, v42, v43
	global_store_dwordx4 v[50:51], v[32:35], off
	s_nop 0
	s_waitcnt vmcnt(7)
; __device__ __forceinline__ unsigned cvtpk(float lo, float hi) { f32x2v_ v = {lo, hi}; bf16x2v_ b = __builtin_convertvector(v, bf16x2v_); return __builtin_bit_cast(unsigned, b); }
;     __device__ __forceinline__ void operator()(const f32x4 (&acc)[2][2][4][2], const Unit& u, int wr, int wc, int fr, int fq) const {
;     ...
;             for (int m = 0; m < 4; ++m) { const int row = row0 + ai * HALF + m * 16; const float rs = row_rs(ss, row);
;                 float hv[8];
; #pragma unroll
;                 for (int n = 0; n < 2; ++n)
; #pragma unroll
;                     for (int i = 0; i < 4; ++i) { const float g = acc[ai][0][m][n][i] * rs, uu = acc[ai][1][m][n][i] * rs;
;                         hv[n * 4 + i] = g * __builtin_amdgcn_rcpf(1.0f + __expf(-g)) * uu; }
;                 u32x4 w; w.x = cvtpk(hv[0], hv[1]); w.y = cvtpk(hv[2], hv[3]); w.z = cvtpk(hv[4], hv[5]); w.w = cvtpk(hv[6], hv[7]);
;                 *(u32x4*)(H + (size_t)row * ldh + col0) = w; }
	v_cvt_f32_u32_e32 v32, v247
	v_cvt_f32_u32_e32 v34, v246
	v_add_u32_e32 v33, 0xa0, v144
	v_fmamk_f32 v32, v34, 0x2f800000, v32
	v_fmamk_f32 v32, v32, 0x3a800000, v158
	v_rsq_f32_e32 v32, v32
	v_mad_i64_i32 v[34:35], s[54:55], v33, s67, v[146:147]
	v_lshl_add_u64 v[34:35], v[34:35], 0, v[148:149]
	v_mul_f32_e32 v246, 0xbfb8aa3b, v32
	v_mul_f32_e32 v247, v32, v32
	v_pk_mul_f32 v[32:33], v[28:29], v[246:247] op_sel_hi:[1,0]
	v_pk_mul_f32 v[36:37], v[30:31], v[246:247] op_sel_hi:[1,0]
	v_pk_mul_f32 v[38:39], v[24:25], v[246:247] op_sel_hi:[1,0]
	v_pk_mul_f32 v[40:41], v[26:27], v[246:247] op_sel_hi:[1,0]
	v_pk_mul_f32 v[20:21], v[20:21], v[28:29]
	v_pk_mul_f32 v[22:23], v[22:23], v[30:31]
	v_pk_mul_f32 v[24:25], v[16:17], v[24:25]
	v_pk_mul_f32 v[26:27], v[18:19], v[26:27]
	v_exp_f32_e32 v32, v32
	v_exp_f32_e32 v33, v33
	v_exp_f32_e32 v36, v36
	v_exp_f32_e32 v37, v37
	v_exp_f32_e32 v38, v38
	v_exp_f32_e32 v39, v39
	v_exp_f32_e32 v40, v40
	v_exp_f32_e32 v41, v41
	v_pk_mul_f32 v[20:21], v[20:21], v[246:247] op_sel:[0,1] op_sel_hi:[1,1]
	v_pk_mul_f32 v[22:23], v[22:23], v[246:247] op_sel:[0,1] op_sel_hi:[1,1]
	v_pk_mul_f32 v[24:25], v[24:25], v[246:247] op_sel:[0,1] op_sel_hi:[1,1]
	v_pk_mul_f32 v[26:27], v[26:27], v[246:247] op_sel:[0,1] op_sel_hi:[1,1]
	v_pk_add_f32 v[32:33], v[32:33], 1.0 op_sel_hi:[1,0]
	v_pk_add_f32 v[36:37], v[36:37], 1.0 op_sel_hi:[1,0]
	v_pk_add_f32 v[38:39], v[38:39], 1.0 op_sel_hi:[1,0]
	v_pk_add_f32 v[40:41], v[40:41], 1.0 op_sel_hi:[1,0]
	v_rcp_f32_e32 v32, v32
	v_rcp_f32_e32 v33, v33
	v_rcp_f32_e32 v36, v36
	v_rcp_f32_e32 v37, v37
	v_rcp_f32_e32 v38, v38
	v_rcp_f32_e32 v39, v39
	v_rcp_f32_e32 v40, v40
	v_rcp_f32_e32 v41, v41
	v_pk_mul_f32 v[20:21], v[20:21], v[32:33]
	v_pk_mul_f32 v[22:23], v[22:23], v[36:37]
	v_pk_mul_f32 v[24:25], v[24:25], v[38:39]
	v_pk_mul_f32 v[26:27], v[26:27], v[40:41]
	v_cvt_pk_bf16_f32 v16, v20, v21
	v_cvt_pk_bf16_f32 v17, v22, v23
	v_cvt_pk_bf16_f32 v18, v24, v25
	v_cvt_pk_bf16_f32 v19, v26, v27
	global_store_dwordx4 v[34:35], v[16:19], off
	s_nop 0
	s_waitcnt vmcnt(7)
	v_cvt_f32_u32_e32 v16, v249
	v_cvt_f32_u32_e32 v18, v248
	v_add_u32_e32 v17, 0xb0, v144
	v_fmamk_f32 v16, v18, 0x2f800000, v16
	v_fmamk_f32 v16, v16, 0x3a800000, v158
	v_rsq_f32_e32 v16, v16
	v_mad_i64_i32 v[18:19], s[54:55], v17, s67, v[146:147]
	v_lshl_add_u64 v[18:19], v[18:19], 0, v[148:149]
	v_mul_f32_e32 v248, 0xbfb8aa3b, v16
	v_mul_f32_e32 v249, v16, v16
	v_pk_mul_f32 v[16:17], v[12:13], v[248:249] op_sel_hi:[1,0]
	v_pk_mul_f32 v[20:21], v[14:15], v[248:249] op_sel_hi:[1,0]
	v_pk_mul_f32 v[22:23], v[8:9], v[248:249] op_sel_hi:[1,0]
	v_pk_mul_f32 v[24:25], v[10:11], v[248:249] op_sel_hi:[1,0]
	v_pk_mul_f32 v[4:5], v[4:5], v[12:13]
	v_pk_mul_f32 v[6:7], v[6:7], v[14:15]
	v_pk_mul_f32 v[8:9], v[0:1], v[8:9]
	v_pk_mul_f32 v[10:11], v[2:3], v[10:11]
	v_exp_f32_e32 v16, v16
	v_exp_f32_e32 v17, v17
	v_exp_f32_e32 v20, v20
	v_exp_f32_e32 v21, v21
	v_exp_f32_e32 v22, v22
	v_exp_f32_e32 v23, v23
	v_exp_f32_e32 v24, v24
	v_exp_f32_e32 v25, v25
	v_pk_mul_f32 v[4:5], v[4:5], v[248:249] op_sel:[0,1] op_sel_hi:[1,1]
	v_pk_mul_f32 v[6:7], v[6:7], v[248:249] op_sel:[0,1] op_sel_hi:[1,1]
	v_pk_mul_f32 v[8:9], v[8:9], v[248:249] op_sel:[0,1] op_sel_hi:[1,1]
	v_pk_mul_f32 v[10:11], v[10:11], v[248:249] op_sel:[0,1] op_sel_hi:[1,1]
	v_pk_add_f32 v[16:17], v[16:17], 1.0 op_sel_hi:[1,0]
	v_pk_add_f32 v[20:21], v[20:21], 1.0 op_sel_hi:[1,0]
	v_pk_add_f32 v[22:23], v[22:23], 1.0 op_sel_hi:[1,0]
	v_pk_add_f32 v[24:25], v[24:25], 1.0 op_sel_hi:[1,0]
	v_rcp_f32_e32 v16, v16
	v_rcp_f32_e32 v17, v17
	v_rcp_f32_e32 v20, v20
	v_rcp_f32_e32 v21, v21
	v_rcp_f32_e32 v22, v22
	v_rcp_f32_e32 v23, v23
	v_rcp_f32_e32 v24, v24
	v_rcp_f32_e32 v25, v25
	v_pk_mul_f32 v[4:5], v[4:5], v[16:17]
	v_pk_mul_f32 v[6:7], v[6:7], v[20:21]
	v_pk_mul_f32 v[8:9], v[8:9], v[22:23]
	v_pk_mul_f32 v[10:11], v[10:11], v[24:25]
	v_cvt_pk_bf16_f32 v0, v4, v5
	v_cvt_pk_bf16_f32 v1, v6, v7
	v_cvt_pk_bf16_f32 v2, v8, v9
	v_cvt_pk_bf16_f32 v3, v10, v11
	global_store_dwordx4 v[18:19], v[0:3], off
	s_cbranch_vccnz .LBB0_953
	s_andn2_b64 vcc, exec, s[12:13]
	s_cbranch_vccnz .LBB0_952
	s_barrier
	s_branch .LBB0_952

; #define PG8_STAGE(bufoff, gbase, voff) do { _Pragma("unroll") for (int _i = 0; _i < 2; ++_i) \
;         __builtin_amdgcn_global_load_lds((const unsigned*)((const char*)(gbase) + (voff)[_i]), (PG8_LAS unsigned*)(lds + (bufoff) + ldsw + _i * 8192), 16, 0, 0); } while (0)
; #define PG8_LDA(dst, b, h) do { _Pragma("unroll") for (int m = 0; m < 4; ++m) _Pragma("unroll") for (int k = 0; k < 2; ++k) dst[m][k] = *(const PG8_LAS bf16x8*)(lds + PG8_SA(b, h) + aoff + m * 2048 + k * 1024); } while (0)
; #define PG8_LDB(dst, b, h) do { _Pragma("unroll") for (int n = 0; n < 2; ++n) _Pragma("unroll") for (int k = 0; k < 2; ++k) dst[n][k] = *(const PG8_LAS bf16x8*)(lds + PG8_SB(b, h) + boff + n * 2048 + k * 1024); } while (0)
; #define PG8_WAIT_V(n) asm volatile("s_waitcnt vmcnt(" #n ")" ::: "memory")
; __device__ __forceinline__ float row_rs(const float* ssp, int row) { const unsigned long long v = ((const unsigned long long*)ssp)[row];
;     return __builtin_amdgcn_rsqf((float)v * (1.0f / 4294967296.0f) * (1.0f / 1024.0f) + RMS_EPS); }
; template <class Epi, class Sched, bool ALIGN_EPI = false, bool SP2 = false>
; __device__ __forceinline__ void gemm_phase(PG8_LAS unsigned char* lds, const Gemm g, const Sched& S, const Epi& E) {
;     ...
;         const char* nA = has_next ? (const char*)g.A + (size_t)nxt.pm * tstep : cA; const char* nB = has_next ? (const char*)g.Bt + (size_t)nxt.pn * tstep : cB;
;         for (int t = 0; t < nt; t += 2) {
;             const bool last = (t == nt - 2);
;             const char* a1 = cA + (size_t)(t + 1) * kstep;
;             const char* a2 = last ? nA : cA + (size_t)(t + 2) * kstep; const char* b2 = last ? nB : cB + (size_t)(t + 2) * kstep;
;             const char* a3 = a2 + kstep; const char* b3 = b2 + kstep;
;             if (last && has_next) S.a_ready(nxt);
;             if constexpr (SP2) {
;             PG8_LDB(B0, 0, 0); PG8_LDB(B1, 0, 1); PG8_SCHED; PG8_LDA(At, 0, 0); PG8_STAGE(PG8_SA(1, 1), a1 + hstep, voffA);
;             PG8_WAIT_V(8); PG8_WAIT_L(0); PG8_BAR; PG8_MMA(0, 0, At, B0); PG8_MMA(0, 1, At, B1); PG8_BAR; PG8_SCHED;
;             PG8_LDA(At, 0, 1); PG8_STAGE(PG8_SB(0, 0), b2, voffB); PG8_STAGE(PG8_SB(0, 1), b2 + hstep, voffB); PG8_STAGE(PG8_SA(0, 0), a2, voffA);
;             PG8_WAIT_V(8); PG8_WAIT_L(0); PG8_BAR; PG8_MMA(1, 0, At, B0); PG8_MMA(1, 1, At, B1); PG8_BAR; PG8_SCHED;
.LBB0_1118:
	v_lshl_add_u32 v144, s52, 8, v152
	v_ashrrev_i32_e32 v145, 31, v144
	v_lshl_add_u64 v[150:151], v[144:145], 3, s[36:37]
	global_load_dwordx2 v[234:235], v[150:151], off
	global_load_dwordx2 v[236:237], v[150:151], off offset:128
	global_load_dwordx2 v[238:239], v[150:151], off offset:256
	global_load_dwordx2 v[240:241], v[150:151], off offset:384
	global_load_dwordx2 v[242:243], v[150:151], off offset:1024
	global_load_dwordx2 v[244:245], v[150:151], off offset:1152
	global_load_dwordx2 v[246:247], v[150:151], off offset:1280
	global_load_dwordx2 v[248:249], v[150:151], off offset:1408
	s_ashr_i32 s45, s44, 31
	s_lshl_b64 s[48:49], s[44:45], 19
	s_add_u32 s48, s22, s48
	s_addc_u32 s49, s23, s49
	s_and_b64 s[50:51], s[10:11], exec
	s_cselect_b32 s45, s49, s55
	s_cselect_b32 s76, s48, s54
	s_ashr_i32 s43, s42, 31
	s_lshl_b64 s[50:51], s[42:43], 19
	s_add_u32 s50, s14, s50
	s_addc_u32 s51, s15, s51
	s_and_b64 s[58:59], s[10:11], exec
	s_cselect_b32 s43, s51, s57
	s_cselect_b32 s77, s50, s56
	s_add_u32 s54, s54, 0x40080
	s_addc_u32 s55, s55, 0
	s_add_u32 s82, s56, 0x100
	s_addc_u32 s83, s57, 0
	s_mov_b32 s84, -2
	ds_read_b128 v[144:147], v155
	ds_read_b128 v[148:151], v155 offset:1024
	ds_read_b128 v[160:163], v155 offset:2048
	ds_read_b128 v[164:167], v155 offset:3072
	ds_read_b128 v[168:171], v156
	ds_read_b128 v[172:175], v156 offset:1024
	ds_read_b128 v[176:179], v156 offset:2048
	ds_read_b128 v[182:185], v156 offset:3072
	s_add_u32 s56, s54, 0xfffc0080
	s_addc_u32 s57, s55, -1
	s_cmp_eq_u32 s84, 12
	s_cselect_b32 s59, s45, s57
	s_cselect_b32 s58, s76, s56
	s_cselect_b32 s57, s43, s83
	s_cselect_b32 s56, s77, s82
	v_lshl_add_u64 v[224:225], s[54:55], 0, v[136:137]
	s_add_i32 m0, s53, 0xc000
	ds_read_b128 v[186:189], v157
	ds_read_b128 v[190:193], v157 offset:1024
	ds_read_b128 v[194:197], v157 offset:2048
	ds_read_b128 v[198:201], v157 offset:3072
	ds_read_b128 v[208:211], v157 offset:4096
	ds_read_b128 v[212:215], v157 offset:5120
	ds_read_b128 v[216:219], v157 offset:6144
	ds_read_b128 v[220:223], v157 offset:7168
	global_load_lds_dwordx4 v[224:225], off
	v_lshl_add_u64 v[224:225], s[54:55], 0, v[138:139]
	s_add_i32 m0, s53, 0xe000
	s_nop 0
	global_load_lds_dwordx4 v[224:225], off
	s_waitcnt vmcnt(8)
	s_waitcnt lgkmcnt(0)
	s_barrier
	s_setprio 1
	s_waitcnt lgkmcnt(0)
	v_mfma_f32_16x16x32_bf16 v[124:127], v[144:147], v[186:189], 0
	v_mfma_f32_16x16x32_bf16 v[120:123], v[160:163], v[186:189], 0
	v_mfma_f32_16x16x32_bf16 v[108:111], v[144:147], v[194:197], 0
	v_mfma_f32_16x16x32_bf16 v[104:107], v[160:163], v[194:197], 0
	v_mfma_f32_16x16x32_bf16 v[92:95], v[144:147], v[208:211], 0
	v_mfma_f32_16x16x32_bf16 v[88:91], v[160:163], v[208:211], 0
	v_mfma_f32_16x16x32_bf16 v[76:79], v[144:147], v[216:219], 0
	v_mfma_f32_16x16x32_bf16 v[72:75], v[160:163], v[216:219], 0
	v_mfma_f32_16x16x32_bf16 v[124:127], v[148:151], v[190:193], v[124:127]
	v_mfma_f32_16x16x32_bf16 v[120:123], v[164:167], v[190:193], v[120:123]
	v_mfma_f32_16x16x32_bf16 v[108:111], v[148:151], v[198:201], v[108:111]
	v_mfma_f32_16x16x32_bf16 v[104:107], v[164:167], v[198:201], v[104:107]
	v_mfma_f32_16x16x32_bf16 v[92:95], v[148:151], v[212:215], v[92:95]
	v_mfma_f32_16x16x32_bf16 v[88:91], v[164:167], v[212:215], v[88:91]
	v_mfma_f32_16x16x32_bf16 v[76:79], v[148:151], v[220:223], v[76:79]
	v_mfma_f32_16x16x32_bf16 v[72:75], v[164:167], v[220:223], v[72:75]
	s_setprio 0
	s_setprio 1
	v_mfma_f32_16x16x32_bf16 v[116:119], v[168:171], v[186:189], 0
	v_mfma_f32_16x16x32_bf16 v[112:115], v[176:179], v[186:189], 0
	v_mfma_f32_16x16x32_bf16 v[100:103], v[168:171], v[194:197], 0
	v_mfma_f32_16x16x32_bf16 v[96:99], v[176:179], v[194:197], 0
	v_mfma_f32_16x16x32_bf16 v[84:87], v[168:171], v[208:211], 0
	v_mfma_f32_16x16x32_bf16 v[80:83], v[176:179], v[208:211], 0
	v_mfma_f32_16x16x32_bf16 v[68:71], v[168:171], v[216:219], 0
	v_mfma_f32_16x16x32_bf16 v[64:67], v[176:179], v[216:219], 0
	v_mfma_f32_16x16x32_bf16 v[116:119], v[172:175], v[190:193], v[116:119]
	v_mfma_f32_16x16x32_bf16 v[112:115], v[182:185], v[190:193], v[112:115]
	v_mfma_f32_16x16x32_bf16 v[100:103], v[172:175], v[198:201], v[100:103]
	v_mfma_f32_16x16x32_bf16 v[96:99], v[182:185], v[198:201], v[96:99]
	v_mfma_f32_16x16x32_bf16 v[84:87], v[172:175], v[212:215], v[84:87]
	v_mfma_f32_16x16x32_bf16 v[80:83], v[182:185], v[212:215], v[80:83]
	v_mfma_f32_16x16x32_bf16 v[68:71], v[172:175], v[220:223], v[68:71]
	v_mfma_f32_16x16x32_bf16 v[64:67], v[182:185], v[220:223], v[64:67]
	s_setprio 0
	s_barrier
	s_add_i32 s78, s66, s33
	v_lshl_add_u64 v[224:225], s[56:57], 0, v[132:133]
	s_mov_b32 m0, s78
	ds_read_b128 v[186:189], v157 offset:16384
	ds_read_b128 v[190:193], v157 offset:17408
	ds_read_b128 v[194:197], v157 offset:18432
	ds_read_b128 v[198:201], v157 offset:19456
	ds_read_b128 v[208:211], v157 offset:20480
	ds_read_b128 v[212:215], v157 offset:21504
	ds_read_b128 v[216:219], v157 offset:22528
	ds_read_b128 v[220:223], v157 offset:23552
	global_load_lds_dwordx4 v[224:225], off
	s_add_i32 m0, s78, 0x2000
	s_add_u32 s78, s56, 0x40000
	v_lshl_add_u64 v[226:227], s[56:57], 0, v[128:129]
	s_addc_u32 s79, s57, 0
	s_add_i32 s85, s67, s33
	global_load_lds_dwordx4 v[226:227], off
	v_lshl_add_u64 v[228:229], s[78:79], 0, v[132:133]
	s_mov_b32 m0, s85
	global_load_lds_dwordx4 v[228:229], off
	v_lshl_add_u64 v[228:229], s[78:79], 0, v[128:129]
	s_add_i32 m0, s85, 0x2000
	s_nop 0
	global_load_lds_dwordx4 v[228:229], off
	s_waitcnt vmcnt(6)
	s_waitcnt lgkmcnt(0)
	s_barrier
; #define PG8_STAGE(bufoff, gbase, voff) do { _Pragma("unroll") for (int _i = 0; _i < 2; ++_i) \
;         __builtin_amdgcn_global_load_lds((const unsigned*)((const char*)(gbase) + (voff)[_i]), (PG8_LAS unsigned*)(lds + (bufoff) + ldsw + _i * 8192), 16, 0, 0); } while (0)
; #define PG8_LDA(dst, b, h) do { _Pragma("unroll") for (int m = 0; m < 4; ++m) _Pragma("unroll") for (int k = 0; k < 2; ++k) dst[m][k] = *(const PG8_LAS bf16x8*)(lds + PG8_SA(b, h) + aoff + m * 2048 + k * 1024); } while (0)
; #define PG8_LDB(dst, b, h) do { _Pragma("unroll") for (int n = 0; n < 2; ++n) _Pragma("unroll") for (int k = 0; k < 2; ++k) dst[n][k] = *(const PG8_LAS bf16x8*)(lds + PG8_SB(b, h) + boff + n * 2048 + k * 1024); } while (0)
; #define PG8_MMA(ai, bj, At, Bt) do { __builtin_amdgcn_s_setprio(1); _Pragma("unroll") for (int m = 0; m < 4; ++m) _Pragma("unroll") for (int n = 0; n < 2; ++n) _Pragma("unroll") for (int k = 0; k < 2; ++k) \
;         acc[ai][bj][m][n] = __builtin_amdgcn_mfma_f32_16x16x32_bf16(Bt[n][k], At[m][k], acc[ai][bj][m][n], 0, 0, 0); __builtin_amdgcn_s_setprio(0); } while (0)
; #define PG8_WAIT_V(n) asm volatile("s_waitcnt vmcnt(" #n ")" ::: "memory")
; #define PG8_WAIT_L(n) asm volatile("s_waitcnt lgkmcnt(" #n ")" ::: "memory")
; #define PG8_BAR __builtin_amdgcn_s_barrier()
; #define PG8_SCHED __builtin_amdgcn_sched_barrier(0)
; template <class Epi, class Sched, bool ALIGN_EPI = false, bool SP2 = false>
; __device__ __forceinline__ void gemm_phase(PG8_LAS unsigned char* lds, const Gemm g, const Sched& S, const Epi& E) {
;     ...
;             PG8_LDB(B0, 0, 0); PG8_LDB(B1, 0, 1); PG8_SCHED; PG8_LDA(At, 0, 0); PG8_STAGE(PG8_SA(1, 1), a1 + hstep, voffA);
;             PG8_WAIT_V(8); PG8_WAIT_L(0); PG8_BAR; PG8_MMA(0, 0, At, B0); PG8_MMA(0, 1, At, B1); PG8_BAR; PG8_SCHED;
;             PG8_LDA(At, 0, 1); PG8_STAGE(PG8_SB(0, 0), b2, voffB); PG8_STAGE(PG8_SB(0, 1), b2 + hstep, voffB); PG8_STAGE(PG8_SA(0, 0), a2, voffA);
;             PG8_WAIT_V(8); PG8_WAIT_L(0); PG8_BAR; PG8_MMA(1, 0, At, B0); PG8_MMA(1, 1, At, B1); PG8_BAR; PG8_SCHED;
;             PG8_LDB(B0, 1, 0); PG8_LDB(B1, 1, 1); PG8_SCHED; PG8_LDA(At, 1, 0); PG8_STAGE(PG8_SA(0, 1), a2 + hstep, voffA);
;             PG8_WAIT_V(8); PG8_WAIT_L(0); PG8_BAR; PG8_MMA(0, 0, At, B0); PG8_MMA(0, 1, At, B1); PG8_BAR; PG8_SCHED;
	s_setprio 1
	s_waitcnt lgkmcnt(0)
	v_mfma_f32_16x16x32_bf16 v[60:63], v[144:147], v[186:189], 0
	v_mfma_f32_16x16x32_bf16 v[56:59], v[160:163], v[186:189], 0
	v_mfma_f32_16x16x32_bf16 v[44:47], v[144:147], v[194:197], 0
	v_mfma_f32_16x16x32_bf16 v[40:43], v[160:163], v[194:197], 0
	v_mfma_f32_16x16x32_bf16 v[28:31], v[144:147], v[208:211], 0
	v_mfma_f32_16x16x32_bf16 v[24:27], v[160:163], v[208:211], 0
	v_mfma_f32_16x16x32_bf16 v[12:15], v[144:147], v[216:219], 0
	v_mfma_f32_16x16x32_bf16 v[8:11], v[160:163], v[216:219], 0
	v_mfma_f32_16x16x32_bf16 v[60:63], v[148:151], v[190:193], v[60:63]
	v_mfma_f32_16x16x32_bf16 v[56:59], v[164:167], v[190:193], v[56:59]
	v_mfma_f32_16x16x32_bf16 v[44:47], v[148:151], v[198:201], v[44:47]
	v_mfma_f32_16x16x32_bf16 v[40:43], v[164:167], v[198:201], v[40:43]
	v_mfma_f32_16x16x32_bf16 v[28:31], v[148:151], v[212:215], v[28:31]
	v_mfma_f32_16x16x32_bf16 v[24:27], v[164:167], v[212:215], v[24:27]
	v_lshl_add_u64 v[228:229], s[58:59], 0, v[134:135]
	s_mov_b32 m0, s53
	s_nop 0
	global_load_lds_dwordx4 v[228:229], off
	v_mfma_f32_16x16x32_bf16 v[12:15], v[148:151], v[220:223], v[12:15]
	v_mfma_f32_16x16x32_bf16 v[8:11], v[164:167], v[220:223], v[8:11]
	s_setprio 0
	s_setprio 1
	v_mfma_f32_16x16x32_bf16 v[52:55], v[168:171], v[186:189], 0
	v_mfma_f32_16x16x32_bf16 v[48:51], v[176:179], v[186:189], 0
	v_mfma_f32_16x16x32_bf16 v[36:39], v[168:171], v[194:197], 0
	v_mfma_f32_16x16x32_bf16 v[32:35], v[176:179], v[194:197], 0
	v_mfma_f32_16x16x32_bf16 v[20:23], v[168:171], v[208:211], 0
	v_mfma_f32_16x16x32_bf16 v[16:19], v[176:179], v[208:211], 0
	v_mfma_f32_16x16x32_bf16 v[4:7], v[168:171], v[216:219], 0
	v_mfma_f32_16x16x32_bf16 v[0:3], v[176:179], v[216:219], 0
	v_mfma_f32_16x16x32_bf16 v[52:55], v[172:175], v[190:193], v[52:55]
	v_mfma_f32_16x16x32_bf16 v[48:51], v[182:185], v[190:193], v[48:51]
	v_mfma_f32_16x16x32_bf16 v[36:39], v[172:175], v[198:201], v[36:39]
	v_mfma_f32_16x16x32_bf16 v[32:35], v[182:185], v[198:201], v[32:35]
	v_mfma_f32_16x16x32_bf16 v[20:23], v[172:175], v[212:215], v[20:23]
	v_mfma_f32_16x16x32_bf16 v[16:19], v[182:185], v[212:215], v[16:19]
	v_lshl_add_u64 v[230:231], s[58:59], 0, v[130:131]
	s_mov_b32 m0, s60
	s_nop 0
	global_load_lds_dwordx4 v[230:231], off
	v_mfma_f32_16x16x32_bf16 v[4:7], v[172:175], v[220:223], v[4:7]
	v_mfma_f32_16x16x32_bf16 v[0:3], v[182:185], v[220:223], v[0:3]
	s_setprio 0
	s_barrier
	s_add_i32 s78, 0, 0x18000
	v_add_u32_e32 v159, s78, v153
	s_add_i32 s79, 0, 0x1c000
	ds_read_b128 v[144:147], v159
	ds_read_b128 v[148:151], v159 offset:1024
	ds_read_b128 v[160:163], v159 offset:2048
	ds_read_b128 v[164:167], v159 offset:3072
	v_add_u32_e32 v159, s79, v153
	ds_read_b128 v[168:171], v159
	ds_read_b128 v[172:175], v159 offset:1024
	ds_read_b128 v[176:179], v159 offset:2048
	ds_read_b128 v[182:185], v159 offset:3072
	s_add_u32 s58, s58, 0x40000
	s_addc_u32 s59, s59, 0
	s_mov_b32 m0, s61
	v_lshl_add_u64 v[232:233], s[58:59], 0, v[134:135]
	ds_read_b128 v[186:189], v157 offset:32768
	ds_read_b128 v[190:193], v157 offset:33792
	ds_read_b128 v[194:197], v157 offset:34816
	ds_read_b128 v[198:201], v157 offset:35840
	ds_read_b128 v[208:211], v157 offset:36864
	ds_read_b128 v[212:215], v157 offset:37888
	ds_read_b128 v[216:219], v157 offset:38912
	ds_read_b128 v[220:223], v157 offset:39936
	global_load_lds_dwordx4 v[232:233], off
	v_lshl_add_u64 v[232:233], s[58:59], 0, v[130:131]
	s_mov_b32 m0, s62
	s_nop 0
	global_load_lds_dwordx4 v[232:233], off
	s_waitcnt vmcnt(8)
	s_waitcnt lgkmcnt(0)
	s_barrier
	s_setprio 1
	s_waitcnt lgkmcnt(0)
	v_mfma_f32_16x16x32_bf16 v[124:127], v[144:147], v[186:189], v[124:127]
	v_mfma_f32_16x16x32_bf16 v[120:123], v[160:163], v[186:189], v[120:123]
	v_mfma_f32_16x16x32_bf16 v[108:111], v[144:147], v[194:197], v[108:111]
	v_mfma_f32_16x16x32_bf16 v[104:107], v[160:163], v[194:197], v[104:107]
	v_mfma_f32_16x16x32_bf16 v[92:95], v[144:147], v[208:211], v[92:95]
	v_mfma_f32_16x16x32_bf16 v[88:91], v[160:163], v[208:211], v[88:91]
	v_mfma_f32_16x16x32_bf16 v[76:79], v[144:147], v[216:219], v[76:79]
	v_mfma_f32_16x16x32_bf16 v[72:75], v[160:163], v[216:219], v[72:75]
	v_mfma_f32_16x16x32_bf16 v[124:127], v[148:151], v[190:193], v[124:127]
	v_mfma_f32_16x16x32_bf16 v[120:123], v[164:167], v[190:193], v[120:123]
	v_mfma_f32_16x16x32_bf16 v[108:111], v[148:151], v[198:201], v[108:111]
	v_mfma_f32_16x16x32_bf16 v[104:107], v[164:167], v[198:201], v[104:107]
	v_mfma_f32_16x16x32_bf16 v[92:95], v[148:151], v[212:215], v[92:95]
	v_mfma_f32_16x16x32_bf16 v[88:91], v[164:167], v[212:215], v[88:91]
	v_mfma_f32_16x16x32_bf16 v[76:79], v[148:151], v[220:223], v[76:79]
	v_mfma_f32_16x16x32_bf16 v[72:75], v[164:167], v[220:223], v[72:75]
	s_setprio 0
	s_setprio 1
	v_mfma_f32_16x16x32_bf16 v[116:119], v[168:171], v[186:189], v[116:119]
	v_mfma_f32_16x16x32_bf16 v[112:115], v[176:179], v[186:189], v[112:115]
	v_mfma_f32_16x16x32_bf16 v[100:103], v[168:171], v[194:197], v[100:103]
	v_mfma_f32_16x16x32_bf16 v[96:99], v[176:179], v[194:197], v[96:99]
	v_mfma_f32_16x16x32_bf16 v[84:87], v[168:171], v[208:211], v[84:87]
	v_mfma_f32_16x16x32_bf16 v[80:83], v[176:179], v[208:211], v[80:83]
	v_mfma_f32_16x16x32_bf16 v[68:71], v[168:171], v[216:219], v[68:71]
	v_mfma_f32_16x16x32_bf16 v[64:67], v[176:179], v[216:219], v[64:67]
	v_mfma_f32_16x16x32_bf16 v[116:119], v[172:175], v[190:193], v[116:119]
	v_mfma_f32_16x16x32_bf16 v[112:115], v[182:185], v[190:193], v[112:115]
	v_mfma_f32_16x16x32_bf16 v[100:103], v[172:175], v[198:201], v[100:103]
	v_mfma_f32_16x16x32_bf16 v[96:99], v[182:185], v[198:201], v[96:99]
	v_mfma_f32_16x16x32_bf16 v[84:87], v[172:175], v[212:215], v[84:87]
	v_mfma_f32_16x16x32_bf16 v[80:83], v[182:185], v[212:215], v[80:83]
	v_mfma_f32_16x16x32_bf16 v[68:71], v[172:175], v[220:223], v[68:71]
	v_mfma_f32_16x16x32_bf16 v[64:67], v[182:185], v[220:223], v[64:67]
	s_setprio 0
	s_barrier
; #define PG8_STAGE(bufoff, gbase, voff) do { _Pragma("unroll") for (int _i = 0; _i < 2; ++_i) \
;         __builtin_amdgcn_global_load_lds((const unsigned*)((const char*)(gbase) + (voff)[_i]), (PG8_LAS unsigned*)(lds + (bufoff) + ldsw + _i * 8192), 16, 0, 0); } while (0)
; #define PG8_LDA(dst, b, h) do { _Pragma("unroll") for (int m = 0; m < 4; ++m) _Pragma("unroll") for (int k = 0; k < 2; ++k) dst[m][k] = *(const PG8_LAS bf16x8*)(lds + PG8_SA(b, h) + aoff + m * 2048 + k * 1024); } while (0)
; #define PG8_LDB(dst, b, h) do { _Pragma("unroll") for (int n = 0; n < 2; ++n) _Pragma("unroll") for (int k = 0; k < 2; ++k) dst[n][k] = *(const PG8_LAS bf16x8*)(lds + PG8_SB(b, h) + boff + n * 2048 + k * 1024); } while (0)
; #define PG8_MMA(ai, bj, At, Bt) do { __builtin_amdgcn_s_setprio(1); _Pragma("unroll") for (int m = 0; m < 4; ++m) _Pragma("unroll") for (int n = 0; n < 2; ++n) _Pragma("unroll") for (int k = 0; k < 2; ++k) \
;         acc[ai][bj][m][n] = __builtin_amdgcn_mfma_f32_16x16x32_bf16(Bt[n][k], At[m][k], acc[ai][bj][m][n], 0, 0, 0); __builtin_amdgcn_s_setprio(0); } while (0)
; #define PG8_WAIT_V(n) asm volatile("s_waitcnt vmcnt(" #n ")" ::: "memory")
; #define PG8_WAIT_L(n) asm volatile("s_waitcnt lgkmcnt(" #n ")" ::: "memory")
; #define PG8_BAR __builtin_amdgcn_s_barrier()
; #define PG8_SCHED __builtin_amdgcn_sched_barrier(0)
; template <class Epi, class Sched, bool ALIGN_EPI = false, bool SP2 = false>
; __device__ __forceinline__ void gemm_phase(PG8_LAS unsigned char* lds, const Gemm g, const Sched& S, const Epi& E) {
;     ...
;             PG8_LDA(At, 0, 1); PG8_STAGE(PG8_SB(0, 0), b2, voffB); PG8_STAGE(PG8_SB(0, 1), b2 + hstep, voffB); PG8_STAGE(PG8_SA(0, 0), a2, voffA);
;             PG8_WAIT_V(8); PG8_WAIT_L(0); PG8_BAR; PG8_MMA(1, 0, At, B0); PG8_MMA(1, 1, At, B1); PG8_BAR; PG8_SCHED;
;             PG8_LDB(B0, 1, 0); PG8_LDB(B1, 1, 1); PG8_SCHED; PG8_LDA(At, 1, 0); PG8_STAGE(PG8_SA(0, 1), a2 + hstep, voffA);
;             PG8_WAIT_V(8); PG8_WAIT_L(0); PG8_BAR; PG8_MMA(0, 0, At, B0); PG8_MMA(0, 1, At, B1); PG8_BAR; PG8_SCHED;
;             PG8_LDA(At, 1, 1); PG8_STAGE(PG8_SB(1, 0), b3, voffB); PG8_STAGE(PG8_SB(1, 1), b3 + hstep, voffB); PG8_STAGE(PG8_SA(1, 0), a3, voffA);
;             PG8_WAIT_V(8); PG8_WAIT_L(0); PG8_BAR; PG8_MMA(1, 0, At, B0); PG8_MMA(1, 1, At, B1); PG8_BAR; PG8_SCHED;
	s_add_i32 s58, s78, s33
	v_lshl_add_u64 v[224:225], v[224:225], 0, s[12:13]
	s_mov_b32 m0, s58
	ds_read_b128 v[186:189], v157 offset:49152
	ds_read_b128 v[190:193], v157 offset:50176
	ds_read_b128 v[194:197], v157 offset:51200
	ds_read_b128 v[198:201], v157 offset:52224
	ds_read_b128 v[208:211], v157 offset:53248
	ds_read_b128 v[212:215], v157 offset:54272
	ds_read_b128 v[216:219], v157 offset:55296
	ds_read_b128 v[220:223], v157 offset:56320
	global_load_lds_dwordx4 v[224:225], off
	s_add_i32 m0, s58, 0x2000
	s_add_u32 s56, s56, 0x40080
	v_lshl_add_u64 v[224:225], v[226:227], 0, s[12:13]
	s_addc_u32 s57, s57, 0
	s_add_i32 s58, s79, s33
	global_load_lds_dwordx4 v[224:225], off
	v_lshl_add_u64 v[224:225], s[56:57], 0, v[132:133]
	s_mov_b32 m0, s58
	s_nop 0
	global_load_lds_dwordx4 v[224:225], off
	v_lshl_add_u64 v[224:225], s[56:57], 0, v[128:129]
	s_add_i32 m0, s58, 0x2000
	s_nop 0
	global_load_lds_dwordx4 v[224:225], off
	s_waitcnt vmcnt(6)
	s_waitcnt lgkmcnt(0)
	s_barrier
	s_setprio 1
	s_waitcnt lgkmcnt(0)
	v_mfma_f32_16x16x32_bf16 v[60:63], v[144:147], v[186:189], v[60:63]
	v_mfma_f32_16x16x32_bf16 v[56:59], v[160:163], v[186:189], v[56:59]
	v_mfma_f32_16x16x32_bf16 v[44:47], v[144:147], v[194:197], v[44:47]
	v_mfma_f32_16x16x32_bf16 v[40:43], v[160:163], v[194:197], v[40:43]
	v_mfma_f32_16x16x32_bf16 v[28:31], v[144:147], v[208:211], v[28:31]
	v_mfma_f32_16x16x32_bf16 v[24:27], v[160:163], v[208:211], v[24:27]
	v_mfma_f32_16x16x32_bf16 v[12:15], v[144:147], v[216:219], v[12:15]
	v_mfma_f32_16x16x32_bf16 v[8:11], v[160:163], v[216:219], v[8:11]
	v_mfma_f32_16x16x32_bf16 v[60:63], v[148:151], v[190:193], v[60:63]
	v_mfma_f32_16x16x32_bf16 v[56:59], v[164:167], v[190:193], v[56:59]
	v_mfma_f32_16x16x32_bf16 v[44:47], v[148:151], v[198:201], v[44:47]
	v_mfma_f32_16x16x32_bf16 v[40:43], v[164:167], v[198:201], v[40:43]
	v_mfma_f32_16x16x32_bf16 v[28:31], v[148:151], v[212:215], v[28:31]
	v_mfma_f32_16x16x32_bf16 v[24:27], v[164:167], v[212:215], v[24:27]
	v_lshl_add_u64 v[224:225], v[228:229], 0, s[12:13]
	s_mov_b32 m0, s64
	s_nop 0
	global_load_lds_dwordx4 v[224:225], off
	v_mfma_f32_16x16x32_bf16 v[12:15], v[148:151], v[220:223], v[12:15]
	v_mfma_f32_16x16x32_bf16 v[8:11], v[164:167], v[220:223], v[8:11]
	s_setprio 0
	s_setprio 1
	v_mfma_f32_16x16x32_bf16 v[52:55], v[168:171], v[186:189], v[52:55]
	v_mfma_f32_16x16x32_bf16 v[48:51], v[176:179], v[186:189], v[48:51]
	v_mfma_f32_16x16x32_bf16 v[36:39], v[168:171], v[194:197], v[36:39]
	v_mfma_f32_16x16x32_bf16 v[32:35], v[176:179], v[194:197], v[32:35]
	v_mfma_f32_16x16x32_bf16 v[20:23], v[168:171], v[208:211], v[20:23]
	v_mfma_f32_16x16x32_bf16 v[16:19], v[176:179], v[208:211], v[16:19]
	v_mfma_f32_16x16x32_bf16 v[4:7], v[168:171], v[216:219], v[4:7]
	v_mfma_f32_16x16x32_bf16 v[0:3], v[176:179], v[216:219], v[0:3]
	v_mfma_f32_16x16x32_bf16 v[52:55], v[172:175], v[190:193], v[52:55]
	v_mfma_f32_16x16x32_bf16 v[48:51], v[182:185], v[190:193], v[48:51]
	v_mfma_f32_16x16x32_bf16 v[36:39], v[172:175], v[198:201], v[36:39]
	v_mfma_f32_16x16x32_bf16 v[32:35], v[182:185], v[198:201], v[32:35]
	v_mfma_f32_16x16x32_bf16 v[20:23], v[172:175], v[212:215], v[20:23]
	v_mfma_f32_16x16x32_bf16 v[16:19], v[182:185], v[212:215], v[16:19]
	v_lshl_add_u64 v[224:225], v[230:231], 0, s[12:13]
	s_mov_b32 m0, s65
	s_nop 0
	global_load_lds_dwordx4 v[224:225], off
	v_mfma_f32_16x16x32_bf16 v[4:7], v[172:175], v[220:223], v[4:7]
	v_mfma_f32_16x16x32_bf16 v[0:3], v[182:185], v[220:223], v[0:3]
	s_setprio 0
	s_barrier
	s_add_i32 s84, s84, 2
	s_add_u32 s54, s54, 0x100
	s_addc_u32 s55, s55, 0
	s_add_u32 s82, s82, 0x100
	s_addc_u32 s83, s83, 0
.LBB0_1119:
	ds_read_b128 v[144:147], v155
	ds_read_b128 v[148:151], v155 offset:1024
	ds_read_b128 v[160:163], v155 offset:2048
	ds_read_b128 v[164:167], v155 offset:3072
	ds_read_b128 v[168:171], v156
	ds_read_b128 v[172:175], v156 offset:1024
	ds_read_b128 v[176:179], v156 offset:2048
	ds_read_b128 v[182:185], v156 offset:3072
	s_add_u32 s56, s54, 0xfffc0080
	s_addc_u32 s57, s55, -1
	s_cmp_eq_u32 s84, 12
	s_cselect_b32 s59, s45, s57
	s_cselect_b32 s58, s76, s56
	s_cselect_b32 s57, s43, s83
	s_cselect_b32 s56, s77, s82
	v_lshl_add_u64 v[224:225], s[54:55], 0, v[136:137]
	s_add_i32 m0, s53, 0xc000
	ds_read_b128 v[186:189], v157
	ds_read_b128 v[190:193], v157 offset:1024
	ds_read_b128 v[194:197], v157 offset:2048
	ds_read_b128 v[198:201], v157 offset:3072
	ds_read_b128 v[208:211], v157 offset:4096
	ds_read_b128 v[212:215], v157 offset:5120
	ds_read_b128 v[216:219], v157 offset:6144
	ds_read_b128 v[220:223], v157 offset:7168
	global_load_lds_dwordx4 v[224:225], off
	v_lshl_add_u64 v[224:225], s[54:55], 0, v[138:139]
	s_add_i32 m0, s53, 0xe000
	s_nop 0
	global_load_lds_dwordx4 v[224:225], off
	s_waitcnt vmcnt(8)
	s_waitcnt lgkmcnt(0)
	s_barrier
; #define PG8_STAGE(bufoff, gbase, voff) do { _Pragma("unroll") for (int _i = 0; _i < 2; ++_i) \
;         __builtin_amdgcn_global_load_lds((const unsigned*)((const char*)(gbase) + (voff)[_i]), (PG8_LAS unsigned*)(lds + (bufoff) + ldsw + _i * 8192), 16, 0, 0); } while (0)
; #define PG8_LDA(dst, b, h) do { _Pragma("unroll") for (int m = 0; m < 4; ++m) _Pragma("unroll") for (int k = 0; k < 2; ++k) dst[m][k] = *(const PG8_LAS bf16x8*)(lds + PG8_SA(b, h) + aoff + m * 2048 + k * 1024); } while (0)
; #define PG8_LDB(dst, b, h) do { _Pragma("unroll") for (int n = 0; n < 2; ++n) _Pragma("unroll") for (int k = 0; k < 2; ++k) dst[n][k] = *(const PG8_LAS bf16x8*)(lds + PG8_SB(b, h) + boff + n * 2048 + k * 1024); } while (0)
; #define PG8_MMA(ai, bj, At, Bt) do { __builtin_amdgcn_s_setprio(1); _Pragma("unroll") for (int m = 0; m < 4; ++m) _Pragma("unroll") for (int n = 0; n < 2; ++n) _Pragma("unroll") for (int k = 0; k < 2; ++k) \
;         acc[ai][bj][m][n] = __builtin_amdgcn_mfma_f32_16x16x32_bf16(Bt[n][k], At[m][k], acc[ai][bj][m][n], 0, 0, 0); __builtin_amdgcn_s_setprio(0); } while (0)
; #define PG8_WAIT_V(n) asm volatile("s_waitcnt vmcnt(" #n ")" ::: "memory")
; template <class Epi, class Sched, bool ALIGN_EPI = false, bool SP2 = false>
; __device__ __forceinline__ void gemm_phase(PG8_LAS unsigned char* lds, const Gemm g, const Sched& S, const Epi& E) {
;     ...
;             PG8_LDB(B0, 0, 0); PG8_LDB(B1, 0, 1); PG8_SCHED; PG8_LDA(At, 0, 0); PG8_STAGE(PG8_SA(1, 1), a1 + hstep, voffA);
;             PG8_WAIT_V(8); PG8_WAIT_L(0); PG8_BAR; PG8_MMA(0, 0, At, B0); PG8_MMA(0, 1, At, B1); PG8_BAR; PG8_SCHED;
;             PG8_LDA(At, 0, 1); PG8_STAGE(PG8_SB(0, 0), b2, voffB); PG8_STAGE(PG8_SB(0, 1), b2 + hstep, voffB); PG8_STAGE(PG8_SA(0, 0), a2, voffA);
;             PG8_WAIT_V(8); PG8_WAIT_L(0); PG8_BAR; PG8_MMA(1, 0, At, B0); PG8_MMA(1, 1, At, B1); PG8_BAR; PG8_SCHED;
;             PG8_LDB(B0, 1, 0); PG8_LDB(B1, 1, 1); PG8_SCHED; PG8_LDA(At, 1, 0); PG8_STAGE(PG8_SA(0, 1), a2 + hstep, voffA);
;             PG8_WAIT_V(8); PG8_WAIT_L(0); PG8_BAR; PG8_MMA(0, 0, At, B0); PG8_MMA(0, 1, At, B1); PG8_BAR; PG8_SCHED;
;             PG8_LDA(At, 1, 1); PG8_STAGE(PG8_SB(1, 0), b3, voffB); PG8_STAGE(PG8_SB(1, 1), b3 + hstep, voffB); PG8_STAGE(PG8_SA(1, 0), a3, voffA);
;             PG8_WAIT_V(8); PG8_WAIT_L(0); PG8_BAR; PG8_MMA(1, 0, At, B0); PG8_MMA(1, 1, At, B1); PG8_BAR; PG8_SCHED;
	s_setprio 1
	s_waitcnt lgkmcnt(0)
	v_mfma_f32_16x16x32_bf16 v[124:127], v[144:147], v[186:189], v[124:127]
	v_mfma_f32_16x16x32_bf16 v[120:123], v[160:163], v[186:189], v[120:123]
	v_mfma_f32_16x16x32_bf16 v[108:111], v[144:147], v[194:197], v[108:111]
	v_mfma_f32_16x16x32_bf16 v[104:107], v[160:163], v[194:197], v[104:107]
	v_mfma_f32_16x16x32_bf16 v[92:95], v[144:147], v[208:211], v[92:95]
	v_mfma_f32_16x16x32_bf16 v[88:91], v[160:163], v[208:211], v[88:91]
	v_mfma_f32_16x16x32_bf16 v[76:79], v[144:147], v[216:219], v[76:79]
	v_mfma_f32_16x16x32_bf16 v[72:75], v[160:163], v[216:219], v[72:75]
	v_mfma_f32_16x16x32_bf16 v[124:127], v[148:151], v[190:193], v[124:127]
	v_mfma_f32_16x16x32_bf16 v[120:123], v[164:167], v[190:193], v[120:123]
	v_mfma_f32_16x16x32_bf16 v[108:111], v[148:151], v[198:201], v[108:111]
	v_mfma_f32_16x16x32_bf16 v[104:107], v[164:167], v[198:201], v[104:107]
	v_mfma_f32_16x16x32_bf16 v[92:95], v[148:151], v[212:215], v[92:95]
	v_mfma_f32_16x16x32_bf16 v[88:91], v[164:167], v[212:215], v[88:91]
	v_mfma_f32_16x16x32_bf16 v[76:79], v[148:151], v[220:223], v[76:79]
	v_mfma_f32_16x16x32_bf16 v[72:75], v[164:167], v[220:223], v[72:75]
	s_setprio 0
	s_setprio 1
	v_mfma_f32_16x16x32_bf16 v[116:119], v[168:171], v[186:189], v[116:119]
	v_mfma_f32_16x16x32_bf16 v[112:115], v[176:179], v[186:189], v[112:115]
	v_mfma_f32_16x16x32_bf16 v[100:103], v[168:171], v[194:197], v[100:103]
	v_mfma_f32_16x16x32_bf16 v[96:99], v[176:179], v[194:197], v[96:99]
	v_mfma_f32_16x16x32_bf16 v[84:87], v[168:171], v[208:211], v[84:87]
	v_mfma_f32_16x16x32_bf16 v[80:83], v[176:179], v[208:211], v[80:83]
	v_mfma_f32_16x16x32_bf16 v[68:71], v[168:171], v[216:219], v[68:71]
	v_mfma_f32_16x16x32_bf16 v[64:67], v[176:179], v[216:219], v[64:67]
	v_mfma_f32_16x16x32_bf16 v[116:119], v[172:175], v[190:193], v[116:119]
	v_mfma_f32_16x16x32_bf16 v[112:115], v[182:185], v[190:193], v[112:115]
	v_mfma_f32_16x16x32_bf16 v[100:103], v[172:175], v[198:201], v[100:103]
	v_mfma_f32_16x16x32_bf16 v[96:99], v[182:185], v[198:201], v[96:99]
	v_mfma_f32_16x16x32_bf16 v[84:87], v[172:175], v[212:215], v[84:87]
	v_mfma_f32_16x16x32_bf16 v[80:83], v[182:185], v[212:215], v[80:83]
	v_mfma_f32_16x16x32_bf16 v[68:71], v[172:175], v[220:223], v[68:71]
	v_mfma_f32_16x16x32_bf16 v[64:67], v[182:185], v[220:223], v[64:67]
	s_setprio 0
	s_barrier
	s_add_i32 s78, s66, s33
	v_lshl_add_u64 v[224:225], s[56:57], 0, v[132:133]
	s_mov_b32 m0, s78
	ds_read_b128 v[186:189], v157 offset:16384
	ds_read_b128 v[190:193], v157 offset:17408
	ds_read_b128 v[194:197], v157 offset:18432
	ds_read_b128 v[198:201], v157 offset:19456
	ds_read_b128 v[208:211], v157 offset:20480
	ds_read_b128 v[212:215], v157 offset:21504
	ds_read_b128 v[216:219], v157 offset:22528
	ds_read_b128 v[220:223], v157 offset:23552
	global_load_lds_dwordx4 v[224:225], off
	s_add_i32 m0, s78, 0x2000
	s_add_u32 s78, s56, 0x40000
	v_lshl_add_u64 v[226:227], s[56:57], 0, v[128:129]
	s_addc_u32 s79, s57, 0
	s_add_i32 s85, s67, s33
	global_load_lds_dwordx4 v[226:227], off
	v_lshl_add_u64 v[228:229], s[78:79], 0, v[132:133]
	s_mov_b32 m0, s85
	global_load_lds_dwordx4 v[228:229], off
	v_lshl_add_u64 v[228:229], s[78:79], 0, v[128:129]
	s_add_i32 m0, s85, 0x2000
	s_nop 0
	global_load_lds_dwordx4 v[228:229], off
	s_waitcnt vmcnt(6)
	s_waitcnt lgkmcnt(0)
	s_barrier
	s_setprio 1
	s_waitcnt lgkmcnt(0)
	v_mfma_f32_16x16x32_bf16 v[60:63], v[144:147], v[186:189], v[60:63]
	v_mfma_f32_16x16x32_bf16 v[56:59], v[160:163], v[186:189], v[56:59]
	v_mfma_f32_16x16x32_bf16 v[44:47], v[144:147], v[194:197], v[44:47]
	v_mfma_f32_16x16x32_bf16 v[40:43], v[160:163], v[194:197], v[40:43]
	v_mfma_f32_16x16x32_bf16 v[28:31], v[144:147], v[208:211], v[28:31]
	v_mfma_f32_16x16x32_bf16 v[24:27], v[160:163], v[208:211], v[24:27]
	v_mfma_f32_16x16x32_bf16 v[12:15], v[144:147], v[216:219], v[12:15]
	v_mfma_f32_16x16x32_bf16 v[8:11], v[160:163], v[216:219], v[8:11]
	v_mfma_f32_16x16x32_bf16 v[60:63], v[148:151], v[190:193], v[60:63]
	v_mfma_f32_16x16x32_bf16 v[56:59], v[164:167], v[190:193], v[56:59]
	v_mfma_f32_16x16x32_bf16 v[44:47], v[148:151], v[198:201], v[44:47]
	v_mfma_f32_16x16x32_bf16 v[40:43], v[164:167], v[198:201], v[40:43]
	v_mfma_f32_16x16x32_bf16 v[28:31], v[148:151], v[212:215], v[28:31]
	v_mfma_f32_16x16x32_bf16 v[24:27], v[164:167], v[212:215], v[24:27]
	v_lshl_add_u64 v[228:229], s[58:59], 0, v[134:135]
	s_mov_b32 m0, s53
	s_nop 0
	global_load_lds_dwordx4 v[228:229], off
	v_mfma_f32_16x16x32_bf16 v[12:15], v[148:151], v[220:223], v[12:15]
	v_mfma_f32_16x16x32_bf16 v[8:11], v[164:167], v[220:223], v[8:11]
	s_setprio 0
	s_setprio 1
	v_mfma_f32_16x16x32_bf16 v[52:55], v[168:171], v[186:189], v[52:55]
	v_mfma_f32_16x16x32_bf16 v[48:51], v[176:179], v[186:189], v[48:51]
	v_mfma_f32_16x16x32_bf16 v[36:39], v[168:171], v[194:197], v[36:39]
	v_mfma_f32_16x16x32_bf16 v[32:35], v[176:179], v[194:197], v[32:35]
	v_mfma_f32_16x16x32_bf16 v[20:23], v[168:171], v[208:211], v[20:23]
	v_mfma_f32_16x16x32_bf16 v[16:19], v[176:179], v[208:211], v[16:19]
	v_mfma_f32_16x16x32_bf16 v[4:7], v[168:171], v[216:219], v[4:7]
	v_mfma_f32_16x16x32_bf16 v[0:3], v[176:179], v[216:219], v[0:3]
	v_mfma_f32_16x16x32_bf16 v[52:55], v[172:175], v[190:193], v[52:55]
	v_mfma_f32_16x16x32_bf16 v[48:51], v[182:185], v[190:193], v[48:51]
	v_mfma_f32_16x16x32_bf16 v[36:39], v[172:175], v[198:201], v[36:39]
	v_mfma_f32_16x16x32_bf16 v[32:35], v[182:185], v[198:201], v[32:35]
	v_mfma_f32_16x16x32_bf16 v[20:23], v[172:175], v[212:215], v[20:23]
	v_mfma_f32_16x16x32_bf16 v[16:19], v[182:185], v[212:215], v[16:19]
	v_lshl_add_u64 v[230:231], s[58:59], 0, v[130:131]
	s_mov_b32 m0, s60
	s_nop 0
	global_load_lds_dwordx4 v[230:231], off
	v_mfma_f32_16x16x32_bf16 v[4:7], v[172:175], v[220:223], v[4:7]
	v_mfma_f32_16x16x32_bf16 v[0:3], v[182:185], v[220:223], v[0:3]
	s_setprio 0
	s_barrier
; #define PG8_STAGE(bufoff, gbase, voff) do { _Pragma("unroll") for (int _i = 0; _i < 2; ++_i) \
;         __builtin_amdgcn_global_load_lds((const unsigned*)((const char*)(gbase) + (voff)[_i]), (PG8_LAS unsigned*)(lds + (bufoff) + ldsw + _i * 8192), 16, 0, 0); } while (0)
; #define PG8_LDA(dst, b, h) do { _Pragma("unroll") for (int m = 0; m < 4; ++m) _Pragma("unroll") for (int k = 0; k < 2; ++k) dst[m][k] = *(const PG8_LAS bf16x8*)(lds + PG8_SA(b, h) + aoff + m * 2048 + k * 1024); } while (0)
; #define PG8_LDB(dst, b, h) do { _Pragma("unroll") for (int n = 0; n < 2; ++n) _Pragma("unroll") for (int k = 0; k < 2; ++k) dst[n][k] = *(const PG8_LAS bf16x8*)(lds + PG8_SB(b, h) + boff + n * 2048 + k * 1024); } while (0)
; #define PG8_MMA(ai, bj, At, Bt) do { __builtin_amdgcn_s_setprio(1); _Pragma("unroll") for (int m = 0; m < 4; ++m) _Pragma("unroll") for (int n = 0; n < 2; ++n) _Pragma("unroll") for (int k = 0; k < 2; ++k) \
;         acc[ai][bj][m][n] = __builtin_amdgcn_mfma_f32_16x16x32_bf16(Bt[n][k], At[m][k], acc[ai][bj][m][n], 0, 0, 0); __builtin_amdgcn_s_setprio(0); } while (0)
; #define PG8_WAIT_V(n) asm volatile("s_waitcnt vmcnt(" #n ")" ::: "memory")
; #define PG8_WAIT_L(n) asm volatile("s_waitcnt lgkmcnt(" #n ")" ::: "memory")
; #define PG8_BAR __builtin_amdgcn_s_barrier()
; #define PG8_SCHED __builtin_amdgcn_sched_barrier(0)
; template <class Epi, class Sched, bool ALIGN_EPI = false, bool SP2 = false>
; __device__ __forceinline__ void gemm_phase(PG8_LAS unsigned char* lds, const Gemm g, const Sched& S, const Epi& E) {
;     ...
;             PG8_LDB(B0, 1, 0); PG8_LDB(B1, 1, 1); PG8_SCHED; PG8_LDA(At, 1, 0); PG8_STAGE(PG8_SA(0, 1), a2 + hstep, voffA);
;             PG8_WAIT_V(8); PG8_WAIT_L(0); PG8_BAR; PG8_MMA(0, 0, At, B0); PG8_MMA(0, 1, At, B1); PG8_BAR; PG8_SCHED;
;             PG8_LDA(At, 1, 1); PG8_STAGE(PG8_SB(1, 0), b3, voffB); PG8_STAGE(PG8_SB(1, 1), b3 + hstep, voffB); PG8_STAGE(PG8_SA(1, 0), a3, voffA);
;             PG8_WAIT_V(8); PG8_WAIT_L(0); PG8_BAR; PG8_MMA(1, 0, At, B0); PG8_MMA(1, 1, At, B1); PG8_BAR; PG8_SCHED;
	s_add_i32 s78, 0, 0x18000
	v_add_u32_e32 v159, s78, v153
	s_add_i32 s79, 0, 0x1c000
	ds_read_b128 v[144:147], v159
	ds_read_b128 v[148:151], v159 offset:1024
	ds_read_b128 v[160:163], v159 offset:2048
	ds_read_b128 v[164:167], v159 offset:3072
	v_add_u32_e32 v159, s79, v153
	ds_read_b128 v[168:171], v159
	ds_read_b128 v[172:175], v159 offset:1024
	ds_read_b128 v[176:179], v159 offset:2048
	ds_read_b128 v[182:185], v159 offset:3072
	s_add_u32 s58, s58, 0x40000
	s_addc_u32 s59, s59, 0
	s_mov_b32 m0, s61
	v_lshl_add_u64 v[232:233], s[58:59], 0, v[134:135]
	ds_read_b128 v[186:189], v157 offset:32768
	ds_read_b128 v[190:193], v157 offset:33792
	ds_read_b128 v[194:197], v157 offset:34816
	ds_read_b128 v[198:201], v157 offset:35840
	ds_read_b128 v[208:211], v157 offset:36864
	ds_read_b128 v[212:215], v157 offset:37888
	ds_read_b128 v[216:219], v157 offset:38912
	ds_read_b128 v[220:223], v157 offset:39936
	global_load_lds_dwordx4 v[232:233], off
	v_lshl_add_u64 v[232:233], s[58:59], 0, v[130:131]
	s_mov_b32 m0, s62
	s_nop 0
	global_load_lds_dwordx4 v[232:233], off
	s_waitcnt vmcnt(8)
	s_waitcnt lgkmcnt(0)
	s_barrier
	s_setprio 1
	s_waitcnt lgkmcnt(0)
	v_mfma_f32_16x16x32_bf16 v[124:127], v[144:147], v[186:189], v[124:127]
	v_mfma_f32_16x16x32_bf16 v[120:123], v[160:163], v[186:189], v[120:123]
	v_mfma_f32_16x16x32_bf16 v[108:111], v[144:147], v[194:197], v[108:111]
	v_mfma_f32_16x16x32_bf16 v[104:107], v[160:163], v[194:197], v[104:107]
	v_mfma_f32_16x16x32_bf16 v[92:95], v[144:147], v[208:211], v[92:95]
	v_mfma_f32_16x16x32_bf16 v[88:91], v[160:163], v[208:211], v[88:91]
	v_mfma_f32_16x16x32_bf16 v[76:79], v[144:147], v[216:219], v[76:79]
	v_mfma_f32_16x16x32_bf16 v[72:75], v[160:163], v[216:219], v[72:75]
	v_mfma_f32_16x16x32_bf16 v[124:127], v[148:151], v[190:193], v[124:127]
	v_mfma_f32_16x16x32_bf16 v[120:123], v[164:167], v[190:193], v[120:123]
	v_mfma_f32_16x16x32_bf16 v[108:111], v[148:151], v[198:201], v[108:111]
	v_mfma_f32_16x16x32_bf16 v[104:107], v[164:167], v[198:201], v[104:107]
	v_mfma_f32_16x16x32_bf16 v[92:95], v[148:151], v[212:215], v[92:95]
	v_mfma_f32_16x16x32_bf16 v[88:91], v[164:167], v[212:215], v[88:91]
	v_mfma_f32_16x16x32_bf16 v[76:79], v[148:151], v[220:223], v[76:79]
	v_mfma_f32_16x16x32_bf16 v[72:75], v[164:167], v[220:223], v[72:75]
	s_setprio 0
	s_setprio 1
	v_mfma_f32_16x16x32_bf16 v[116:119], v[168:171], v[186:189], v[116:119]
	v_mfma_f32_16x16x32_bf16 v[112:115], v[176:179], v[186:189], v[112:115]
	v_mfma_f32_16x16x32_bf16 v[100:103], v[168:171], v[194:197], v[100:103]
	v_mfma_f32_16x16x32_bf16 v[96:99], v[176:179], v[194:197], v[96:99]
	v_mfma_f32_16x16x32_bf16 v[84:87], v[168:171], v[208:211], v[84:87]
	v_mfma_f32_16x16x32_bf16 v[80:83], v[176:179], v[208:211], v[80:83]
	v_mfma_f32_16x16x32_bf16 v[68:71], v[168:171], v[216:219], v[68:71]
	v_mfma_f32_16x16x32_bf16 v[64:67], v[176:179], v[216:219], v[64:67]
	v_mfma_f32_16x16x32_bf16 v[116:119], v[172:175], v[190:193], v[116:119]
	v_mfma_f32_16x16x32_bf16 v[112:115], v[182:185], v[190:193], v[112:115]
	v_mfma_f32_16x16x32_bf16 v[100:103], v[172:175], v[198:201], v[100:103]
	v_mfma_f32_16x16x32_bf16 v[96:99], v[182:185], v[198:201], v[96:99]
	v_mfma_f32_16x16x32_bf16 v[84:87], v[172:175], v[212:215], v[84:87]
	v_mfma_f32_16x16x32_bf16 v[80:83], v[182:185], v[212:215], v[80:83]
	v_mfma_f32_16x16x32_bf16 v[68:71], v[172:175], v[220:223], v[68:71]
	v_mfma_f32_16x16x32_bf16 v[64:67], v[182:185], v[220:223], v[64:67]
	s_setprio 0
	s_barrier
	s_add_i32 s58, s78, s33
	v_lshl_add_u64 v[224:225], v[224:225], 0, s[12:13]
	s_mov_b32 m0, s58
	ds_read_b128 v[186:189], v157 offset:49152
	ds_read_b128 v[190:193], v157 offset:50176
	ds_read_b128 v[194:197], v157 offset:51200
	ds_read_b128 v[198:201], v157 offset:52224
	ds_read_b128 v[208:211], v157 offset:53248
	ds_read_b128 v[212:215], v157 offset:54272
	ds_read_b128 v[216:219], v157 offset:55296
	ds_read_b128 v[220:223], v157 offset:56320
	global_load_lds_dwordx4 v[224:225], off
	s_add_i32 m0, s58, 0x2000
	s_add_u32 s56, s56, 0x40080
	v_lshl_add_u64 v[224:225], v[226:227], 0, s[12:13]
	s_addc_u32 s57, s57, 0
	s_add_i32 s58, s79, s33
	global_load_lds_dwordx4 v[224:225], off
	v_lshl_add_u64 v[224:225], s[56:57], 0, v[132:133]
	s_mov_b32 m0, s58
	s_nop 0
	global_load_lds_dwordx4 v[224:225], off
	v_lshl_add_u64 v[224:225], s[56:57], 0, v[128:129]
	s_add_i32 m0, s58, 0x2000
	s_nop 0
	global_load_lds_dwordx4 v[224:225], off
	s_waitcnt vmcnt(6)
	s_waitcnt lgkmcnt(0)
	s_barrier
; __device__ __forceinline__ unsigned cvtpk(float lo, float hi) { f32x2v_ v = {lo, hi}; bf16x2v_ b = __builtin_convertvector(v, bf16x2v_); return __builtin_bit_cast(unsigned, b); }
; #define PG8_STAGE(bufoff, gbase, voff) do { _Pragma("unroll") for (int _i = 0; _i < 2; ++_i) \
;         __builtin_amdgcn_global_load_lds((const unsigned*)((const char*)(gbase) + (voff)[_i]), (PG8_LAS unsigned*)(lds + (bufoff) + ldsw + _i * 8192), 16, 0, 0); } while (0)
; #define PG8_LDA(dst, b, h) do { _Pragma("unroll") for (int m = 0; m < 4; ++m) _Pragma("unroll") for (int k = 0; k < 2; ++k) dst[m][k] = *(const PG8_LAS bf16x8*)(lds + PG8_SA(b, h) + aoff + m * 2048 + k * 1024); } while (0)
; #define PG8_WAIT_V(n) asm volatile("s_waitcnt vmcnt(" #n ")" ::: "memory")
; #define PG8_WAIT_L(n) asm volatile("s_waitcnt lgkmcnt(" #n ")" ::: "memory")
; #define PG8_BAR __builtin_amdgcn_s_barrier()
; #define PG8_SCHED __builtin_amdgcn_sched_barrier(0)
;     __device__ __forceinline__ void operator()(const f32x4 (&acc)[2][2][4][2], const Unit& u, int wr, int wc, int fr, int fq) const {
;         const int row0 = u.pm * BM + wr * 64 + fr, col0 = u.pn * HALF + wc * 32 + 8 * fq;
; #pragma unroll
;         for (int ai = 0; ai < 2; ++ai)
; #pragma unroll
;             for (int m = 0; m < 4; ++m) { const int row = row0 + ai * HALF + m * 16; const float rs = row_rs(ss, row);
;                 float hv[8];
; #pragma unroll
;                 for (int n = 0; n < 2; ++n)
; #pragma unroll
;                     for (int i = 0; i < 4; ++i) { const float g = acc[ai][0][m][n][i] * rs, uu = acc[ai][1][m][n][i] * rs;
;                         hv[n * 4 + i] = g * __builtin_amdgcn_rcpf(1.0f + __expf(-g)) * uu; }
;                 u32x4 w; w.x = cvtpk(hv[0], hv[1]); w.y = cvtpk(hv[2], hv[3]); w.z = cvtpk(hv[4], hv[5]); w.w = cvtpk(hv[6], hv[7]);
;                 *(u32x4*)(H + (size_t)row * ldh + col0) = w; }
; template <class Epi, class Sched, bool ALIGN_EPI = false, bool SP2 = false>
; __device__ __forceinline__ void gemm_phase(PG8_LAS unsigned char* lds, const Gemm g, const Sched& S, const Epi& E) {
;     ...
;             PG8_LDA(At, 1, 1); PG8_STAGE(PG8_SB(1, 0), b3, voffB); PG8_STAGE(PG8_SB(1, 1), b3 + hstep, voffB); PG8_STAGE(PG8_SA(1, 0), a3, voffA);
;             PG8_WAIT_V(8); PG8_WAIT_L(0); PG8_BAR; PG8_MMA(1, 0, At, B0); PG8_MMA(1, 1, At, B1); PG8_BAR; PG8_SCHED;
	s_setprio 1
	s_waitcnt lgkmcnt(0)
	v_mfma_f32_16x16x32_bf16 v[60:63], v[144:147], v[186:189], v[60:63]
	v_mfma_f32_16x16x32_bf16 v[56:59], v[160:163], v[186:189], v[56:59]
	v_mfma_f32_16x16x32_bf16 v[44:47], v[144:147], v[194:197], v[44:47]
	v_mfma_f32_16x16x32_bf16 v[40:43], v[160:163], v[194:197], v[40:43]
	v_mfma_f32_16x16x32_bf16 v[28:31], v[144:147], v[208:211], v[28:31]
	v_mfma_f32_16x16x32_bf16 v[24:27], v[160:163], v[208:211], v[24:27]
	v_mfma_f32_16x16x32_bf16 v[12:15], v[144:147], v[216:219], v[12:15]
	v_mfma_f32_16x16x32_bf16 v[8:11], v[160:163], v[216:219], v[8:11]
	v_mfma_f32_16x16x32_bf16 v[60:63], v[148:151], v[190:193], v[60:63]
	v_mfma_f32_16x16x32_bf16 v[56:59], v[164:167], v[190:193], v[56:59]
	v_mfma_f32_16x16x32_bf16 v[44:47], v[148:151], v[198:201], v[44:47]
	v_mfma_f32_16x16x32_bf16 v[40:43], v[164:167], v[198:201], v[40:43]
	v_mfma_f32_16x16x32_bf16 v[28:31], v[148:151], v[212:215], v[28:31]
	v_mfma_f32_16x16x32_bf16 v[24:27], v[164:167], v[212:215], v[24:27]
	v_lshl_add_u64 v[224:225], v[228:229], 0, s[12:13]
	s_mov_b32 m0, s64
	s_nop 0
	global_load_lds_dwordx4 v[224:225], off
	v_mfma_f32_16x16x32_bf16 v[12:15], v[148:151], v[220:223], v[12:15]
	v_mfma_f32_16x16x32_bf16 v[8:11], v[164:167], v[220:223], v[8:11]
	s_setprio 0
	s_setprio 1
	v_mfma_f32_16x16x32_bf16 v[52:55], v[168:171], v[186:189], v[52:55]
	v_mfma_f32_16x16x32_bf16 v[48:51], v[176:179], v[186:189], v[48:51]
	v_mfma_f32_16x16x32_bf16 v[36:39], v[168:171], v[194:197], v[36:39]
	v_mfma_f32_16x16x32_bf16 v[32:35], v[176:179], v[194:197], v[32:35]
	v_mfma_f32_16x16x32_bf16 v[20:23], v[168:171], v[208:211], v[20:23]
	v_mfma_f32_16x16x32_bf16 v[16:19], v[176:179], v[208:211], v[16:19]
	v_mfma_f32_16x16x32_bf16 v[4:7], v[168:171], v[216:219], v[4:7]
	v_mfma_f32_16x16x32_bf16 v[0:3], v[176:179], v[216:219], v[0:3]
	v_mfma_f32_16x16x32_bf16 v[52:55], v[172:175], v[190:193], v[52:55]
	v_mfma_f32_16x16x32_bf16 v[48:51], v[182:185], v[190:193], v[48:51]
	v_mfma_f32_16x16x32_bf16 v[36:39], v[172:175], v[198:201], v[36:39]
	v_mfma_f32_16x16x32_bf16 v[32:35], v[182:185], v[198:201], v[32:35]
	v_mfma_f32_16x16x32_bf16 v[20:23], v[172:175], v[212:215], v[20:23]
	v_mfma_f32_16x16x32_bf16 v[16:19], v[182:185], v[212:215], v[16:19]
	v_lshl_add_u64 v[224:225], v[230:231], 0, s[12:13]
	s_mov_b32 m0, s65
	s_nop 0
	global_load_lds_dwordx4 v[224:225], off
	v_mfma_f32_16x16x32_bf16 v[4:7], v[172:175], v[220:223], v[4:7]
	v_mfma_f32_16x16x32_bf16 v[0:3], v[182:185], v[220:223], v[0:3]
	s_setprio 0
	s_barrier
	s_add_i32 s84, s84, 2
	s_add_u32 s54, s54, 0x100
	s_addc_u32 s55, s55, 0
	s_add_u32 s82, s82, 0x100
	s_addc_u32 s83, s83, 0
	s_cmp_gt_u32 s84, 13
	s_cbranch_scc0 .LBB0_1119
	v_lshl_add_u32 v144, s52, 8, v152
	v_ashrrev_i32_e32 v145, 31, v144
	s_and_b64 vcc, exec, s[38:39]
	s_cbranch_vccz .LBB0_1122
	s_barrier
.LBB0_1122:
	v_lshl_or_b32 v160, s75, 7, v154
	v_ashrrev_i32_e32 v161, 31, v160
	v_or_b32_e32 v164, 16, v144
	v_ashrrev_i32_e32 v165, 31, v164
	v_lshl_add_u64 v[166:167], v[164:165], 3, s[36:37]
	v_mov_b64_e32 v[146:147], s[20:21]
	v_mad_i64_i32 v[162:163], s[54:55], v144, s74, v[146:147]
	s_andn2_b64 vcc, exec, s[10:11]
	s_mov_b64 s[10:11], -1
	s_waitcnt vmcnt(20)
	v_cvt_f32_u32_e32 v159, v235
	v_cvt_f32_u32_e32 v145, v234
	v_lshlrev_b64 v[148:149], 1, v[160:161]
	v_lshl_add_u64 v[162:163], v[162:163], 0, v[148:149]
	v_fmamk_f32 v145, v145, 0x2f800000, v159
	v_fmamk_f32 v145, v145, 0x3a800000, v158
	v_rsq_f32_e32 v160, v145
	s_nop 0
	v_mul_f32_e32 v234, 0xbfb8aa3b, v160
	v_mul_f32_e32 v235, v160, v160
	v_pk_mul_f32 v[160:161], v[124:125], v[234:235] op_sel_hi:[1,0]
	v_pk_mul_f32 v[168:169], v[126:127], v[234:235] op_sel_hi:[1,0]
	v_pk_mul_f32 v[170:171], v[120:121], v[234:235] op_sel_hi:[1,0]
	v_pk_mul_f32 v[172:173], v[122:123], v[234:235] op_sel_hi:[1,0]
	v_pk_mul_f32 v[116:117], v[116:117], v[124:125]
	v_pk_mul_f32 v[118:119], v[118:119], v[126:127]
	v_pk_mul_f32 v[120:121], v[112:113], v[120:121]
	v_pk_mul_f32 v[122:123], v[114:115], v[122:123]
	v_exp_f32_e32 v160, v160
	v_exp_f32_e32 v161, v161
	v_exp_f32_e32 v168, v168
	v_exp_f32_e32 v169, v169
	v_exp_f32_e32 v170, v170
	v_exp_f32_e32 v171, v171
	v_exp_f32_e32 v172, v172
	v_exp_f32_e32 v173, v173
	v_pk_mul_f32 v[116:117], v[116:117], v[234:235] op_sel:[0,1] op_sel_hi:[1,1]
	v_pk_mul_f32 v[118:119], v[118:119], v[234:235] op_sel:[0,1] op_sel_hi:[1,1]
	v_pk_mul_f32 v[120:121], v[120:121], v[234:235] op_sel:[0,1] op_sel_hi:[1,1]
	v_pk_mul_f32 v[122:123], v[122:123], v[234:235] op_sel:[0,1] op_sel_hi:[1,1]
	v_pk_add_f32 v[160:161], v[160:161], 1.0 op_sel_hi:[1,0]
	v_pk_add_f32 v[168:169], v[168:169], 1.0 op_sel_hi:[1,0]
	v_pk_add_f32 v[170:171], v[170:171], 1.0 op_sel_hi:[1,0]
	v_pk_add_f32 v[172:173], v[172:173], 1.0 op_sel_hi:[1,0]
	v_rcp_f32_e32 v160, v160
	v_rcp_f32_e32 v161, v161
	v_rcp_f32_e32 v168, v168
	v_rcp_f32_e32 v169, v169
	v_rcp_f32_e32 v170, v170
	v_rcp_f32_e32 v171, v171
	v_rcp_f32_e32 v172, v172
	v_rcp_f32_e32 v173, v173
	v_pk_mul_f32 v[116:117], v[116:117], v[160:161]
	v_pk_mul_f32 v[118:119], v[118:119], v[168:169]
	v_pk_mul_f32 v[120:121], v[120:121], v[170:171]
	v_pk_mul_f32 v[122:123], v[122:123], v[172:173]
	v_cvt_pk_bf16_f32 v112, v116, v117
	v_cvt_pk_bf16_f32 v113, v118, v119
	v_cvt_pk_bf16_f32 v114, v120, v121
	v_cvt_pk_bf16_f32 v115, v122, v123
	global_store_dwordx4 v[162:163], v[112:115], off
	s_nop 0
	s_nop 0
	v_or_b32_e32 v114, 32, v144
	s_waitcnt vmcnt(7)
; __device__ __forceinline__ unsigned cvtpk(float lo, float hi) { f32x2v_ v = {lo, hi}; bf16x2v_ b = __builtin_convertvector(v, bf16x2v_); return __builtin_bit_cast(unsigned, b); }
;     __device__ __forceinline__ void operator()(const f32x4 (&acc)[2][2][4][2], const Unit& u, int wr, int wc, int fr, int fq) const {
;     ...
;             for (int m = 0; m < 4; ++m) { const int row = row0 + ai * HALF + m * 16; const float rs = row_rs(ss, row);
;                 float hv[8];
; #pragma unroll
;                 for (int n = 0; n < 2; ++n)
; #pragma unroll
;                     for (int i = 0; i < 4; ++i) { const float g = acc[ai][0][m][n][i] * rs, uu = acc[ai][1][m][n][i] * rs;
;                         hv[n * 4 + i] = g * __builtin_amdgcn_rcpf(1.0f + __expf(-g)) * uu; }
;                 u32x4 w; w.x = cvtpk(hv[0], hv[1]); w.y = cvtpk(hv[2], hv[3]); w.z = cvtpk(hv[4], hv[5]); w.w = cvtpk(hv[6], hv[7]);
;                 *(u32x4*)(H + (size_t)row * ldh + col0) = w; }
	v_cvt_f32_u32_e32 v116, v237
	v_cvt_f32_u32_e32 v115, v236
	v_mad_i64_i32 v[112:113], s[54:55], v164, s74, v[146:147]
	v_fmamk_f32 v115, v115, 0x2f800000, v116
	v_fmamk_f32 v115, v115, 0x3a800000, v158
	v_rsq_f32_e32 v116, v115
	v_ashrrev_i32_e32 v115, 31, v114
	v_lshl_add_u64 v[118:119], v[114:115], 3, s[36:37]
	v_lshl_add_u64 v[112:113], v[112:113], 0, v[148:149]
	v_mul_f32_e32 v236, 0xbfb8aa3b, v116
	v_mul_f32_e32 v237, v116, v116
	v_pk_mul_f32 v[116:117], v[108:109], v[236:237] op_sel_hi:[1,0]
	v_pk_mul_f32 v[120:121], v[110:111], v[236:237] op_sel_hi:[1,0]
	v_pk_mul_f32 v[122:123], v[104:105], v[236:237] op_sel_hi:[1,0]
	v_pk_mul_f32 v[124:125], v[106:107], v[236:237] op_sel_hi:[1,0]
	v_pk_mul_f32 v[100:101], v[100:101], v[108:109]
	v_pk_mul_f32 v[102:103], v[102:103], v[110:111]
	v_pk_mul_f32 v[104:105], v[96:97], v[104:105]
	v_pk_mul_f32 v[106:107], v[98:99], v[106:107]
	v_exp_f32_e32 v116, v116
	v_exp_f32_e32 v117, v117
	v_exp_f32_e32 v120, v120
	v_exp_f32_e32 v121, v121
	v_exp_f32_e32 v122, v122
	v_exp_f32_e32 v123, v123
	v_exp_f32_e32 v124, v124
	v_exp_f32_e32 v125, v125
	v_pk_mul_f32 v[100:101], v[100:101], v[236:237] op_sel:[0,1] op_sel_hi:[1,1]
	v_pk_mul_f32 v[102:103], v[102:103], v[236:237] op_sel:[0,1] op_sel_hi:[1,1]
	v_pk_mul_f32 v[104:105], v[104:105], v[236:237] op_sel:[0,1] op_sel_hi:[1,1]
	v_pk_mul_f32 v[106:107], v[106:107], v[236:237] op_sel:[0,1] op_sel_hi:[1,1]
	v_pk_add_f32 v[116:117], v[116:117], 1.0 op_sel_hi:[1,0]
	v_pk_add_f32 v[120:121], v[120:121], 1.0 op_sel_hi:[1,0]
	v_pk_add_f32 v[122:123], v[122:123], 1.0 op_sel_hi:[1,0]
	v_pk_add_f32 v[124:125], v[124:125], 1.0 op_sel_hi:[1,0]
	v_rcp_f32_e32 v116, v116
	v_rcp_f32_e32 v117, v117
	v_rcp_f32_e32 v120, v120
	v_rcp_f32_e32 v121, v121
	v_rcp_f32_e32 v122, v122
	v_rcp_f32_e32 v123, v123
	v_rcp_f32_e32 v124, v124
	v_rcp_f32_e32 v125, v125
	v_pk_mul_f32 v[100:101], v[100:101], v[116:117]
	v_pk_mul_f32 v[102:103], v[102:103], v[120:121]
	v_pk_mul_f32 v[104:105], v[104:105], v[122:123]
	v_pk_mul_f32 v[106:107], v[106:107], v[124:125]
	v_cvt_pk_bf16_f32 v96, v100, v101
	v_cvt_pk_bf16_f32 v97, v102, v103
	v_cvt_pk_bf16_f32 v98, v104, v105
	v_cvt_pk_bf16_f32 v99, v106, v107
	global_store_dwordx4 v[112:113], v[96:99], off
	s_nop 0
	s_nop 0
	v_or_b32_e32 v98, 48, v144
	s_waitcnt vmcnt(7)
	v_cvt_f32_u32_e32 v100, v239
	v_cvt_f32_u32_e32 v99, v238
	v_mad_i64_i32 v[96:97], s[54:55], v114, s74, v[146:147]
	v_fmamk_f32 v99, v99, 0x2f800000, v100
	v_fmamk_f32 v99, v99, 0x3a800000, v158
	v_rsq_f32_e32 v100, v99
	v_ashrrev_i32_e32 v99, 31, v98
	v_lshl_add_u64 v[102:103], v[98:99], 3, s[36:37]
	v_lshl_add_u64 v[96:97], v[96:97], 0, v[148:149]
	v_mul_f32_e32 v238, 0xbfb8aa3b, v100
	v_mul_f32_e32 v239, v100, v100
	v_pk_mul_f32 v[100:101], v[92:93], v[238:239] op_sel_hi:[1,0]
	v_pk_mul_f32 v[104:105], v[94:95], v[238:239] op_sel_hi:[1,0]
	v_pk_mul_f32 v[106:107], v[88:89], v[238:239] op_sel_hi:[1,0]
	v_pk_mul_f32 v[108:109], v[90:91], v[238:239] op_sel_hi:[1,0]
	v_pk_mul_f32 v[84:85], v[84:85], v[92:93]
	v_pk_mul_f32 v[86:87], v[86:87], v[94:95]
	v_pk_mul_f32 v[88:89], v[80:81], v[88:89]
	v_pk_mul_f32 v[90:91], v[82:83], v[90:91]
	v_exp_f32_e32 v100, v100
	v_exp_f32_e32 v101, v101
	v_exp_f32_e32 v104, v104
	v_exp_f32_e32 v105, v105
	v_exp_f32_e32 v106, v106
	v_exp_f32_e32 v107, v107
	v_exp_f32_e32 v108, v108
	v_exp_f32_e32 v109, v109
	v_pk_mul_f32 v[84:85], v[84:85], v[238:239] op_sel:[0,1] op_sel_hi:[1,1]
	v_pk_mul_f32 v[86:87], v[86:87], v[238:239] op_sel:[0,1] op_sel_hi:[1,1]
	v_pk_mul_f32 v[88:89], v[88:89], v[238:239] op_sel:[0,1] op_sel_hi:[1,1]
	v_pk_mul_f32 v[90:91], v[90:91], v[238:239] op_sel:[0,1] op_sel_hi:[1,1]
	v_pk_add_f32 v[100:101], v[100:101], 1.0 op_sel_hi:[1,0]
	v_pk_add_f32 v[104:105], v[104:105], 1.0 op_sel_hi:[1,0]
	v_pk_add_f32 v[106:107], v[106:107], 1.0 op_sel_hi:[1,0]
	v_pk_add_f32 v[108:109], v[108:109], 1.0 op_sel_hi:[1,0]
	v_rcp_f32_e32 v100, v100
	v_rcp_f32_e32 v101, v101
	v_rcp_f32_e32 v104, v104
	v_rcp_f32_e32 v105, v105
	v_rcp_f32_e32 v106, v106
	v_rcp_f32_e32 v107, v107
	v_rcp_f32_e32 v108, v108
	v_rcp_f32_e32 v109, v109
	v_pk_mul_f32 v[84:85], v[84:85], v[100:101]
	v_pk_mul_f32 v[86:87], v[86:87], v[104:105]
	v_pk_mul_f32 v[88:89], v[88:89], v[106:107]
	v_pk_mul_f32 v[90:91], v[90:91], v[108:109]
	v_cvt_pk_bf16_f32 v80, v84, v85
	v_cvt_pk_bf16_f32 v81, v86, v87
	v_cvt_pk_bf16_f32 v82, v88, v89
	v_cvt_pk_bf16_f32 v83, v90, v91
	global_store_dwordx4 v[96:97], v[80:83], off
	s_nop 0
	s_waitcnt vmcnt(7)
	v_cvt_f32_u32_e32 v80, v241
	v_cvt_f32_u32_e32 v81, v240
	v_mad_i64_i32 v[82:83], s[54:55], v98, s74, v[146:147]
	v_fmamk_f32 v80, v81, 0x2f800000, v80
	v_fmamk_f32 v80, v80, 0x3a800000, v158
	v_rsq_f32_e32 v80, v80
	v_lshl_add_u64 v[82:83], v[82:83], 0, v[148:149]
	v_mul_f32_e32 v240, 0xbfb8aa3b, v80
	v_mul_f32_e32 v241, v80, v80
	v_pk_mul_f32 v[80:81], v[76:77], v[240:241] op_sel_hi:[1,0]
	v_pk_mul_f32 v[84:85], v[78:79], v[240:241] op_sel_hi:[1,0]
	v_pk_mul_f32 v[86:87], v[72:73], v[240:241] op_sel_hi:[1,0]
	v_pk_mul_f32 v[88:89], v[74:75], v[240:241] op_sel_hi:[1,0]
	v_pk_mul_f32 v[68:69], v[68:69], v[76:77]
	v_pk_mul_f32 v[70:71], v[70:71], v[78:79]
	v_pk_mul_f32 v[72:73], v[64:65], v[72:73]
	v_pk_mul_f32 v[74:75], v[66:67], v[74:75]
	v_exp_f32_e32 v80, v80
	v_exp_f32_e32 v81, v81
	v_exp_f32_e32 v84, v84
	v_exp_f32_e32 v85, v85
	v_exp_f32_e32 v86, v86
	v_exp_f32_e32 v87, v87
	v_exp_f32_e32 v88, v88
	v_exp_f32_e32 v89, v89
	v_pk_mul_f32 v[68:69], v[68:69], v[240:241] op_sel:[0,1] op_sel_hi:[1,1]
	v_pk_mul_f32 v[70:71], v[70:71], v[240:241] op_sel:[0,1] op_sel_hi:[1,1]
	v_pk_mul_f32 v[72:73], v[72:73], v[240:241] op_sel:[0,1] op_sel_hi:[1,1]
	v_pk_mul_f32 v[74:75], v[74:75], v[240:241] op_sel:[0,1] op_sel_hi:[1,1]
	v_pk_add_f32 v[80:81], v[80:81], 1.0 op_sel_hi:[1,0]
	v_pk_add_f32 v[84:85], v[84:85], 1.0 op_sel_hi:[1,0]
	v_pk_add_f32 v[86:87], v[86:87], 1.0 op_sel_hi:[1,0]
	v_pk_add_f32 v[88:89], v[88:89], 1.0 op_sel_hi:[1,0]
	v_rcp_f32_e32 v80, v80
	v_rcp_f32_e32 v81, v81
	v_rcp_f32_e32 v84, v84
	v_rcp_f32_e32 v85, v85
	v_rcp_f32_e32 v86, v86
	v_rcp_f32_e32 v87, v87
	v_rcp_f32_e32 v88, v88
	v_rcp_f32_e32 v89, v89
	v_pk_mul_f32 v[68:69], v[68:69], v[80:81]
	v_pk_mul_f32 v[70:71], v[70:71], v[84:85]
	v_pk_mul_f32 v[72:73], v[72:73], v[86:87]
	v_pk_mul_f32 v[74:75], v[74:75], v[88:89]
	v_cvt_pk_bf16_f32 v64, v68, v69
	v_cvt_pk_bf16_f32 v65, v70, v71
	v_cvt_pk_bf16_f32 v66, v72, v73
	v_cvt_pk_bf16_f32 v67, v74, v75
	global_store_dwordx4 v[82:83], v[64:67], off
	s_nop 0
	s_waitcnt vmcnt(7)
; __device__ __forceinline__ unsigned cvtpk(float lo, float hi) { f32x2v_ v = {lo, hi}; bf16x2v_ b = __builtin_convertvector(v, bf16x2v_); return __builtin_bit_cast(unsigned, b); }
;     __device__ __forceinline__ void operator()(const f32x4 (&acc)[2][2][4][2], const Unit& u, int wr, int wc, int fr, int fq) const {
;     ...
;             for (int m = 0; m < 4; ++m) { const int row = row0 + ai * HALF + m * 16; const float rs = row_rs(ss, row);
;                 float hv[8];
; #pragma unroll
;                 for (int n = 0; n < 2; ++n)
; #pragma unroll
;                     for (int i = 0; i < 4; ++i) { const float g = acc[ai][0][m][n][i] * rs, uu = acc[ai][1][m][n][i] * rs;
;                         hv[n * 4 + i] = g * __builtin_amdgcn_rcpf(1.0f + __expf(-g)) * uu; }
;                 u32x4 w; w.x = cvtpk(hv[0], hv[1]); w.y = cvtpk(hv[2], hv[3]); w.z = cvtpk(hv[4], hv[5]); w.w = cvtpk(hv[6], hv[7]);
;                 *(u32x4*)(H + (size_t)row * ldh + col0) = w; }
	v_cvt_f32_u32_e32 v64, v243
	v_cvt_f32_u32_e32 v66, v242
	v_add_u32_e32 v65, 0x80, v144
	v_fmamk_f32 v64, v66, 0x2f800000, v64
	v_fmamk_f32 v64, v64, 0x3a800000, v158
	v_rsq_f32_e32 v64, v64
	v_mad_i64_i32 v[66:67], s[54:55], v65, s74, v[146:147]
	v_lshl_add_u64 v[66:67], v[66:67], 0, v[148:149]
	v_mul_f32_e32 v242, 0xbfb8aa3b, v64
	v_mul_f32_e32 v243, v64, v64
	v_pk_mul_f32 v[64:65], v[60:61], v[242:243] op_sel_hi:[1,0]
	v_pk_mul_f32 v[68:69], v[62:63], v[242:243] op_sel_hi:[1,0]
	v_pk_mul_f32 v[70:71], v[56:57], v[242:243] op_sel_hi:[1,0]
	v_pk_mul_f32 v[72:73], v[58:59], v[242:243] op_sel_hi:[1,0]
	v_pk_mul_f32 v[52:53], v[52:53], v[60:61]
	v_pk_mul_f32 v[54:55], v[54:55], v[62:63]
	v_pk_mul_f32 v[56:57], v[48:49], v[56:57]
	v_pk_mul_f32 v[58:59], v[50:51], v[58:59]
	v_exp_f32_e32 v64, v64
	v_exp_f32_e32 v65, v65
	v_exp_f32_e32 v68, v68
	v_exp_f32_e32 v69, v69
	v_exp_f32_e32 v70, v70
	v_exp_f32_e32 v71, v71
	v_exp_f32_e32 v72, v72
	v_exp_f32_e32 v73, v73
	v_pk_mul_f32 v[52:53], v[52:53], v[242:243] op_sel:[0,1] op_sel_hi:[1,1]
	v_pk_mul_f32 v[54:55], v[54:55], v[242:243] op_sel:[0,1] op_sel_hi:[1,1]
	v_pk_mul_f32 v[56:57], v[56:57], v[242:243] op_sel:[0,1] op_sel_hi:[1,1]
	v_pk_mul_f32 v[58:59], v[58:59], v[242:243] op_sel:[0,1] op_sel_hi:[1,1]
	v_pk_add_f32 v[64:65], v[64:65], 1.0 op_sel_hi:[1,0]
	v_pk_add_f32 v[68:69], v[68:69], 1.0 op_sel_hi:[1,0]
	v_pk_add_f32 v[70:71], v[70:71], 1.0 op_sel_hi:[1,0]
	v_pk_add_f32 v[72:73], v[72:73], 1.0 op_sel_hi:[1,0]
	v_rcp_f32_e32 v64, v64
	v_rcp_f32_e32 v65, v65
	v_rcp_f32_e32 v68, v68
	v_rcp_f32_e32 v69, v69
	v_rcp_f32_e32 v70, v70
	v_rcp_f32_e32 v71, v71
	v_rcp_f32_e32 v72, v72
	v_rcp_f32_e32 v73, v73
	v_pk_mul_f32 v[52:53], v[52:53], v[64:65]
	v_pk_mul_f32 v[54:55], v[54:55], v[68:69]
	v_pk_mul_f32 v[56:57], v[56:57], v[70:71]
	v_pk_mul_f32 v[58:59], v[58:59], v[72:73]
	v_cvt_pk_bf16_f32 v48, v52, v53
	v_cvt_pk_bf16_f32 v49, v54, v55
	v_cvt_pk_bf16_f32 v50, v56, v57
	v_cvt_pk_bf16_f32 v51, v58, v59
	global_store_dwordx4 v[66:67], v[48:51], off
	s_nop 0
	s_waitcnt vmcnt(7)
	v_cvt_f32_u32_e32 v48, v245
	v_cvt_f32_u32_e32 v50, v244
	v_add_u32_e32 v49, 0x90, v144
	v_fmamk_f32 v48, v50, 0x2f800000, v48
	v_fmamk_f32 v48, v48, 0x3a800000, v158
	v_rsq_f32_e32 v48, v48
	v_mad_i64_i32 v[50:51], s[54:55], v49, s74, v[146:147]
	v_lshl_add_u64 v[50:51], v[50:51], 0, v[148:149]
	v_mul_f32_e32 v244, 0xbfb8aa3b, v48
	v_mul_f32_e32 v245, v48, v48
	v_pk_mul_f32 v[48:49], v[44:45], v[244:245] op_sel_hi:[1,0]
	v_pk_mul_f32 v[52:53], v[46:47], v[244:245] op_sel_hi:[1,0]
	v_pk_mul_f32 v[54:55], v[40:41], v[244:245] op_sel_hi:[1,0]
	v_pk_mul_f32 v[56:57], v[42:43], v[244:245] op_sel_hi:[1,0]
	v_pk_mul_f32 v[36:37], v[36:37], v[44:45]
	v_pk_mul_f32 v[38:39], v[38:39], v[46:47]
	v_pk_mul_f32 v[40:41], v[32:33], v[40:41]
	v_pk_mul_f32 v[42:43], v[34:35], v[42:43]
	v_exp_f32_e32 v48, v48
	v_exp_f32_e32 v49, v49
	v_exp_f32_e32 v52, v52
	v_exp_f32_e32 v53, v53
	v_exp_f32_e32 v54, v54
	v_exp_f32_e32 v55, v55
	v_exp_f32_e32 v56, v56
	v_exp_f32_e32 v57, v57
	v_pk_mul_f32 v[36:37], v[36:37], v[244:245] op_sel:[0,1] op_sel_hi:[1,1]
	v_pk_mul_f32 v[38:39], v[38:39], v[244:245] op_sel:[0,1] op_sel_hi:[1,1]
	v_pk_mul_f32 v[40:41], v[40:41], v[244:245] op_sel:[0,1] op_sel_hi:[1,1]
	v_pk_mul_f32 v[42:43], v[42:43], v[244:245] op_sel:[0,1] op_sel_hi:[1,1]
	v_pk_add_f32 v[48:49], v[48:49], 1.0 op_sel_hi:[1,0]
	v_pk_add_f32 v[52:53], v[52:53], 1.0 op_sel_hi:[1,0]
	v_pk_add_f32 v[54:55], v[54:55], 1.0 op_sel_hi:[1,0]
	v_pk_add_f32 v[56:57], v[56:57], 1.0 op_sel_hi:[1,0]
	v_rcp_f32_e32 v48, v48
	v_rcp_f32_e32 v49, v49
	v_rcp_f32_e32 v52, v52
	v_rcp_f32_e32 v53, v53
	v_rcp_f32_e32 v54, v54
	v_rcp_f32_e32 v55, v55
	v_rcp_f32_e32 v56, v56
	v_rcp_f32_e32 v57, v57
	v_pk_mul_f32 v[36:37], v[36:37], v[48:49]
	v_pk_mul_f32 v[38:39], v[38:39], v[52:53]
	v_pk_mul_f32 v[40:41], v[40:41], v[54:55]
	v_pk_mul_f32 v[42:43], v[42:43], v[56:57]
	v_cvt_pk_bf16_f32 v32, v36, v37
	v_cvt_pk_bf16_f32 v33, v38, v39
	v_cvt_pk_bf16_f32 v34, v40, v41
	v_cvt_pk_bf16_f32 v35, v42, v43
	global_store_dwordx4 v[50:51], v[32:35], off
	s_nop 0
	s_waitcnt vmcnt(7)
; __device__ __forceinline__ unsigned cvtpk(float lo, float hi) { f32x2v_ v = {lo, hi}; bf16x2v_ b = __builtin_convertvector(v, bf16x2v_); return __builtin_bit_cast(unsigned, b); }
; #define PG8_BAR __builtin_amdgcn_s_barrier()
;     __device__ __forceinline__ void operator()(const f32x4 (&acc)[2][2][4][2], const Unit& u, int wr, int wc, int fr, int fq) const {
;     ...
;             for (int m = 0; m < 4; ++m) { const int row = row0 + ai * HALF + m * 16; const float rs = row_rs(ss, row);
;                 float hv[8];
; #pragma unroll
;                 for (int n = 0; n < 2; ++n)
; #pragma unroll
;                     for (int i = 0; i < 4; ++i) { const float g = acc[ai][0][m][n][i] * rs, uu = acc[ai][1][m][n][i] * rs;
;                         hv[n * 4 + i] = g * __builtin_amdgcn_rcpf(1.0f + __expf(-g)) * uu; }
;                 u32x4 w; w.x = cvtpk(hv[0], hv[1]); w.y = cvtpk(hv[2], hv[3]); w.z = cvtpk(hv[4], hv[5]); w.w = cvtpk(hv[6], hv[7]);
;                 *(u32x4*)(H + (size_t)row * ldh + col0) = w; }
; template <class Epi, class Sched, bool ALIGN_EPI = false, bool SP2 = false>
; __device__ __forceinline__ void gemm_phase(PG8_LAS unsigned char* lds, const Gemm g, const Sched& S, const Epi& E) {
;     ...
;         if (!has_next) break;
; #pragma unroll
;         for (int a = 0; a < 2; ++a)
; #pragma unroll
;             for (int b = 0; b < 2; ++b)
; #pragma unroll
;                 for (int m = 0; m < 4; ++m)
; #pragma unroll
;                     for (int n = 0; n < 2; ++n) acc[a][b][m][n] = (f32x4){0.f, 0.f, 0.f, 0.f};
;         cur = nxt; cA = nA; cB = nB; ++ui;
;         if constexpr (ALIGN_EPI) { if (wr == 1) PG8_BAR; }
;     }
	v_cvt_f32_u32_e32 v32, v247
	v_cvt_f32_u32_e32 v34, v246
	v_add_u32_e32 v33, 0xa0, v144
	v_fmamk_f32 v32, v34, 0x2f800000, v32
	v_fmamk_f32 v32, v32, 0x3a800000, v158
	v_rsq_f32_e32 v32, v32
	v_mad_i64_i32 v[34:35], s[54:55], v33, s74, v[146:147]
	v_lshl_add_u64 v[34:35], v[34:35], 0, v[148:149]
	v_mul_f32_e32 v246, 0xbfb8aa3b, v32
	v_mul_f32_e32 v247, v32, v32
	v_pk_mul_f32 v[32:33], v[28:29], v[246:247] op_sel_hi:[1,0]
	v_pk_mul_f32 v[36:37], v[30:31], v[246:247] op_sel_hi:[1,0]
	v_pk_mul_f32 v[38:39], v[24:25], v[246:247] op_sel_hi:[1,0]
	v_pk_mul_f32 v[40:41], v[26:27], v[246:247] op_sel_hi:[1,0]
	v_pk_mul_f32 v[20:21], v[20:21], v[28:29]
	v_pk_mul_f32 v[22:23], v[22:23], v[30:31]
	v_pk_mul_f32 v[24:25], v[16:17], v[24:25]
	v_pk_mul_f32 v[26:27], v[18:19], v[26:27]
	v_exp_f32_e32 v32, v32
	v_exp_f32_e32 v33, v33
	v_exp_f32_e32 v36, v36
	v_exp_f32_e32 v37, v37
	v_exp_f32_e32 v38, v38
	v_exp_f32_e32 v39, v39
	v_exp_f32_e32 v40, v40
	v_exp_f32_e32 v41, v41
	v_pk_mul_f32 v[20:21], v[20:21], v[246:247] op_sel:[0,1] op_sel_hi:[1,1]
	v_pk_mul_f32 v[22:23], v[22:23], v[246:247] op_sel:[0,1] op_sel_hi:[1,1]
	v_pk_mul_f32 v[24:25], v[24:25], v[246:247] op_sel:[0,1] op_sel_hi:[1,1]
	v_pk_mul_f32 v[26:27], v[26:27], v[246:247] op_sel:[0,1] op_sel_hi:[1,1]
	v_pk_add_f32 v[32:33], v[32:33], 1.0 op_sel_hi:[1,0]
	v_pk_add_f32 v[36:37], v[36:37], 1.0 op_sel_hi:[1,0]
	v_pk_add_f32 v[38:39], v[38:39], 1.0 op_sel_hi:[1,0]
	v_pk_add_f32 v[40:41], v[40:41], 1.0 op_sel_hi:[1,0]
	v_rcp_f32_e32 v32, v32
	v_rcp_f32_e32 v33, v33
	v_rcp_f32_e32 v36, v36
	v_rcp_f32_e32 v37, v37
	v_rcp_f32_e32 v38, v38
	v_rcp_f32_e32 v39, v39
	v_rcp_f32_e32 v40, v40
	v_rcp_f32_e32 v41, v41
	v_pk_mul_f32 v[20:21], v[20:21], v[32:33]
	v_pk_mul_f32 v[22:23], v[22:23], v[36:37]
	v_pk_mul_f32 v[24:25], v[24:25], v[38:39]
	v_pk_mul_f32 v[26:27], v[26:27], v[40:41]
	v_cvt_pk_bf16_f32 v16, v20, v21
	v_cvt_pk_bf16_f32 v17, v22, v23
	v_cvt_pk_bf16_f32 v18, v24, v25
	v_cvt_pk_bf16_f32 v19, v26, v27
	global_store_dwordx4 v[34:35], v[16:19], off
	s_nop 0
	s_waitcnt vmcnt(7)
	v_cvt_f32_u32_e32 v16, v249
	v_cvt_f32_u32_e32 v18, v248
	v_add_u32_e32 v17, 0xb0, v144
	v_fmamk_f32 v16, v18, 0x2f800000, v16
	v_fmamk_f32 v16, v16, 0x3a800000, v158
	v_rsq_f32_e32 v16, v16
	v_mad_i64_i32 v[18:19], s[54:55], v17, s74, v[146:147]
	v_lshl_add_u64 v[18:19], v[18:19], 0, v[148:149]
	v_mul_f32_e32 v248, 0xbfb8aa3b, v16
	v_mul_f32_e32 v249, v16, v16
	v_pk_mul_f32 v[16:17], v[12:13], v[248:249] op_sel_hi:[1,0]
	v_pk_mul_f32 v[20:21], v[14:15], v[248:249] op_sel_hi:[1,0]
	v_pk_mul_f32 v[22:23], v[8:9], v[248:249] op_sel_hi:[1,0]
	v_pk_mul_f32 v[24:25], v[10:11], v[248:249] op_sel_hi:[1,0]
	v_pk_mul_f32 v[4:5], v[4:5], v[12:13]
	v_pk_mul_f32 v[6:7], v[6:7], v[14:15]
	v_pk_mul_f32 v[8:9], v[0:1], v[8:9]
	v_pk_mul_f32 v[10:11], v[2:3], v[10:11]
	v_exp_f32_e32 v16, v16
	v_exp_f32_e32 v17, v17
	v_exp_f32_e32 v20, v20
	v_exp_f32_e32 v21, v21
	v_exp_f32_e32 v22, v22
	v_exp_f32_e32 v23, v23
	v_exp_f32_e32 v24, v24
	v_exp_f32_e32 v25, v25
	v_pk_mul_f32 v[4:5], v[4:5], v[248:249] op_sel:[0,1] op_sel_hi:[1,1]
	v_pk_mul_f32 v[6:7], v[6:7], v[248:249] op_sel:[0,1] op_sel_hi:[1,1]
	v_pk_mul_f32 v[8:9], v[8:9], v[248:249] op_sel:[0,1] op_sel_hi:[1,1]
	v_pk_mul_f32 v[10:11], v[10:11], v[248:249] op_sel:[0,1] op_sel_hi:[1,1]
	v_pk_add_f32 v[16:17], v[16:17], 1.0 op_sel_hi:[1,0]
	v_pk_add_f32 v[20:21], v[20:21], 1.0 op_sel_hi:[1,0]
	v_pk_add_f32 v[22:23], v[22:23], 1.0 op_sel_hi:[1,0]
	v_pk_add_f32 v[24:25], v[24:25], 1.0 op_sel_hi:[1,0]
	v_rcp_f32_e32 v16, v16
	v_rcp_f32_e32 v17, v17
	v_rcp_f32_e32 v20, v20
	v_rcp_f32_e32 v21, v21
	v_rcp_f32_e32 v22, v22
	v_rcp_f32_e32 v23, v23
	v_rcp_f32_e32 v24, v24
	v_rcp_f32_e32 v25, v25
	v_pk_mul_f32 v[4:5], v[4:5], v[16:17]
	v_pk_mul_f32 v[6:7], v[6:7], v[20:21]
	v_pk_mul_f32 v[8:9], v[8:9], v[22:23]
	v_pk_mul_f32 v[10:11], v[10:11], v[24:25]
	v_cvt_pk_bf16_f32 v0, v4, v5
	v_cvt_pk_bf16_f32 v1, v6, v7
	v_cvt_pk_bf16_f32 v2, v8, v9
	v_cvt_pk_bf16_f32 v3, v10, v11
	global_store_dwordx4 v[18:19], v[0:3], off
	s_cbranch_vccnz .LBB0_1115
	s_andn2_b64 vcc, exec, s[0:1]
	s_cbranch_vccnz .LBB0_1114
	s_barrier
	s_branch .LBB0_1114

; #define PG8_STAGE(bufoff, gbase, voff) do { _Pragma("unroll") for (int _i = 0; _i < 2; ++_i) \
;         __builtin_amdgcn_global_load_lds((const unsigned*)((const char*)(gbase) + (voff)[_i]), (PG8_LAS unsigned*)(lds + (bufoff) + ldsw + _i * 8192), 16, 0, 0); } while (0)
; #define PG8_LDA(dst, b, h) do { _Pragma("unroll") for (int m = 0; m < 4; ++m) _Pragma("unroll") for (int k = 0; k < 2; ++k) dst[m][k] = *(const PG8_LAS bf16x8*)(lds + PG8_SA(b, h) + aoff + m * 2048 + k * 1024); } while (0)
; #define PG8_LDB(dst, b, h) do { _Pragma("unroll") for (int n = 0; n < 2; ++n) _Pragma("unroll") for (int k = 0; k < 2; ++k) dst[n][k] = *(const PG8_LAS bf16x8*)(lds + PG8_SB(b, h) + boff + n * 2048 + k * 1024); } while (0)
; #define PG8_WAIT_V(n) asm volatile("s_waitcnt vmcnt(" #n ")" ::: "memory")
; #define PG8_WAIT_L(n) asm volatile("s_waitcnt lgkmcnt(" #n ")" ::: "memory")
; __device__ __forceinline__ float row_rs(const float* ssp, int row) { const unsigned long long v = ((const unsigned long long*)ssp)[row];
;     return __builtin_amdgcn_rsqf((float)v * (1.0f / 4294967296.0f) * (1.0f / 1024.0f) + RMS_EPS); }
; template <class Epi, class Sched, bool ALIGN_EPI = false, bool SP2 = false>
; __device__ __forceinline__ void gemm_phase(PG8_LAS unsigned char* lds, const Gemm g, const Sched& S, const Epi& E) {
;     ...
;         const bool has_next = S.next(ui + 1, nxt);
;         const char* nA = has_next ? (const char*)g.A + (size_t)nxt.pm * tstep : cA; const char* nB = has_next ? (const char*)g.Bt + (size_t)nxt.pn * tstep : cB;
;         for (int t = 0; t < nt; t += 2) {
;             const bool last = (t == nt - 2);
;             const char* a1 = cA + (size_t)(t + 1) * kstep;
;             const char* a2 = last ? nA : cA + (size_t)(t + 2) * kstep; const char* b2 = last ? nB : cB + (size_t)(t + 2) * kstep;
;             const char* a3 = a2 + kstep; const char* b3 = b2 + kstep;
;             if (last && has_next) S.a_ready(nxt);
;             if constexpr (SP2) {
;             PG8_LDB(B0, 0, 0); PG8_LDB(B1, 0, 1); PG8_SCHED; PG8_LDA(At, 0, 0); PG8_STAGE(PG8_SA(1, 1), a1 + hstep, voffA);
;             PG8_WAIT_V(8); PG8_WAIT_L(0); PG8_BAR; PG8_MMA(0, 0, At, B0); PG8_MMA(0, 1, At, B1); PG8_BAR; PG8_SCHED;
;             PG8_LDA(At, 0, 1); PG8_STAGE(PG8_SB(0, 0), b2, voffB); PG8_STAGE(PG8_SB(0, 1), b2 + hstep, voffB); PG8_STAGE(PG8_SA(0, 0), a2, voffA);
.LBB0_1899:
	v_lshl_add_u32 v144, s36, 8, v152
	v_ashrrev_i32_e32 v145, 31, v144
	v_lshl_add_u64 v[150:151], v[144:145], 3, s[0:1]
	global_load_dwordx2 v[234:235], v[150:151], off
	global_load_dwordx2 v[236:237], v[150:151], off offset:128
	global_load_dwordx2 v[238:239], v[150:151], off offset:256
	global_load_dwordx2 v[240:241], v[150:151], off offset:384
	global_load_dwordx2 v[242:243], v[150:151], off offset:1024
	global_load_dwordx2 v[244:245], v[150:151], off offset:1152
	global_load_dwordx2 v[246:247], v[150:151], off offset:1280
	global_load_dwordx2 v[248:249], v[150:151], off offset:1408
	s_ashr_i32 s25, s24, 31
	s_lshl_b64 s[26:27], s[24:25], 19
	s_add_u32 s26, s22, s26
	s_addc_u32 s27, s23, s27
	s_and_b64 s[28:29], s[4:5], exec
	s_cselect_b32 s25, s27, s39
	s_cselect_b32 s53, s26, s38
	s_ashr_i32 s13, s12, 31
	s_lshl_b64 s[28:29], s[12:13], 19
	s_add_u32 s28, s3, s28
	s_addc_u32 s29, s14, s29
	s_and_b64 s[42:43], s[4:5], exec
	s_cselect_b32 s13, s29, s41
	s_cselect_b32 s54, s28, s40
	s_add_u32 s38, s38, 0x40080
	s_addc_u32 s39, s39, 0
	s_add_u32 s55, s40, 0x100
	s_addc_u32 s56, s41, 0
	s_mov_b32 s57, -2
	ds_read_b128 v[144:147], v155
	ds_read_b128 v[148:151], v155 offset:1024
	ds_read_b128 v[160:163], v155 offset:2048
	ds_read_b128 v[164:167], v155 offset:3072
	ds_read_b128 v[168:171], v156
	ds_read_b128 v[172:175], v156 offset:1024
	ds_read_b128 v[176:179], v156 offset:2048
	ds_read_b128 v[180:183], v156 offset:3072
	s_add_u32 s40, s38, 0xfffc0080
	s_addc_u32 s41, s39, -1
	s_cmp_eq_u32 s57, 12
	s_cselect_b32 s43, s25, s41
	s_cselect_b32 s42, s53, s40
	s_cselect_b32 s41, s13, s56
	s_cselect_b32 s40, s54, s55
	v_lshl_add_u64 v[218:219], s[38:39], 0, v[136:137]
	s_add_i32 m0, s34, 0xc000
	ds_read_b128 v[184:187], v157
	ds_read_b128 v[188:191], v157 offset:1024
	ds_read_b128 v[192:195], v157 offset:2048
	ds_read_b128 v[196:199], v157 offset:3072
	ds_read_b128 v[200:203], v157 offset:4096
	ds_read_b128 v[206:209], v157 offset:5120
	ds_read_b128 v[210:213], v157 offset:6144
	ds_read_b128 v[214:217], v157 offset:7168
	global_load_lds_dwordx4 v[218:219], off
	v_lshl_add_u64 v[218:219], s[38:39], 0, v[138:139]
	s_add_i32 m0, s34, 0xe000
	s_nop 0
	global_load_lds_dwordx4 v[218:219], off
	s_waitcnt vmcnt(8)
	s_waitcnt lgkmcnt(0)
	s_barrier
	s_setprio 1
	s_waitcnt lgkmcnt(0)
	v_mfma_f32_16x16x32_bf16 v[124:127], v[144:147], v[184:187], 0
	v_mfma_f32_16x16x32_bf16 v[120:123], v[160:163], v[184:187], 0
	v_mfma_f32_16x16x32_bf16 v[108:111], v[144:147], v[192:195], 0
	v_mfma_f32_16x16x32_bf16 v[104:107], v[160:163], v[192:195], 0
	v_mfma_f32_16x16x32_bf16 v[92:95], v[144:147], v[200:203], 0
	v_mfma_f32_16x16x32_bf16 v[88:91], v[160:163], v[200:203], 0
	v_mfma_f32_16x16x32_bf16 v[76:79], v[144:147], v[210:213], 0
	v_mfma_f32_16x16x32_bf16 v[72:75], v[160:163], v[210:213], 0
	v_mfma_f32_16x16x32_bf16 v[124:127], v[148:151], v[188:191], v[124:127]
	v_mfma_f32_16x16x32_bf16 v[120:123], v[164:167], v[188:191], v[120:123]
	v_mfma_f32_16x16x32_bf16 v[108:111], v[148:151], v[196:199], v[108:111]
	v_mfma_f32_16x16x32_bf16 v[104:107], v[164:167], v[196:199], v[104:107]
	v_mfma_f32_16x16x32_bf16 v[92:95], v[148:151], v[206:209], v[92:95]
	v_mfma_f32_16x16x32_bf16 v[88:91], v[164:167], v[206:209], v[88:91]
	v_mfma_f32_16x16x32_bf16 v[76:79], v[148:151], v[214:217], v[76:79]
	v_mfma_f32_16x16x32_bf16 v[72:75], v[164:167], v[214:217], v[72:75]
	s_setprio 0
	s_setprio 1
	v_mfma_f32_16x16x32_bf16 v[116:119], v[168:171], v[184:187], 0
	v_mfma_f32_16x16x32_bf16 v[112:115], v[176:179], v[184:187], 0
	v_mfma_f32_16x16x32_bf16 v[100:103], v[168:171], v[192:195], 0
	v_mfma_f32_16x16x32_bf16 v[96:99], v[176:179], v[192:195], 0
	v_mfma_f32_16x16x32_bf16 v[84:87], v[168:171], v[200:203], 0
	v_mfma_f32_16x16x32_bf16 v[80:83], v[176:179], v[200:203], 0
	v_mfma_f32_16x16x32_bf16 v[68:71], v[168:171], v[210:213], 0
	v_mfma_f32_16x16x32_bf16 v[64:67], v[176:179], v[210:213], 0
	v_mfma_f32_16x16x32_bf16 v[116:119], v[172:175], v[188:191], v[116:119]
	v_mfma_f32_16x16x32_bf16 v[112:115], v[180:183], v[188:191], v[112:115]
	v_mfma_f32_16x16x32_bf16 v[100:103], v[172:175], v[196:199], v[100:103]
	v_mfma_f32_16x16x32_bf16 v[96:99], v[180:183], v[196:199], v[96:99]
	v_mfma_f32_16x16x32_bf16 v[84:87], v[172:175], v[206:209], v[84:87]
	v_mfma_f32_16x16x32_bf16 v[80:83], v[180:183], v[206:209], v[80:83]
	v_mfma_f32_16x16x32_bf16 v[68:71], v[172:175], v[214:217], v[68:71]
	v_mfma_f32_16x16x32_bf16 v[64:67], v[180:183], v[214:217], v[64:67]
	s_setprio 0
	s_barrier
	s_add_i32 s58, s49, s15
	v_lshl_add_u64 v[218:219], s[40:41], 0, v[132:133]
	s_mov_b32 m0, s58
	ds_read_b128 v[184:187], v157 offset:16384
	ds_read_b128 v[188:191], v157 offset:17408
	ds_read_b128 v[192:195], v157 offset:18432
	ds_read_b128 v[196:199], v157 offset:19456
	ds_read_b128 v[200:203], v157 offset:20480
	ds_read_b128 v[206:209], v157 offset:21504
	ds_read_b128 v[210:213], v157 offset:22528
	ds_read_b128 v[214:217], v157 offset:23552
	global_load_lds_dwordx4 v[218:219], off
	s_add_i32 m0, s58, 0x2000
	s_add_u32 s58, s40, 0x40000
	v_lshl_add_u64 v[220:221], s[40:41], 0, v[128:129]
	s_addc_u32 s59, s41, 0
	s_add_i32 s60, s50, s15
	global_load_lds_dwordx4 v[220:221], off
	v_lshl_add_u64 v[222:223], s[58:59], 0, v[132:133]
	s_mov_b32 m0, s60
	global_load_lds_dwordx4 v[222:223], off
	v_lshl_add_u64 v[222:223], s[58:59], 0, v[128:129]
	s_add_i32 m0, s60, 0x2000
	s_nop 0
	global_load_lds_dwordx4 v[222:223], off
	s_waitcnt vmcnt(6)
	s_waitcnt lgkmcnt(0)
	s_barrier
; #define PG8_STAGE(bufoff, gbase, voff) do { _Pragma("unroll") for (int _i = 0; _i < 2; ++_i) \
;         __builtin_amdgcn_global_load_lds((const unsigned*)((const char*)(gbase) + (voff)[_i]), (PG8_LAS unsigned*)(lds + (bufoff) + ldsw + _i * 8192), 16, 0, 0); } while (0)
; #define PG8_LDA(dst, b, h) do { _Pragma("unroll") for (int m = 0; m < 4; ++m) _Pragma("unroll") for (int k = 0; k < 2; ++k) dst[m][k] = *(const PG8_LAS bf16x8*)(lds + PG8_SA(b, h) + aoff + m * 2048 + k * 1024); } while (0)
; #define PG8_LDB(dst, b, h) do { _Pragma("unroll") for (int n = 0; n < 2; ++n) _Pragma("unroll") for (int k = 0; k < 2; ++k) dst[n][k] = *(const PG8_LAS bf16x8*)(lds + PG8_SB(b, h) + boff + n * 2048 + k * 1024); } while (0)
; #define PG8_MMA(ai, bj, At, Bt) do { __builtin_amdgcn_s_setprio(1); _Pragma("unroll") for (int m = 0; m < 4; ++m) _Pragma("unroll") for (int n = 0; n < 2; ++n) _Pragma("unroll") for (int k = 0; k < 2; ++k) \
;         acc[ai][bj][m][n] = __builtin_amdgcn_mfma_f32_16x16x32_bf16(Bt[n][k], At[m][k], acc[ai][bj][m][n], 0, 0, 0); __builtin_amdgcn_s_setprio(0); } while (0)
; #define PG8_WAIT_V(n) asm volatile("s_waitcnt vmcnt(" #n ")" ::: "memory")
; #define PG8_WAIT_L(n) asm volatile("s_waitcnt lgkmcnt(" #n ")" ::: "memory")
; #define PG8_BAR __builtin_amdgcn_s_barrier()
; #define PG8_SCHED __builtin_amdgcn_sched_barrier(0)
; template <class Epi, class Sched, bool ALIGN_EPI = false, bool SP2 = false>
; __device__ __forceinline__ void gemm_phase(PG8_LAS unsigned char* lds, const Gemm g, const Sched& S, const Epi& E) {
;     ...
;             PG8_LDA(At, 0, 1); PG8_STAGE(PG8_SB(0, 0), b2, voffB); PG8_STAGE(PG8_SB(0, 1), b2 + hstep, voffB); PG8_STAGE(PG8_SA(0, 0), a2, voffA);
;             PG8_WAIT_V(8); PG8_WAIT_L(0); PG8_BAR; PG8_MMA(1, 0, At, B0); PG8_MMA(1, 1, At, B1); PG8_BAR; PG8_SCHED;
;             PG8_LDB(B0, 1, 0); PG8_LDB(B1, 1, 1); PG8_SCHED; PG8_LDA(At, 1, 0); PG8_STAGE(PG8_SA(0, 1), a2 + hstep, voffA);
;             PG8_WAIT_V(8); PG8_WAIT_L(0); PG8_BAR; PG8_MMA(0, 0, At, B0); PG8_MMA(0, 1, At, B1); PG8_BAR; PG8_SCHED;
	s_setprio 1
	s_waitcnt lgkmcnt(0)
	v_mfma_f32_16x16x32_bf16 v[60:63], v[144:147], v[184:187], 0
	v_mfma_f32_16x16x32_bf16 v[56:59], v[160:163], v[184:187], 0
	v_mfma_f32_16x16x32_bf16 v[44:47], v[144:147], v[192:195], 0
	v_mfma_f32_16x16x32_bf16 v[40:43], v[160:163], v[192:195], 0
	v_mfma_f32_16x16x32_bf16 v[28:31], v[144:147], v[200:203], 0
	v_mfma_f32_16x16x32_bf16 v[24:27], v[160:163], v[200:203], 0
	v_mfma_f32_16x16x32_bf16 v[12:15], v[144:147], v[210:213], 0
	v_mfma_f32_16x16x32_bf16 v[8:11], v[160:163], v[210:213], 0
	v_mfma_f32_16x16x32_bf16 v[60:63], v[148:151], v[188:191], v[60:63]
	v_mfma_f32_16x16x32_bf16 v[56:59], v[164:167], v[188:191], v[56:59]
	v_mfma_f32_16x16x32_bf16 v[44:47], v[148:151], v[196:199], v[44:47]
	v_mfma_f32_16x16x32_bf16 v[40:43], v[164:167], v[196:199], v[40:43]
	v_mfma_f32_16x16x32_bf16 v[28:31], v[148:151], v[206:209], v[28:31]
	v_mfma_f32_16x16x32_bf16 v[24:27], v[164:167], v[206:209], v[24:27]
	v_lshl_add_u64 v[222:223], s[42:43], 0, v[134:135]
	s_mov_b32 m0, s34
	s_nop 0
	global_load_lds_dwordx4 v[222:223], off
	v_mfma_f32_16x16x32_bf16 v[12:15], v[148:151], v[214:217], v[12:15]
	v_mfma_f32_16x16x32_bf16 v[8:11], v[164:167], v[214:217], v[8:11]
	s_setprio 0
	s_setprio 1
	v_mfma_f32_16x16x32_bf16 v[52:55], v[168:171], v[184:187], 0
	v_mfma_f32_16x16x32_bf16 v[48:51], v[176:179], v[184:187], 0
	v_mfma_f32_16x16x32_bf16 v[36:39], v[168:171], v[192:195], 0
	v_mfma_f32_16x16x32_bf16 v[32:35], v[176:179], v[192:195], 0
	v_mfma_f32_16x16x32_bf16 v[20:23], v[168:171], v[200:203], 0
	v_mfma_f32_16x16x32_bf16 v[16:19], v[176:179], v[200:203], 0
	v_mfma_f32_16x16x32_bf16 v[4:7], v[168:171], v[210:213], 0
	v_mfma_f32_16x16x32_bf16 v[0:3], v[176:179], v[210:213], 0
	v_mfma_f32_16x16x32_bf16 v[52:55], v[172:175], v[188:191], v[52:55]
	v_mfma_f32_16x16x32_bf16 v[48:51], v[180:183], v[188:191], v[48:51]
	v_mfma_f32_16x16x32_bf16 v[36:39], v[172:175], v[196:199], v[36:39]
	v_mfma_f32_16x16x32_bf16 v[32:35], v[180:183], v[196:199], v[32:35]
	v_mfma_f32_16x16x32_bf16 v[20:23], v[172:175], v[206:209], v[20:23]
	v_mfma_f32_16x16x32_bf16 v[16:19], v[180:183], v[206:209], v[16:19]
	v_lshl_add_u64 v[224:225], s[42:43], 0, v[130:131]
	s_mov_b32 m0, s37
	s_nop 0
	global_load_lds_dwordx4 v[224:225], off
	v_mfma_f32_16x16x32_bf16 v[4:7], v[172:175], v[214:217], v[4:7]
	v_mfma_f32_16x16x32_bf16 v[0:3], v[180:183], v[214:217], v[0:3]
	s_setprio 0
	s_barrier
	s_add_i32 s58, 0, 0x18000
	v_add_u32_e32 v159, s58, v153
	s_add_i32 s59, 0, 0x1c000
	ds_read_b128 v[144:147], v159
	ds_read_b128 v[148:151], v159 offset:1024
	ds_read_b128 v[160:163], v159 offset:2048
	ds_read_b128 v[164:167], v159 offset:3072
	v_add_u32_e32 v159, s59, v153
	ds_read_b128 v[168:171], v159
	ds_read_b128 v[172:175], v159 offset:1024
	ds_read_b128 v[176:179], v159 offset:2048
	ds_read_b128 v[180:183], v159 offset:3072
	s_add_u32 s42, s42, 0x40000
	s_addc_u32 s43, s43, 0
	s_mov_b32 m0, s44
	v_lshl_add_u64 v[226:227], s[42:43], 0, v[134:135]
	ds_read_b128 v[184:187], v157 offset:32768
	ds_read_b128 v[188:191], v157 offset:33792
	ds_read_b128 v[192:195], v157 offset:34816
	ds_read_b128 v[196:199], v157 offset:35840
	ds_read_b128 v[200:203], v157 offset:36864
	ds_read_b128 v[206:209], v157 offset:37888
	ds_read_b128 v[210:213], v157 offset:38912
	ds_read_b128 v[214:217], v157 offset:39936
	global_load_lds_dwordx4 v[226:227], off
	v_lshl_add_u64 v[226:227], s[42:43], 0, v[130:131]
	s_mov_b32 m0, s45
	s_nop 0
	global_load_lds_dwordx4 v[226:227], off
	s_waitcnt vmcnt(8)
	s_waitcnt lgkmcnt(0)
	s_barrier
	s_setprio 1
	s_waitcnt lgkmcnt(0)
	v_mfma_f32_16x16x32_bf16 v[124:127], v[144:147], v[184:187], v[124:127]
	v_mfma_f32_16x16x32_bf16 v[120:123], v[160:163], v[184:187], v[120:123]
	v_mfma_f32_16x16x32_bf16 v[108:111], v[144:147], v[192:195], v[108:111]
	v_mfma_f32_16x16x32_bf16 v[104:107], v[160:163], v[192:195], v[104:107]
	v_mfma_f32_16x16x32_bf16 v[92:95], v[144:147], v[200:203], v[92:95]
	v_mfma_f32_16x16x32_bf16 v[88:91], v[160:163], v[200:203], v[88:91]
	v_mfma_f32_16x16x32_bf16 v[76:79], v[144:147], v[210:213], v[76:79]
	v_mfma_f32_16x16x32_bf16 v[72:75], v[160:163], v[210:213], v[72:75]
	v_mfma_f32_16x16x32_bf16 v[124:127], v[148:151], v[188:191], v[124:127]
	v_mfma_f32_16x16x32_bf16 v[120:123], v[164:167], v[188:191], v[120:123]
	v_mfma_f32_16x16x32_bf16 v[108:111], v[148:151], v[196:199], v[108:111]
	v_mfma_f32_16x16x32_bf16 v[104:107], v[164:167], v[196:199], v[104:107]
	v_mfma_f32_16x16x32_bf16 v[92:95], v[148:151], v[206:209], v[92:95]
	v_mfma_f32_16x16x32_bf16 v[88:91], v[164:167], v[206:209], v[88:91]
	v_mfma_f32_16x16x32_bf16 v[76:79], v[148:151], v[214:217], v[76:79]
	v_mfma_f32_16x16x32_bf16 v[72:75], v[164:167], v[214:217], v[72:75]
	s_setprio 0
	s_setprio 1
	v_mfma_f32_16x16x32_bf16 v[116:119], v[168:171], v[184:187], v[116:119]
	v_mfma_f32_16x16x32_bf16 v[112:115], v[176:179], v[184:187], v[112:115]
	v_mfma_f32_16x16x32_bf16 v[100:103], v[168:171], v[192:195], v[100:103]
	v_mfma_f32_16x16x32_bf16 v[96:99], v[176:179], v[192:195], v[96:99]
	v_mfma_f32_16x16x32_bf16 v[84:87], v[168:171], v[200:203], v[84:87]
	v_mfma_f32_16x16x32_bf16 v[80:83], v[176:179], v[200:203], v[80:83]
	v_mfma_f32_16x16x32_bf16 v[68:71], v[168:171], v[210:213], v[68:71]
	v_mfma_f32_16x16x32_bf16 v[64:67], v[176:179], v[210:213], v[64:67]
	v_mfma_f32_16x16x32_bf16 v[116:119], v[172:175], v[188:191], v[116:119]
	v_mfma_f32_16x16x32_bf16 v[112:115], v[180:183], v[188:191], v[112:115]
	v_mfma_f32_16x16x32_bf16 v[100:103], v[172:175], v[196:199], v[100:103]
	v_mfma_f32_16x16x32_bf16 v[96:99], v[180:183], v[196:199], v[96:99]
	v_mfma_f32_16x16x32_bf16 v[84:87], v[172:175], v[206:209], v[84:87]
	v_mfma_f32_16x16x32_bf16 v[80:83], v[180:183], v[206:209], v[80:83]
	v_mfma_f32_16x16x32_bf16 v[68:71], v[172:175], v[214:217], v[68:71]
	v_mfma_f32_16x16x32_bf16 v[64:67], v[180:183], v[214:217], v[64:67]
	s_setprio 0
	s_barrier
; #define PG8_STAGE(bufoff, gbase, voff) do { _Pragma("unroll") for (int _i = 0; _i < 2; ++_i) \
;         __builtin_amdgcn_global_load_lds((const unsigned*)((const char*)(gbase) + (voff)[_i]), (PG8_LAS unsigned*)(lds + (bufoff) + ldsw + _i * 8192), 16, 0, 0); } while (0)
; #define PG8_LDA(dst, b, h) do { _Pragma("unroll") for (int m = 0; m < 4; ++m) _Pragma("unroll") for (int k = 0; k < 2; ++k) dst[m][k] = *(const PG8_LAS bf16x8*)(lds + PG8_SA(b, h) + aoff + m * 2048 + k * 1024); } while (0)
; #define PG8_LDB(dst, b, h) do { _Pragma("unroll") for (int n = 0; n < 2; ++n) _Pragma("unroll") for (int k = 0; k < 2; ++k) dst[n][k] = *(const PG8_LAS bf16x8*)(lds + PG8_SB(b, h) + boff + n * 2048 + k * 1024); } while (0)
; #define PG8_MMA(ai, bj, At, Bt) do { __builtin_amdgcn_s_setprio(1); _Pragma("unroll") for (int m = 0; m < 4; ++m) _Pragma("unroll") for (int n = 0; n < 2; ++n) _Pragma("unroll") for (int k = 0; k < 2; ++k) \
;         acc[ai][bj][m][n] = __builtin_amdgcn_mfma_f32_16x16x32_bf16(Bt[n][k], At[m][k], acc[ai][bj][m][n], 0, 0, 0); __builtin_amdgcn_s_setprio(0); } while (0)
; template <class Epi, class Sched, bool ALIGN_EPI = false, bool SP2 = false>
; __device__ __forceinline__ void gemm_phase(PG8_LAS unsigned char* lds, const Gemm g, const Sched& S, const Epi& E) {
;     ...
;         for (int t = 0; t < nt; t += 2) {
;             const bool last = (t == nt - 2);
;             const char* a1 = cA + (size_t)(t + 1) * kstep;
;             const char* a2 = last ? nA : cA + (size_t)(t + 2) * kstep; const char* b2 = last ? nB : cB + (size_t)(t + 2) * kstep;
;             const char* a3 = a2 + kstep; const char* b3 = b2 + kstep;
;             if (last && has_next) S.a_ready(nxt);
;             if constexpr (SP2) {
;             PG8_LDB(B0, 0, 0); PG8_LDB(B1, 0, 1); PG8_SCHED; PG8_LDA(At, 0, 0); PG8_STAGE(PG8_SA(1, 1), a1 + hstep, voffA);
;     ...
;             PG8_WAIT_V(8); PG8_WAIT_L(0); PG8_BAR; PG8_MMA(0, 0, At, B0); PG8_MMA(0, 1, At, B1); PG8_BAR; PG8_SCHED;
;             PG8_LDA(At, 1, 1); PG8_STAGE(PG8_SB(1, 0), b3, voffB); PG8_STAGE(PG8_SB(1, 1), b3 + hstep, voffB); PG8_STAGE(PG8_SA(1, 0), a3, voffA);
;             PG8_WAIT_V(8); PG8_WAIT_L(0); PG8_BAR; PG8_MMA(1, 0, At, B0); PG8_MMA(1, 1, At, B1); PG8_BAR; PG8_SCHED;
;             } else {
;             PG8_LDB(B0, 0, 0); PG8_SCHED; PG8_LDA(At, 0, 0); PG8_STAGE(PG8_SA(1, 1), a1 + hstep, voffA);
	s_add_i32 s42, s58, s15
	v_lshl_add_u64 v[218:219], v[218:219], 0, s[8:9]
	s_mov_b32 m0, s42
	ds_read_b128 v[184:187], v157 offset:49152
	ds_read_b128 v[188:191], v157 offset:50176
	ds_read_b128 v[192:195], v157 offset:51200
	ds_read_b128 v[196:199], v157 offset:52224
	ds_read_b128 v[200:203], v157 offset:53248
	ds_read_b128 v[206:209], v157 offset:54272
	ds_read_b128 v[210:213], v157 offset:55296
	ds_read_b128 v[214:217], v157 offset:56320
	global_load_lds_dwordx4 v[218:219], off
	s_add_i32 m0, s42, 0x2000
	s_add_u32 s40, s40, 0x40080
	v_lshl_add_u64 v[218:219], v[220:221], 0, s[8:9]
	s_addc_u32 s41, s41, 0
	s_add_i32 s42, s59, s15
	global_load_lds_dwordx4 v[218:219], off
	v_lshl_add_u64 v[218:219], s[40:41], 0, v[132:133]
	s_mov_b32 m0, s42
	s_nop 0
	global_load_lds_dwordx4 v[218:219], off
	v_lshl_add_u64 v[218:219], s[40:41], 0, v[128:129]
	s_add_i32 m0, s42, 0x2000
	s_nop 0
	global_load_lds_dwordx4 v[218:219], off
	s_waitcnt vmcnt(6)
	s_waitcnt lgkmcnt(0)
	s_barrier
	s_setprio 1
	s_waitcnt lgkmcnt(0)
	v_mfma_f32_16x16x32_bf16 v[60:63], v[144:147], v[184:187], v[60:63]
	v_mfma_f32_16x16x32_bf16 v[56:59], v[160:163], v[184:187], v[56:59]
	v_mfma_f32_16x16x32_bf16 v[44:47], v[144:147], v[192:195], v[44:47]
	v_mfma_f32_16x16x32_bf16 v[40:43], v[160:163], v[192:195], v[40:43]
	v_mfma_f32_16x16x32_bf16 v[28:31], v[144:147], v[200:203], v[28:31]
	v_mfma_f32_16x16x32_bf16 v[24:27], v[160:163], v[200:203], v[24:27]
	v_mfma_f32_16x16x32_bf16 v[12:15], v[144:147], v[210:213], v[12:15]
	v_mfma_f32_16x16x32_bf16 v[8:11], v[160:163], v[210:213], v[8:11]
	v_mfma_f32_16x16x32_bf16 v[60:63], v[148:151], v[188:191], v[60:63]
	v_mfma_f32_16x16x32_bf16 v[56:59], v[164:167], v[188:191], v[56:59]
	v_mfma_f32_16x16x32_bf16 v[44:47], v[148:151], v[196:199], v[44:47]
	v_mfma_f32_16x16x32_bf16 v[40:43], v[164:167], v[196:199], v[40:43]
	v_mfma_f32_16x16x32_bf16 v[28:31], v[148:151], v[206:209], v[28:31]
	v_mfma_f32_16x16x32_bf16 v[24:27], v[164:167], v[206:209], v[24:27]
	v_lshl_add_u64 v[218:219], v[222:223], 0, s[8:9]
	s_mov_b32 m0, s47
	s_nop 0
	global_load_lds_dwordx4 v[218:219], off
	v_mfma_f32_16x16x32_bf16 v[12:15], v[148:151], v[214:217], v[12:15]
	v_mfma_f32_16x16x32_bf16 v[8:11], v[164:167], v[214:217], v[8:11]
	s_setprio 0
	s_setprio 1
	v_mfma_f32_16x16x32_bf16 v[52:55], v[168:171], v[184:187], v[52:55]
	v_mfma_f32_16x16x32_bf16 v[48:51], v[176:179], v[184:187], v[48:51]
	v_mfma_f32_16x16x32_bf16 v[36:39], v[168:171], v[192:195], v[36:39]
	v_mfma_f32_16x16x32_bf16 v[32:35], v[176:179], v[192:195], v[32:35]
	v_mfma_f32_16x16x32_bf16 v[20:23], v[168:171], v[200:203], v[20:23]
	v_mfma_f32_16x16x32_bf16 v[16:19], v[176:179], v[200:203], v[16:19]
	v_mfma_f32_16x16x32_bf16 v[4:7], v[168:171], v[210:213], v[4:7]
	v_mfma_f32_16x16x32_bf16 v[0:3], v[176:179], v[210:213], v[0:3]
	v_mfma_f32_16x16x32_bf16 v[52:55], v[172:175], v[188:191], v[52:55]
	v_mfma_f32_16x16x32_bf16 v[48:51], v[180:183], v[188:191], v[48:51]
	v_mfma_f32_16x16x32_bf16 v[36:39], v[172:175], v[196:199], v[36:39]
	v_mfma_f32_16x16x32_bf16 v[32:35], v[180:183], v[196:199], v[32:35]
	v_mfma_f32_16x16x32_bf16 v[20:23], v[172:175], v[206:209], v[20:23]
	v_mfma_f32_16x16x32_bf16 v[16:19], v[180:183], v[206:209], v[16:19]
	v_lshl_add_u64 v[218:219], v[224:225], 0, s[8:9]
	s_mov_b32 m0, s48
	s_nop 0
	global_load_lds_dwordx4 v[218:219], off
	v_mfma_f32_16x16x32_bf16 v[4:7], v[172:175], v[214:217], v[4:7]
	v_mfma_f32_16x16x32_bf16 v[0:3], v[180:183], v[214:217], v[0:3]
	s_setprio 0
	s_barrier
	s_add_i32 s57, s57, 2
	s_add_u32 s38, s38, 0x100
	s_addc_u32 s39, s39, 0
	s_add_u32 s55, s55, 0x100
	s_addc_u32 s56, s56, 0
.LBB0_1900:
	ds_read_b128 v[144:147], v155
	ds_read_b128 v[148:151], v155 offset:1024
	ds_read_b128 v[160:163], v155 offset:2048
	ds_read_b128 v[164:167], v155 offset:3072
	ds_read_b128 v[168:171], v156
	ds_read_b128 v[172:175], v156 offset:1024
	ds_read_b128 v[176:179], v156 offset:2048
	ds_read_b128 v[180:183], v156 offset:3072
	s_add_u32 s40, s38, 0xfffc0080
	s_addc_u32 s41, s39, -1
	s_cmp_eq_u32 s57, 12
	s_cselect_b32 s43, s25, s41
	s_cselect_b32 s42, s53, s40
	s_cselect_b32 s41, s13, s56
	s_cselect_b32 s40, s54, s55
	v_lshl_add_u64 v[218:219], s[38:39], 0, v[136:137]
	s_add_i32 m0, s34, 0xc000
	ds_read_b128 v[184:187], v157
	ds_read_b128 v[188:191], v157 offset:1024
	ds_read_b128 v[192:195], v157 offset:2048
	ds_read_b128 v[196:199], v157 offset:3072
	ds_read_b128 v[200:203], v157 offset:4096
	ds_read_b128 v[206:209], v157 offset:5120
	ds_read_b128 v[210:213], v157 offset:6144
	ds_read_b128 v[214:217], v157 offset:7168
	global_load_lds_dwordx4 v[218:219], off
	v_lshl_add_u64 v[218:219], s[38:39], 0, v[138:139]
	s_add_i32 m0, s34, 0xe000
	s_nop 0
	global_load_lds_dwordx4 v[218:219], off
	s_waitcnt vmcnt(8)
	s_waitcnt lgkmcnt(0)
	s_barrier
; #define PG8_STAGE(bufoff, gbase, voff) do { _Pragma("unroll") for (int _i = 0; _i < 2; ++_i) \
;         __builtin_amdgcn_global_load_lds((const unsigned*)((const char*)(gbase) + (voff)[_i]), (PG8_LAS unsigned*)(lds + (bufoff) + ldsw + _i * 8192), 16, 0, 0); } while (0)
; #define PG8_LDA(dst, b, h) do { _Pragma("unroll") for (int m = 0; m < 4; ++m) _Pragma("unroll") for (int k = 0; k < 2; ++k) dst[m][k] = *(const PG8_LAS bf16x8*)(lds + PG8_SA(b, h) + aoff + m * 2048 + k * 1024); } while (0)
; #define PG8_LDB(dst, b, h) do { _Pragma("unroll") for (int n = 0; n < 2; ++n) _Pragma("unroll") for (int k = 0; k < 2; ++k) dst[n][k] = *(const PG8_LAS bf16x8*)(lds + PG8_SB(b, h) + boff + n * 2048 + k * 1024); } while (0)
; #define PG8_MMA(ai, bj, At, Bt) do { __builtin_amdgcn_s_setprio(1); _Pragma("unroll") for (int m = 0; m < 4; ++m) _Pragma("unroll") for (int n = 0; n < 2; ++n) _Pragma("unroll") for (int k = 0; k < 2; ++k) \
;         acc[ai][bj][m][n] = __builtin_amdgcn_mfma_f32_16x16x32_bf16(Bt[n][k], At[m][k], acc[ai][bj][m][n], 0, 0, 0); __builtin_amdgcn_s_setprio(0); } while (0)
; #define PG8_WAIT_V(n) asm volatile("s_waitcnt vmcnt(" #n ")" ::: "memory")
; #define PG8_WAIT_L(n) asm volatile("s_waitcnt lgkmcnt(" #n ")" ::: "memory")
; #define PG8_BAR __builtin_amdgcn_s_barrier()
; #define PG8_SCHED __builtin_amdgcn_sched_barrier(0)
; template <class Epi, class Sched, bool ALIGN_EPI = false, bool SP2 = false>
; __device__ __forceinline__ void gemm_phase(PG8_LAS unsigned char* lds, const Gemm g, const Sched& S, const Epi& E) {
;     ...
;             PG8_LDB(B0, 0, 0); PG8_LDB(B1, 0, 1); PG8_SCHED; PG8_LDA(At, 0, 0); PG8_STAGE(PG8_SA(1, 1), a1 + hstep, voffA);
;             PG8_WAIT_V(8); PG8_WAIT_L(0); PG8_BAR; PG8_MMA(0, 0, At, B0); PG8_MMA(0, 1, At, B1); PG8_BAR; PG8_SCHED;
;             PG8_LDA(At, 0, 1); PG8_STAGE(PG8_SB(0, 0), b2, voffB); PG8_STAGE(PG8_SB(0, 1), b2 + hstep, voffB); PG8_STAGE(PG8_SA(0, 0), a2, voffA);
;             PG8_WAIT_V(8); PG8_WAIT_L(0); PG8_BAR; PG8_MMA(1, 0, At, B0); PG8_MMA(1, 1, At, B1); PG8_BAR; PG8_SCHED;
;             PG8_LDB(B0, 1, 0); PG8_LDB(B1, 1, 1); PG8_SCHED; PG8_LDA(At, 1, 0); PG8_STAGE(PG8_SA(0, 1), a2 + hstep, voffA);
;             PG8_WAIT_V(8); PG8_WAIT_L(0); PG8_BAR; PG8_MMA(0, 0, At, B0); PG8_MMA(0, 1, At, B1); PG8_BAR; PG8_SCHED;
	s_setprio 1
	s_waitcnt lgkmcnt(0)
	v_mfma_f32_16x16x32_bf16 v[124:127], v[144:147], v[184:187], v[124:127]
	v_mfma_f32_16x16x32_bf16 v[120:123], v[160:163], v[184:187], v[120:123]
	v_mfma_f32_16x16x32_bf16 v[108:111], v[144:147], v[192:195], v[108:111]
	v_mfma_f32_16x16x32_bf16 v[104:107], v[160:163], v[192:195], v[104:107]
	v_mfma_f32_16x16x32_bf16 v[92:95], v[144:147], v[200:203], v[92:95]
	v_mfma_f32_16x16x32_bf16 v[88:91], v[160:163], v[200:203], v[88:91]
	v_mfma_f32_16x16x32_bf16 v[76:79], v[144:147], v[210:213], v[76:79]
	v_mfma_f32_16x16x32_bf16 v[72:75], v[160:163], v[210:213], v[72:75]
	v_mfma_f32_16x16x32_bf16 v[124:127], v[148:151], v[188:191], v[124:127]
	v_mfma_f32_16x16x32_bf16 v[120:123], v[164:167], v[188:191], v[120:123]
	v_mfma_f32_16x16x32_bf16 v[108:111], v[148:151], v[196:199], v[108:111]
	v_mfma_f32_16x16x32_bf16 v[104:107], v[164:167], v[196:199], v[104:107]
	v_mfma_f32_16x16x32_bf16 v[92:95], v[148:151], v[206:209], v[92:95]
	v_mfma_f32_16x16x32_bf16 v[88:91], v[164:167], v[206:209], v[88:91]
	v_mfma_f32_16x16x32_bf16 v[76:79], v[148:151], v[214:217], v[76:79]
	v_mfma_f32_16x16x32_bf16 v[72:75], v[164:167], v[214:217], v[72:75]
	s_setprio 0
	s_setprio 1
	v_mfma_f32_16x16x32_bf16 v[116:119], v[168:171], v[184:187], v[116:119]
	v_mfma_f32_16x16x32_bf16 v[112:115], v[176:179], v[184:187], v[112:115]
	v_mfma_f32_16x16x32_bf16 v[100:103], v[168:171], v[192:195], v[100:103]
	v_mfma_f32_16x16x32_bf16 v[96:99], v[176:179], v[192:195], v[96:99]
	v_mfma_f32_16x16x32_bf16 v[84:87], v[168:171], v[200:203], v[84:87]
	v_mfma_f32_16x16x32_bf16 v[80:83], v[176:179], v[200:203], v[80:83]
	v_mfma_f32_16x16x32_bf16 v[68:71], v[168:171], v[210:213], v[68:71]
	v_mfma_f32_16x16x32_bf16 v[64:67], v[176:179], v[210:213], v[64:67]
	v_mfma_f32_16x16x32_bf16 v[116:119], v[172:175], v[188:191], v[116:119]
	v_mfma_f32_16x16x32_bf16 v[112:115], v[180:183], v[188:191], v[112:115]
	v_mfma_f32_16x16x32_bf16 v[100:103], v[172:175], v[196:199], v[100:103]
	v_mfma_f32_16x16x32_bf16 v[96:99], v[180:183], v[196:199], v[96:99]
	v_mfma_f32_16x16x32_bf16 v[84:87], v[172:175], v[206:209], v[84:87]
	v_mfma_f32_16x16x32_bf16 v[80:83], v[180:183], v[206:209], v[80:83]
	v_mfma_f32_16x16x32_bf16 v[68:71], v[172:175], v[214:217], v[68:71]
	v_mfma_f32_16x16x32_bf16 v[64:67], v[180:183], v[214:217], v[64:67]
	s_setprio 0
	s_barrier
	s_add_i32 s58, s49, s15
	v_lshl_add_u64 v[218:219], s[40:41], 0, v[132:133]
	s_mov_b32 m0, s58
	ds_read_b128 v[184:187], v157 offset:16384
	ds_read_b128 v[188:191], v157 offset:17408
	ds_read_b128 v[192:195], v157 offset:18432
	ds_read_b128 v[196:199], v157 offset:19456
	ds_read_b128 v[200:203], v157 offset:20480
	ds_read_b128 v[206:209], v157 offset:21504
	ds_read_b128 v[210:213], v157 offset:22528
	ds_read_b128 v[214:217], v157 offset:23552
	global_load_lds_dwordx4 v[218:219], off
	s_add_i32 m0, s58, 0x2000
	s_add_u32 s58, s40, 0x40000
	v_lshl_add_u64 v[220:221], s[40:41], 0, v[128:129]
	s_addc_u32 s59, s41, 0
	s_add_i32 s60, s50, s15
	global_load_lds_dwordx4 v[220:221], off
	v_lshl_add_u64 v[222:223], s[58:59], 0, v[132:133]
	s_mov_b32 m0, s60
	global_load_lds_dwordx4 v[222:223], off
	v_lshl_add_u64 v[222:223], s[58:59], 0, v[128:129]
	s_add_i32 m0, s60, 0x2000
	s_nop 0
	global_load_lds_dwordx4 v[222:223], off
	s_waitcnt vmcnt(6)
	s_waitcnt lgkmcnt(0)
	s_barrier
	s_setprio 1
	s_waitcnt lgkmcnt(0)
	v_mfma_f32_16x16x32_bf16 v[60:63], v[144:147], v[184:187], v[60:63]
	v_mfma_f32_16x16x32_bf16 v[56:59], v[160:163], v[184:187], v[56:59]
	v_mfma_f32_16x16x32_bf16 v[44:47], v[144:147], v[192:195], v[44:47]
	v_mfma_f32_16x16x32_bf16 v[40:43], v[160:163], v[192:195], v[40:43]
	v_mfma_f32_16x16x32_bf16 v[28:31], v[144:147], v[200:203], v[28:31]
	v_mfma_f32_16x16x32_bf16 v[24:27], v[160:163], v[200:203], v[24:27]
	v_mfma_f32_16x16x32_bf16 v[12:15], v[144:147], v[210:213], v[12:15]
	v_mfma_f32_16x16x32_bf16 v[8:11], v[160:163], v[210:213], v[8:11]
	v_mfma_f32_16x16x32_bf16 v[60:63], v[148:151], v[188:191], v[60:63]
	v_mfma_f32_16x16x32_bf16 v[56:59], v[164:167], v[188:191], v[56:59]
	v_mfma_f32_16x16x32_bf16 v[44:47], v[148:151], v[196:199], v[44:47]
	v_mfma_f32_16x16x32_bf16 v[40:43], v[164:167], v[196:199], v[40:43]
	v_mfma_f32_16x16x32_bf16 v[28:31], v[148:151], v[206:209], v[28:31]
	v_mfma_f32_16x16x32_bf16 v[24:27], v[164:167], v[206:209], v[24:27]
	v_lshl_add_u64 v[222:223], s[42:43], 0, v[134:135]
	s_mov_b32 m0, s34
	s_nop 0
	global_load_lds_dwordx4 v[222:223], off
	v_mfma_f32_16x16x32_bf16 v[12:15], v[148:151], v[214:217], v[12:15]
	v_mfma_f32_16x16x32_bf16 v[8:11], v[164:167], v[214:217], v[8:11]
	s_setprio 0
	s_setprio 1
	v_mfma_f32_16x16x32_bf16 v[52:55], v[168:171], v[184:187], v[52:55]
	v_mfma_f32_16x16x32_bf16 v[48:51], v[176:179], v[184:187], v[48:51]
	v_mfma_f32_16x16x32_bf16 v[36:39], v[168:171], v[192:195], v[36:39]
	v_mfma_f32_16x16x32_bf16 v[32:35], v[176:179], v[192:195], v[32:35]
	v_mfma_f32_16x16x32_bf16 v[20:23], v[168:171], v[200:203], v[20:23]
	v_mfma_f32_16x16x32_bf16 v[16:19], v[176:179], v[200:203], v[16:19]
	v_mfma_f32_16x16x32_bf16 v[4:7], v[168:171], v[210:213], v[4:7]
	v_mfma_f32_16x16x32_bf16 v[0:3], v[176:179], v[210:213], v[0:3]
	v_mfma_f32_16x16x32_bf16 v[52:55], v[172:175], v[188:191], v[52:55]
	v_mfma_f32_16x16x32_bf16 v[48:51], v[180:183], v[188:191], v[48:51]
	v_mfma_f32_16x16x32_bf16 v[36:39], v[172:175], v[196:199], v[36:39]
	v_mfma_f32_16x16x32_bf16 v[32:35], v[180:183], v[196:199], v[32:35]
	v_mfma_f32_16x16x32_bf16 v[20:23], v[172:175], v[206:209], v[20:23]
	v_mfma_f32_16x16x32_bf16 v[16:19], v[180:183], v[206:209], v[16:19]
	v_lshl_add_u64 v[224:225], s[42:43], 0, v[130:131]
	s_mov_b32 m0, s37
	s_nop 0
	global_load_lds_dwordx4 v[224:225], off
	v_mfma_f32_16x16x32_bf16 v[4:7], v[172:175], v[214:217], v[4:7]
	v_mfma_f32_16x16x32_bf16 v[0:3], v[180:183], v[214:217], v[0:3]
	s_setprio 0
	s_barrier
; #define PG8_STAGE(bufoff, gbase, voff) do { _Pragma("unroll") for (int _i = 0; _i < 2; ++_i) \
;         __builtin_amdgcn_global_load_lds((const unsigned*)((const char*)(gbase) + (voff)[_i]), (PG8_LAS unsigned*)(lds + (bufoff) + ldsw + _i * 8192), 16, 0, 0); } while (0)
; #define PG8_LDA(dst, b, h) do { _Pragma("unroll") for (int m = 0; m < 4; ++m) _Pragma("unroll") for (int k = 0; k < 2; ++k) dst[m][k] = *(const PG8_LAS bf16x8*)(lds + PG8_SA(b, h) + aoff + m * 2048 + k * 1024); } while (0)
; #define PG8_LDB(dst, b, h) do { _Pragma("unroll") for (int n = 0; n < 2; ++n) _Pragma("unroll") for (int k = 0; k < 2; ++k) dst[n][k] = *(const PG8_LAS bf16x8*)(lds + PG8_SB(b, h) + boff + n * 2048 + k * 1024); } while (0)
; #define PG8_MMA(ai, bj, At, Bt) do { __builtin_amdgcn_s_setprio(1); _Pragma("unroll") for (int m = 0; m < 4; ++m) _Pragma("unroll") for (int n = 0; n < 2; ++n) _Pragma("unroll") for (int k = 0; k < 2; ++k) \
;         acc[ai][bj][m][n] = __builtin_amdgcn_mfma_f32_16x16x32_bf16(Bt[n][k], At[m][k], acc[ai][bj][m][n], 0, 0, 0); __builtin_amdgcn_s_setprio(0); } while (0)
; #define PG8_WAIT_V(n) asm volatile("s_waitcnt vmcnt(" #n ")" ::: "memory")
; #define PG8_WAIT_L(n) asm volatile("s_waitcnt lgkmcnt(" #n ")" ::: "memory")
; #define PG8_BAR __builtin_amdgcn_s_barrier()
; #define PG8_SCHED __builtin_amdgcn_sched_barrier(0)
; template <class Epi, class Sched, bool ALIGN_EPI = false, bool SP2 = false>
; __device__ __forceinline__ void gemm_phase(PG8_LAS unsigned char* lds, const Gemm g, const Sched& S, const Epi& E) {
;     ...
;             PG8_LDB(B0, 1, 0); PG8_LDB(B1, 1, 1); PG8_SCHED; PG8_LDA(At, 1, 0); PG8_STAGE(PG8_SA(0, 1), a2 + hstep, voffA);
;             PG8_WAIT_V(8); PG8_WAIT_L(0); PG8_BAR; PG8_MMA(0, 0, At, B0); PG8_MMA(0, 1, At, B1); PG8_BAR; PG8_SCHED;
;             PG8_LDA(At, 1, 1); PG8_STAGE(PG8_SB(1, 0), b3, voffB); PG8_STAGE(PG8_SB(1, 1), b3 + hstep, voffB); PG8_STAGE(PG8_SA(1, 0), a3, voffA);
;             PG8_WAIT_V(8); PG8_WAIT_L(0); PG8_BAR; PG8_MMA(1, 0, At, B0); PG8_MMA(1, 1, At, B1); PG8_BAR; PG8_SCHED;
	s_add_i32 s58, 0, 0x18000
	v_add_u32_e32 v159, s58, v153
	s_add_i32 s59, 0, 0x1c000
	ds_read_b128 v[144:147], v159
	ds_read_b128 v[148:151], v159 offset:1024
	ds_read_b128 v[160:163], v159 offset:2048
	ds_read_b128 v[164:167], v159 offset:3072
	v_add_u32_e32 v159, s59, v153
	ds_read_b128 v[168:171], v159
	ds_read_b128 v[172:175], v159 offset:1024
	ds_read_b128 v[176:179], v159 offset:2048
	ds_read_b128 v[180:183], v159 offset:3072
	s_add_u32 s42, s42, 0x40000
	s_addc_u32 s43, s43, 0
	s_mov_b32 m0, s44
	v_lshl_add_u64 v[226:227], s[42:43], 0, v[134:135]
	ds_read_b128 v[184:187], v157 offset:32768
	ds_read_b128 v[188:191], v157 offset:33792
	ds_read_b128 v[192:195], v157 offset:34816
	ds_read_b128 v[196:199], v157 offset:35840
	ds_read_b128 v[200:203], v157 offset:36864
	ds_read_b128 v[206:209], v157 offset:37888
	ds_read_b128 v[210:213], v157 offset:38912
	ds_read_b128 v[214:217], v157 offset:39936
	global_load_lds_dwordx4 v[226:227], off
	v_lshl_add_u64 v[226:227], s[42:43], 0, v[130:131]
	s_mov_b32 m0, s45
	s_nop 0
	global_load_lds_dwordx4 v[226:227], off
	s_waitcnt vmcnt(8)
	s_waitcnt lgkmcnt(0)
	s_barrier
	s_setprio 1
	s_waitcnt lgkmcnt(0)
	v_mfma_f32_16x16x32_bf16 v[124:127], v[144:147], v[184:187], v[124:127]
	v_mfma_f32_16x16x32_bf16 v[120:123], v[160:163], v[184:187], v[120:123]
	v_mfma_f32_16x16x32_bf16 v[108:111], v[144:147], v[192:195], v[108:111]
	v_mfma_f32_16x16x32_bf16 v[104:107], v[160:163], v[192:195], v[104:107]
	v_mfma_f32_16x16x32_bf16 v[92:95], v[144:147], v[200:203], v[92:95]
	v_mfma_f32_16x16x32_bf16 v[88:91], v[160:163], v[200:203], v[88:91]
	v_mfma_f32_16x16x32_bf16 v[76:79], v[144:147], v[210:213], v[76:79]
	v_mfma_f32_16x16x32_bf16 v[72:75], v[160:163], v[210:213], v[72:75]
	v_mfma_f32_16x16x32_bf16 v[124:127], v[148:151], v[188:191], v[124:127]
	v_mfma_f32_16x16x32_bf16 v[120:123], v[164:167], v[188:191], v[120:123]
	v_mfma_f32_16x16x32_bf16 v[108:111], v[148:151], v[196:199], v[108:111]
	v_mfma_f32_16x16x32_bf16 v[104:107], v[164:167], v[196:199], v[104:107]
	v_mfma_f32_16x16x32_bf16 v[92:95], v[148:151], v[206:209], v[92:95]
	v_mfma_f32_16x16x32_bf16 v[88:91], v[164:167], v[206:209], v[88:91]
	v_mfma_f32_16x16x32_bf16 v[76:79], v[148:151], v[214:217], v[76:79]
	v_mfma_f32_16x16x32_bf16 v[72:75], v[164:167], v[214:217], v[72:75]
	s_setprio 0
	s_setprio 1
	v_mfma_f32_16x16x32_bf16 v[116:119], v[168:171], v[184:187], v[116:119]
	v_mfma_f32_16x16x32_bf16 v[112:115], v[176:179], v[184:187], v[112:115]
	v_mfma_f32_16x16x32_bf16 v[100:103], v[168:171], v[192:195], v[100:103]
	v_mfma_f32_16x16x32_bf16 v[96:99], v[176:179], v[192:195], v[96:99]
	v_mfma_f32_16x16x32_bf16 v[84:87], v[168:171], v[200:203], v[84:87]
	v_mfma_f32_16x16x32_bf16 v[80:83], v[176:179], v[200:203], v[80:83]
	v_mfma_f32_16x16x32_bf16 v[68:71], v[168:171], v[210:213], v[68:71]
	v_mfma_f32_16x16x32_bf16 v[64:67], v[176:179], v[210:213], v[64:67]
	v_mfma_f32_16x16x32_bf16 v[116:119], v[172:175], v[188:191], v[116:119]
	v_mfma_f32_16x16x32_bf16 v[112:115], v[180:183], v[188:191], v[112:115]
	v_mfma_f32_16x16x32_bf16 v[100:103], v[172:175], v[196:199], v[100:103]
	v_mfma_f32_16x16x32_bf16 v[96:99], v[180:183], v[196:199], v[96:99]
	v_mfma_f32_16x16x32_bf16 v[84:87], v[172:175], v[206:209], v[84:87]
	v_mfma_f32_16x16x32_bf16 v[80:83], v[180:183], v[206:209], v[80:83]
	v_mfma_f32_16x16x32_bf16 v[68:71], v[172:175], v[214:217], v[68:71]
	v_mfma_f32_16x16x32_bf16 v[64:67], v[180:183], v[214:217], v[64:67]
	s_setprio 0
	s_barrier
	s_add_i32 s42, s58, s15
	v_lshl_add_u64 v[218:219], v[218:219], 0, s[8:9]
	s_mov_b32 m0, s42
	ds_read_b128 v[184:187], v157 offset:49152
	ds_read_b128 v[188:191], v157 offset:50176
	ds_read_b128 v[192:195], v157 offset:51200
	ds_read_b128 v[196:199], v157 offset:52224
	ds_read_b128 v[200:203], v157 offset:53248
	ds_read_b128 v[206:209], v157 offset:54272
	ds_read_b128 v[210:213], v157 offset:55296
	ds_read_b128 v[214:217], v157 offset:56320
	global_load_lds_dwordx4 v[218:219], off
	s_add_i32 m0, s42, 0x2000
	s_add_u32 s40, s40, 0x40080
	v_lshl_add_u64 v[218:219], v[220:221], 0, s[8:9]
	s_addc_u32 s41, s41, 0
	s_add_i32 s42, s59, s15
	global_load_lds_dwordx4 v[218:219], off
	v_lshl_add_u64 v[218:219], s[40:41], 0, v[132:133]
	s_mov_b32 m0, s42
	s_nop 0
	global_load_lds_dwordx4 v[218:219], off
	v_lshl_add_u64 v[218:219], s[40:41], 0, v[128:129]
	s_add_i32 m0, s42, 0x2000
	s_nop 0
	global_load_lds_dwordx4 v[218:219], off
	s_waitcnt vmcnt(6)
	s_waitcnt lgkmcnt(0)
	s_barrier
; __device__ __forceinline__ unsigned cvtpk(float lo, float hi) { f32x2v_ v = {lo, hi}; bf16x2v_ b = __builtin_convertvector(v, bf16x2v_); return __builtin_bit_cast(unsigned, b); }
; #define PG8_STAGE(bufoff, gbase, voff) do { _Pragma("unroll") for (int _i = 0; _i < 2; ++_i) \
;         __builtin_amdgcn_global_load_lds((const unsigned*)((const char*)(gbase) + (voff)[_i]), (PG8_LAS unsigned*)(lds + (bufoff) + ldsw + _i * 8192), 16, 0, 0); } while (0)
; #define PG8_LDA(dst, b, h) do { _Pragma("unroll") for (int m = 0; m < 4; ++m) _Pragma("unroll") for (int k = 0; k < 2; ++k) dst[m][k] = *(const PG8_LAS bf16x8*)(lds + PG8_SA(b, h) + aoff + m * 2048 + k * 1024); } while (0)
; #define PG8_WAIT_V(n) asm volatile("s_waitcnt vmcnt(" #n ")" ::: "memory")
; #define PG8_WAIT_L(n) asm volatile("s_waitcnt lgkmcnt(" #n ")" ::: "memory")
; #define PG8_BAR __builtin_amdgcn_s_barrier()
; #define PG8_SCHED __builtin_amdgcn_sched_barrier(0)
;     __device__ __forceinline__ void operator()(const f32x4 (&acc)[2][2][4][2], const Unit& u, int wr, int wc, int fr, int fq) const {
;         const int row0 = u.pm * BM + wr * 64 + fr, col0 = u.pn * HALF + wc * 32 + 8 * fq;
; #pragma unroll
;         for (int ai = 0; ai < 2; ++ai)
; #pragma unroll
;             for (int m = 0; m < 4; ++m) { const int row = row0 + ai * HALF + m * 16; const float rs = row_rs(ss, row);
;                 float hv[8];
; #pragma unroll
;                 for (int n = 0; n < 2; ++n)
; #pragma unroll
;                     for (int i = 0; i < 4; ++i) { const float g = acc[ai][0][m][n][i] * rs, uu = acc[ai][1][m][n][i] * rs;
;                         hv[n * 4 + i] = g * __builtin_amdgcn_rcpf(1.0f + __expf(-g)) * uu; }
;                 u32x4 w; w.x = cvtpk(hv[0], hv[1]); w.y = cvtpk(hv[2], hv[3]); w.z = cvtpk(hv[4], hv[5]); w.w = cvtpk(hv[6], hv[7]);
;                 *(u32x4*)(H + (size_t)row * ldh + col0) = w; }
; template <class Epi, class Sched, bool ALIGN_EPI = false, bool SP2 = false>
; __device__ __forceinline__ void gemm_phase(PG8_LAS unsigned char* lds, const Gemm g, const Sched& S, const Epi& E) {
;     ...
;             PG8_LDA(At, 1, 1); PG8_STAGE(PG8_SB(1, 0), b3, voffB); PG8_STAGE(PG8_SB(1, 1), b3 + hstep, voffB); PG8_STAGE(PG8_SA(1, 0), a3, voffA);
;             PG8_WAIT_V(8); PG8_WAIT_L(0); PG8_BAR; PG8_MMA(1, 0, At, B0); PG8_MMA(1, 1, At, B1); PG8_BAR; PG8_SCHED;
	s_setprio 1
	s_waitcnt lgkmcnt(0)
	v_mfma_f32_16x16x32_bf16 v[60:63], v[144:147], v[184:187], v[60:63]
	v_mfma_f32_16x16x32_bf16 v[56:59], v[160:163], v[184:187], v[56:59]
	v_mfma_f32_16x16x32_bf16 v[44:47], v[144:147], v[192:195], v[44:47]
	v_mfma_f32_16x16x32_bf16 v[40:43], v[160:163], v[192:195], v[40:43]
	v_mfma_f32_16x16x32_bf16 v[28:31], v[144:147], v[200:203], v[28:31]
	v_mfma_f32_16x16x32_bf16 v[24:27], v[160:163], v[200:203], v[24:27]
	v_mfma_f32_16x16x32_bf16 v[12:15], v[144:147], v[210:213], v[12:15]
	v_mfma_f32_16x16x32_bf16 v[8:11], v[160:163], v[210:213], v[8:11]
	v_mfma_f32_16x16x32_bf16 v[60:63], v[148:151], v[188:191], v[60:63]
	v_mfma_f32_16x16x32_bf16 v[56:59], v[164:167], v[188:191], v[56:59]
	v_mfma_f32_16x16x32_bf16 v[44:47], v[148:151], v[196:199], v[44:47]
	v_mfma_f32_16x16x32_bf16 v[40:43], v[164:167], v[196:199], v[40:43]
	v_mfma_f32_16x16x32_bf16 v[28:31], v[148:151], v[206:209], v[28:31]
	v_mfma_f32_16x16x32_bf16 v[24:27], v[164:167], v[206:209], v[24:27]
	v_lshl_add_u64 v[218:219], v[222:223], 0, s[8:9]
	s_mov_b32 m0, s47
	s_nop 0
	global_load_lds_dwordx4 v[218:219], off
	v_mfma_f32_16x16x32_bf16 v[12:15], v[148:151], v[214:217], v[12:15]
	v_mfma_f32_16x16x32_bf16 v[8:11], v[164:167], v[214:217], v[8:11]
	s_setprio 0
	s_setprio 1
	v_mfma_f32_16x16x32_bf16 v[52:55], v[168:171], v[184:187], v[52:55]
	v_mfma_f32_16x16x32_bf16 v[48:51], v[176:179], v[184:187], v[48:51]
	v_mfma_f32_16x16x32_bf16 v[36:39], v[168:171], v[192:195], v[36:39]
	v_mfma_f32_16x16x32_bf16 v[32:35], v[176:179], v[192:195], v[32:35]
	v_mfma_f32_16x16x32_bf16 v[20:23], v[168:171], v[200:203], v[20:23]
	v_mfma_f32_16x16x32_bf16 v[16:19], v[176:179], v[200:203], v[16:19]
	v_mfma_f32_16x16x32_bf16 v[4:7], v[168:171], v[210:213], v[4:7]
	v_mfma_f32_16x16x32_bf16 v[0:3], v[176:179], v[210:213], v[0:3]
	v_mfma_f32_16x16x32_bf16 v[52:55], v[172:175], v[188:191], v[52:55]
	v_mfma_f32_16x16x32_bf16 v[48:51], v[180:183], v[188:191], v[48:51]
	v_mfma_f32_16x16x32_bf16 v[36:39], v[172:175], v[196:199], v[36:39]
	v_mfma_f32_16x16x32_bf16 v[32:35], v[180:183], v[196:199], v[32:35]
	v_mfma_f32_16x16x32_bf16 v[20:23], v[172:175], v[206:209], v[20:23]
	v_mfma_f32_16x16x32_bf16 v[16:19], v[180:183], v[206:209], v[16:19]
	v_lshl_add_u64 v[218:219], v[224:225], 0, s[8:9]
	s_mov_b32 m0, s48
	s_nop 0
	global_load_lds_dwordx4 v[218:219], off
	v_mfma_f32_16x16x32_bf16 v[4:7], v[172:175], v[214:217], v[4:7]
	v_mfma_f32_16x16x32_bf16 v[0:3], v[180:183], v[214:217], v[0:3]
	s_setprio 0
	s_barrier
	s_add_i32 s57, s57, 2
	s_add_u32 s38, s38, 0x100
	s_addc_u32 s39, s39, 0
	s_add_u32 s55, s55, 0x100
	s_addc_u32 s56, s56, 0
	s_cmp_gt_u32 s57, 13
	s_cbranch_scc0 .LBB0_1900
	v_lshl_add_u32 v144, s36, 8, v152
	v_ashrrev_i32_e32 v145, 31, v144
	s_and_b64 vcc, exec, s[10:11]
	s_cbranch_vccz .LBB0_1903
	s_barrier
.LBB0_1903:
	v_lshl_or_b32 v160, s52, 7, v154
	v_ashrrev_i32_e32 v161, 31, v160
	v_or_b32_e32 v164, 16, v144
	v_ashrrev_i32_e32 v165, 31, v164
	v_lshl_add_u64 v[166:167], v[164:165], 3, s[0:1]
	v_mov_b64_e32 v[146:147], s[20:21]
	v_mad_i64_i32 v[162:163], s[38:39], v144, s51, v[146:147]
	s_andn2_b64 vcc, exec, s[4:5]
	s_mov_b64 s[4:5], -1
	s_waitcnt vmcnt(20)
	v_cvt_f32_u32_e32 v159, v235
	v_cvt_f32_u32_e32 v145, v234
	v_lshlrev_b64 v[148:149], 1, v[160:161]
	v_lshl_add_u64 v[162:163], v[162:163], 0, v[148:149]
	v_fmamk_f32 v145, v145, 0x2f800000, v159
	v_fmamk_f32 v145, v145, 0x3a800000, v158
	v_rsq_f32_e32 v160, v145
	s_nop 0
	v_mul_f32_e32 v234, 0xbfb8aa3b, v160
	v_mul_f32_e32 v235, v160, v160
	v_pk_mul_f32 v[160:161], v[124:125], v[234:235] op_sel_hi:[1,0]
	v_pk_mul_f32 v[168:169], v[126:127], v[234:235] op_sel_hi:[1,0]
	v_pk_mul_f32 v[170:171], v[120:121], v[234:235] op_sel_hi:[1,0]
	v_pk_mul_f32 v[172:173], v[122:123], v[234:235] op_sel_hi:[1,0]
	v_pk_mul_f32 v[116:117], v[116:117], v[124:125]
	v_pk_mul_f32 v[118:119], v[118:119], v[126:127]
	v_pk_mul_f32 v[120:121], v[112:113], v[120:121]
	v_pk_mul_f32 v[122:123], v[114:115], v[122:123]
	v_exp_f32_e32 v160, v160
	v_exp_f32_e32 v161, v161
	v_exp_f32_e32 v168, v168
	v_exp_f32_e32 v169, v169
	v_exp_f32_e32 v170, v170
	v_exp_f32_e32 v171, v171
	v_exp_f32_e32 v172, v172
	v_exp_f32_e32 v173, v173
	v_pk_mul_f32 v[116:117], v[116:117], v[234:235] op_sel:[0,1] op_sel_hi:[1,1]
	v_pk_mul_f32 v[118:119], v[118:119], v[234:235] op_sel:[0,1] op_sel_hi:[1,1]
	v_pk_mul_f32 v[120:121], v[120:121], v[234:235] op_sel:[0,1] op_sel_hi:[1,1]
	v_pk_mul_f32 v[122:123], v[122:123], v[234:235] op_sel:[0,1] op_sel_hi:[1,1]
	v_pk_add_f32 v[160:161], v[160:161], 1.0 op_sel_hi:[1,0]
	v_pk_add_f32 v[168:169], v[168:169], 1.0 op_sel_hi:[1,0]
	v_pk_add_f32 v[170:171], v[170:171], 1.0 op_sel_hi:[1,0]
	v_pk_add_f32 v[172:173], v[172:173], 1.0 op_sel_hi:[1,0]
	v_rcp_f32_e32 v160, v160
	v_rcp_f32_e32 v161, v161
	v_rcp_f32_e32 v168, v168
	v_rcp_f32_e32 v169, v169
	v_rcp_f32_e32 v170, v170
	v_rcp_f32_e32 v171, v171
	v_rcp_f32_e32 v172, v172
	v_rcp_f32_e32 v173, v173
	v_pk_mul_f32 v[116:117], v[116:117], v[160:161]
	v_pk_mul_f32 v[118:119], v[118:119], v[168:169]
	v_pk_mul_f32 v[120:121], v[120:121], v[170:171]
	v_pk_mul_f32 v[122:123], v[122:123], v[172:173]
	v_cvt_pk_bf16_f32 v112, v116, v117
	v_cvt_pk_bf16_f32 v113, v118, v119
	v_cvt_pk_bf16_f32 v114, v120, v121
	v_cvt_pk_bf16_f32 v115, v122, v123
	global_store_dwordx4 v[162:163], v[112:115], off
	s_nop 0
	s_nop 0
	v_or_b32_e32 v114, 32, v144
	s_waitcnt vmcnt(7)
; __device__ __forceinline__ unsigned cvtpk(float lo, float hi) { f32x2v_ v = {lo, hi}; bf16x2v_ b = __builtin_convertvector(v, bf16x2v_); return __builtin_bit_cast(unsigned, b); }
;     __device__ __forceinline__ void operator()(const f32x4 (&acc)[2][2][4][2], const Unit& u, int wr, int wc, int fr, int fq) const {
;     ...
;             for (int m = 0; m < 4; ++m) { const int row = row0 + ai * HALF + m * 16; const float rs = row_rs(ss, row);
;                 float hv[8];
; #pragma unroll
;                 for (int n = 0; n < 2; ++n)
; #pragma unroll
;                     for (int i = 0; i < 4; ++i) { const float g = acc[ai][0][m][n][i] * rs, uu = acc[ai][1][m][n][i] * rs;
;                         hv[n * 4 + i] = g * __builtin_amdgcn_rcpf(1.0f + __expf(-g)) * uu; }
;                 u32x4 w; w.x = cvtpk(hv[0], hv[1]); w.y = cvtpk(hv[2], hv[3]); w.z = cvtpk(hv[4], hv[5]); w.w = cvtpk(hv[6], hv[7]);
;                 *(u32x4*)(H + (size_t)row * ldh + col0) = w; }
	v_cvt_f32_u32_e32 v116, v237
	v_cvt_f32_u32_e32 v115, v236
	v_mad_i64_i32 v[112:113], s[38:39], v164, s51, v[146:147]
	v_fmamk_f32 v115, v115, 0x2f800000, v116
	v_fmamk_f32 v115, v115, 0x3a800000, v158
	v_rsq_f32_e32 v116, v115
	v_ashrrev_i32_e32 v115, 31, v114
	v_lshl_add_u64 v[118:119], v[114:115], 3, s[0:1]
	v_lshl_add_u64 v[112:113], v[112:113], 0, v[148:149]
	v_mul_f32_e32 v236, 0xbfb8aa3b, v116
	v_mul_f32_e32 v237, v116, v116
	v_pk_mul_f32 v[116:117], v[108:109], v[236:237] op_sel_hi:[1,0]
	v_pk_mul_f32 v[120:121], v[110:111], v[236:237] op_sel_hi:[1,0]
	v_pk_mul_f32 v[122:123], v[104:105], v[236:237] op_sel_hi:[1,0]
	v_pk_mul_f32 v[124:125], v[106:107], v[236:237] op_sel_hi:[1,0]
	v_pk_mul_f32 v[100:101], v[100:101], v[108:109]
	v_pk_mul_f32 v[102:103], v[102:103], v[110:111]
	v_pk_mul_f32 v[104:105], v[96:97], v[104:105]
	v_pk_mul_f32 v[106:107], v[98:99], v[106:107]
	v_exp_f32_e32 v116, v116
	v_exp_f32_e32 v117, v117
	v_exp_f32_e32 v120, v120
	v_exp_f32_e32 v121, v121
	v_exp_f32_e32 v122, v122
	v_exp_f32_e32 v123, v123
	v_exp_f32_e32 v124, v124
	v_exp_f32_e32 v125, v125
	v_pk_mul_f32 v[100:101], v[100:101], v[236:237] op_sel:[0,1] op_sel_hi:[1,1]
	v_pk_mul_f32 v[102:103], v[102:103], v[236:237] op_sel:[0,1] op_sel_hi:[1,1]
	v_pk_mul_f32 v[104:105], v[104:105], v[236:237] op_sel:[0,1] op_sel_hi:[1,1]
	v_pk_mul_f32 v[106:107], v[106:107], v[236:237] op_sel:[0,1] op_sel_hi:[1,1]
	v_pk_add_f32 v[116:117], v[116:117], 1.0 op_sel_hi:[1,0]
	v_pk_add_f32 v[120:121], v[120:121], 1.0 op_sel_hi:[1,0]
	v_pk_add_f32 v[122:123], v[122:123], 1.0 op_sel_hi:[1,0]
	v_pk_add_f32 v[124:125], v[124:125], 1.0 op_sel_hi:[1,0]
	v_rcp_f32_e32 v116, v116
	v_rcp_f32_e32 v117, v117
	v_rcp_f32_e32 v120, v120
	v_rcp_f32_e32 v121, v121
	v_rcp_f32_e32 v122, v122
	v_rcp_f32_e32 v123, v123
	v_rcp_f32_e32 v124, v124
	v_rcp_f32_e32 v125, v125
	v_pk_mul_f32 v[100:101], v[100:101], v[116:117]
	v_pk_mul_f32 v[102:103], v[102:103], v[120:121]
	v_pk_mul_f32 v[104:105], v[104:105], v[122:123]
	v_pk_mul_f32 v[106:107], v[106:107], v[124:125]
	v_cvt_pk_bf16_f32 v96, v100, v101
	v_cvt_pk_bf16_f32 v97, v102, v103
	v_cvt_pk_bf16_f32 v98, v104, v105
	v_cvt_pk_bf16_f32 v99, v106, v107
	global_store_dwordx4 v[112:113], v[96:99], off
	s_nop 0
	s_nop 0
	v_or_b32_e32 v98, 48, v144
	s_waitcnt vmcnt(7)
	v_cvt_f32_u32_e32 v100, v239
	v_cvt_f32_u32_e32 v99, v238
	v_mad_i64_i32 v[96:97], s[38:39], v114, s51, v[146:147]
	v_fmamk_f32 v99, v99, 0x2f800000, v100
	v_fmamk_f32 v99, v99, 0x3a800000, v158
	v_rsq_f32_e32 v100, v99
	v_ashrrev_i32_e32 v99, 31, v98
	v_lshl_add_u64 v[102:103], v[98:99], 3, s[0:1]
	v_lshl_add_u64 v[96:97], v[96:97], 0, v[148:149]
	v_mul_f32_e32 v238, 0xbfb8aa3b, v100
	v_mul_f32_e32 v239, v100, v100
	v_pk_mul_f32 v[100:101], v[92:93], v[238:239] op_sel_hi:[1,0]
	v_pk_mul_f32 v[104:105], v[94:95], v[238:239] op_sel_hi:[1,0]
	v_pk_mul_f32 v[106:107], v[88:89], v[238:239] op_sel_hi:[1,0]
	v_pk_mul_f32 v[108:109], v[90:91], v[238:239] op_sel_hi:[1,0]
	v_pk_mul_f32 v[84:85], v[84:85], v[92:93]
	v_pk_mul_f32 v[86:87], v[86:87], v[94:95]
	v_pk_mul_f32 v[88:89], v[80:81], v[88:89]
	v_pk_mul_f32 v[90:91], v[82:83], v[90:91]
	v_exp_f32_e32 v100, v100
	v_exp_f32_e32 v101, v101
	v_exp_f32_e32 v104, v104
	v_exp_f32_e32 v105, v105
	v_exp_f32_e32 v106, v106
	v_exp_f32_e32 v107, v107
	v_exp_f32_e32 v108, v108
	v_exp_f32_e32 v109, v109
	v_pk_mul_f32 v[84:85], v[84:85], v[238:239] op_sel:[0,1] op_sel_hi:[1,1]
	v_pk_mul_f32 v[86:87], v[86:87], v[238:239] op_sel:[0,1] op_sel_hi:[1,1]
	v_pk_mul_f32 v[88:89], v[88:89], v[238:239] op_sel:[0,1] op_sel_hi:[1,1]
	v_pk_mul_f32 v[90:91], v[90:91], v[238:239] op_sel:[0,1] op_sel_hi:[1,1]
	v_pk_add_f32 v[100:101], v[100:101], 1.0 op_sel_hi:[1,0]
	v_pk_add_f32 v[104:105], v[104:105], 1.0 op_sel_hi:[1,0]
	v_pk_add_f32 v[106:107], v[106:107], 1.0 op_sel_hi:[1,0]
	v_pk_add_f32 v[108:109], v[108:109], 1.0 op_sel_hi:[1,0]
	v_rcp_f32_e32 v100, v100
	v_rcp_f32_e32 v101, v101
	v_rcp_f32_e32 v104, v104
	v_rcp_f32_e32 v105, v105
	v_rcp_f32_e32 v106, v106
	v_rcp_f32_e32 v107, v107
	v_rcp_f32_e32 v108, v108
	v_rcp_f32_e32 v109, v109
	v_pk_mul_f32 v[84:85], v[84:85], v[100:101]
	v_pk_mul_f32 v[86:87], v[86:87], v[104:105]
	v_pk_mul_f32 v[88:89], v[88:89], v[106:107]
	v_pk_mul_f32 v[90:91], v[90:91], v[108:109]
	v_cvt_pk_bf16_f32 v80, v84, v85
	v_cvt_pk_bf16_f32 v81, v86, v87
	v_cvt_pk_bf16_f32 v82, v88, v89
	v_cvt_pk_bf16_f32 v83, v90, v91
	global_store_dwordx4 v[96:97], v[80:83], off
	s_nop 0
	s_waitcnt vmcnt(7)
	v_cvt_f32_u32_e32 v80, v241
	v_cvt_f32_u32_e32 v81, v240
	v_mad_i64_i32 v[82:83], s[38:39], v98, s51, v[146:147]
	v_fmamk_f32 v80, v81, 0x2f800000, v80
	v_fmamk_f32 v80, v80, 0x3a800000, v158
	v_rsq_f32_e32 v80, v80
	v_lshl_add_u64 v[82:83], v[82:83], 0, v[148:149]
	v_mul_f32_e32 v240, 0xbfb8aa3b, v80
	v_mul_f32_e32 v241, v80, v80
	v_pk_mul_f32 v[80:81], v[76:77], v[240:241] op_sel_hi:[1,0]
	v_pk_mul_f32 v[84:85], v[78:79], v[240:241] op_sel_hi:[1,0]
	v_pk_mul_f32 v[86:87], v[72:73], v[240:241] op_sel_hi:[1,0]
	v_pk_mul_f32 v[88:89], v[74:75], v[240:241] op_sel_hi:[1,0]
	v_pk_mul_f32 v[68:69], v[68:69], v[76:77]
	v_pk_mul_f32 v[70:71], v[70:71], v[78:79]
	v_pk_mul_f32 v[72:73], v[64:65], v[72:73]
	v_pk_mul_f32 v[74:75], v[66:67], v[74:75]
	v_exp_f32_e32 v80, v80
	v_exp_f32_e32 v81, v81
	v_exp_f32_e32 v84, v84
	v_exp_f32_e32 v85, v85
	v_exp_f32_e32 v86, v86
	v_exp_f32_e32 v87, v87
	v_exp_f32_e32 v88, v88
	v_exp_f32_e32 v89, v89
	v_pk_mul_f32 v[68:69], v[68:69], v[240:241] op_sel:[0,1] op_sel_hi:[1,1]
	v_pk_mul_f32 v[70:71], v[70:71], v[240:241] op_sel:[0,1] op_sel_hi:[1,1]
	v_pk_mul_f32 v[72:73], v[72:73], v[240:241] op_sel:[0,1] op_sel_hi:[1,1]
	v_pk_mul_f32 v[74:75], v[74:75], v[240:241] op_sel:[0,1] op_sel_hi:[1,1]
	v_pk_add_f32 v[80:81], v[80:81], 1.0 op_sel_hi:[1,0]
	v_pk_add_f32 v[84:85], v[84:85], 1.0 op_sel_hi:[1,0]
	v_pk_add_f32 v[86:87], v[86:87], 1.0 op_sel_hi:[1,0]
	v_pk_add_f32 v[88:89], v[88:89], 1.0 op_sel_hi:[1,0]
	v_rcp_f32_e32 v80, v80
	v_rcp_f32_e32 v81, v81
	v_rcp_f32_e32 v84, v84
	v_rcp_f32_e32 v85, v85
	v_rcp_f32_e32 v86, v86
	v_rcp_f32_e32 v87, v87
	v_rcp_f32_e32 v88, v88
	v_rcp_f32_e32 v89, v89
	v_pk_mul_f32 v[68:69], v[68:69], v[80:81]
	v_pk_mul_f32 v[70:71], v[70:71], v[84:85]
	v_pk_mul_f32 v[72:73], v[72:73], v[86:87]
	v_pk_mul_f32 v[74:75], v[74:75], v[88:89]
	v_cvt_pk_bf16_f32 v64, v68, v69
	v_cvt_pk_bf16_f32 v65, v70, v71
	v_cvt_pk_bf16_f32 v66, v72, v73
	v_cvt_pk_bf16_f32 v67, v74, v75
	global_store_dwordx4 v[82:83], v[64:67], off
	s_nop 0
	s_waitcnt vmcnt(7)
; __device__ __forceinline__ unsigned cvtpk(float lo, float hi) { f32x2v_ v = {lo, hi}; bf16x2v_ b = __builtin_convertvector(v, bf16x2v_); return __builtin_bit_cast(unsigned, b); }
;     __device__ __forceinline__ void operator()(const f32x4 (&acc)[2][2][4][2], const Unit& u, int wr, int wc, int fr, int fq) const {
;     ...
;             for (int m = 0; m < 4; ++m) { const int row = row0 + ai * HALF + m * 16; const float rs = row_rs(ss, row);
;                 float hv[8];
; #pragma unroll
;                 for (int n = 0; n < 2; ++n)
; #pragma unroll
;                     for (int i = 0; i < 4; ++i) { const float g = acc[ai][0][m][n][i] * rs, uu = acc[ai][1][m][n][i] * rs;
;                         hv[n * 4 + i] = g * __builtin_amdgcn_rcpf(1.0f + __expf(-g)) * uu; }
;                 u32x4 w; w.x = cvtpk(hv[0], hv[1]); w.y = cvtpk(hv[2], hv[3]); w.z = cvtpk(hv[4], hv[5]); w.w = cvtpk(hv[6], hv[7]);
;                 *(u32x4*)(H + (size_t)row * ldh + col0) = w; }
	v_cvt_f32_u32_e32 v64, v243
	v_cvt_f32_u32_e32 v66, v242
	v_add_u32_e32 v65, 0x80, v144
	v_fmamk_f32 v64, v66, 0x2f800000, v64
	v_fmamk_f32 v64, v64, 0x3a800000, v158
	v_rsq_f32_e32 v64, v64
	v_mad_i64_i32 v[66:67], s[38:39], v65, s51, v[146:147]
	v_lshl_add_u64 v[66:67], v[66:67], 0, v[148:149]
	v_mul_f32_e32 v242, 0xbfb8aa3b, v64
	v_mul_f32_e32 v243, v64, v64
	v_pk_mul_f32 v[64:65], v[60:61], v[242:243] op_sel_hi:[1,0]
	v_pk_mul_f32 v[68:69], v[62:63], v[242:243] op_sel_hi:[1,0]
	v_pk_mul_f32 v[70:71], v[56:57], v[242:243] op_sel_hi:[1,0]
	v_pk_mul_f32 v[72:73], v[58:59], v[242:243] op_sel_hi:[1,0]
	v_pk_mul_f32 v[52:53], v[52:53], v[60:61]
	v_pk_mul_f32 v[54:55], v[54:55], v[62:63]
	v_pk_mul_f32 v[56:57], v[48:49], v[56:57]
	v_pk_mul_f32 v[58:59], v[50:51], v[58:59]
	v_exp_f32_e32 v64, v64
	v_exp_f32_e32 v65, v65
	v_exp_f32_e32 v68, v68
	v_exp_f32_e32 v69, v69
	v_exp_f32_e32 v70, v70
	v_exp_f32_e32 v71, v71
	v_exp_f32_e32 v72, v72
	v_exp_f32_e32 v73, v73
	v_pk_mul_f32 v[52:53], v[52:53], v[242:243] op_sel:[0,1] op_sel_hi:[1,1]
	v_pk_mul_f32 v[54:55], v[54:55], v[242:243] op_sel:[0,1] op_sel_hi:[1,1]
	v_pk_mul_f32 v[56:57], v[56:57], v[242:243] op_sel:[0,1] op_sel_hi:[1,1]
	v_pk_mul_f32 v[58:59], v[58:59], v[242:243] op_sel:[0,1] op_sel_hi:[1,1]
	v_pk_add_f32 v[64:65], v[64:65], 1.0 op_sel_hi:[1,0]
	v_pk_add_f32 v[68:69], v[68:69], 1.0 op_sel_hi:[1,0]
	v_pk_add_f32 v[70:71], v[70:71], 1.0 op_sel_hi:[1,0]
	v_pk_add_f32 v[72:73], v[72:73], 1.0 op_sel_hi:[1,0]
	v_rcp_f32_e32 v64, v64
	v_rcp_f32_e32 v65, v65
	v_rcp_f32_e32 v68, v68
	v_rcp_f32_e32 v69, v69
	v_rcp_f32_e32 v70, v70
	v_rcp_f32_e32 v71, v71
	v_rcp_f32_e32 v72, v72
	v_rcp_f32_e32 v73, v73
	v_pk_mul_f32 v[52:53], v[52:53], v[64:65]
	v_pk_mul_f32 v[54:55], v[54:55], v[68:69]
	v_pk_mul_f32 v[56:57], v[56:57], v[70:71]
	v_pk_mul_f32 v[58:59], v[58:59], v[72:73]
	v_cvt_pk_bf16_f32 v48, v52, v53
	v_cvt_pk_bf16_f32 v49, v54, v55
	v_cvt_pk_bf16_f32 v50, v56, v57
	v_cvt_pk_bf16_f32 v51, v58, v59
	global_store_dwordx4 v[66:67], v[48:51], off
	s_nop 0
	s_waitcnt vmcnt(7)
	v_cvt_f32_u32_e32 v48, v245
	v_cvt_f32_u32_e32 v50, v244
	v_add_u32_e32 v49, 0x90, v144
	v_fmamk_f32 v48, v50, 0x2f800000, v48
	v_fmamk_f32 v48, v48, 0x3a800000, v158
	v_rsq_f32_e32 v48, v48
	v_mad_i64_i32 v[50:51], s[38:39], v49, s51, v[146:147]
	v_lshl_add_u64 v[50:51], v[50:51], 0, v[148:149]
	v_mul_f32_e32 v244, 0xbfb8aa3b, v48
	v_mul_f32_e32 v245, v48, v48
	v_pk_mul_f32 v[48:49], v[44:45], v[244:245] op_sel_hi:[1,0]
	v_pk_mul_f32 v[52:53], v[46:47], v[244:245] op_sel_hi:[1,0]
	v_pk_mul_f32 v[54:55], v[40:41], v[244:245] op_sel_hi:[1,0]
	v_pk_mul_f32 v[56:57], v[42:43], v[244:245] op_sel_hi:[1,0]
	v_pk_mul_f32 v[36:37], v[36:37], v[44:45]
	v_pk_mul_f32 v[38:39], v[38:39], v[46:47]
	v_pk_mul_f32 v[40:41], v[32:33], v[40:41]
	v_pk_mul_f32 v[42:43], v[34:35], v[42:43]
	v_exp_f32_e32 v48, v48
	v_exp_f32_e32 v49, v49
	v_exp_f32_e32 v52, v52
	v_exp_f32_e32 v53, v53
	v_exp_f32_e32 v54, v54
	v_exp_f32_e32 v55, v55
	v_exp_f32_e32 v56, v56
	v_exp_f32_e32 v57, v57
	v_pk_mul_f32 v[36:37], v[36:37], v[244:245] op_sel:[0,1] op_sel_hi:[1,1]
	v_pk_mul_f32 v[38:39], v[38:39], v[244:245] op_sel:[0,1] op_sel_hi:[1,1]
	v_pk_mul_f32 v[40:41], v[40:41], v[244:245] op_sel:[0,1] op_sel_hi:[1,1]
	v_pk_mul_f32 v[42:43], v[42:43], v[244:245] op_sel:[0,1] op_sel_hi:[1,1]
	v_pk_add_f32 v[48:49], v[48:49], 1.0 op_sel_hi:[1,0]
	v_pk_add_f32 v[52:53], v[52:53], 1.0 op_sel_hi:[1,0]
	v_pk_add_f32 v[54:55], v[54:55], 1.0 op_sel_hi:[1,0]
	v_pk_add_f32 v[56:57], v[56:57], 1.0 op_sel_hi:[1,0]
	v_rcp_f32_e32 v48, v48
	v_rcp_f32_e32 v49, v49
	v_rcp_f32_e32 v52, v52
	v_rcp_f32_e32 v53, v53
	v_rcp_f32_e32 v54, v54
	v_rcp_f32_e32 v55, v55
	v_rcp_f32_e32 v56, v56
	v_rcp_f32_e32 v57, v57
	v_pk_mul_f32 v[36:37], v[36:37], v[48:49]
	v_pk_mul_f32 v[38:39], v[38:39], v[52:53]
	v_pk_mul_f32 v[40:41], v[40:41], v[54:55]
	v_pk_mul_f32 v[42:43], v[42:43], v[56:57]
	v_cvt_pk_bf16_f32 v32, v36, v37
	v_cvt_pk_bf16_f32 v33, v38, v39
	v_cvt_pk_bf16_f32 v34, v40, v41
	v_cvt_pk_bf16_f32 v35, v42, v43
	global_store_dwordx4 v[50:51], v[32:35], off
	s_nop 0
	s_waitcnt vmcnt(7)
; __device__ __forceinline__ unsigned cvtpk(float lo, float hi) { f32x2v_ v = {lo, hi}; bf16x2v_ b = __builtin_convertvector(v, bf16x2v_); return __builtin_bit_cast(unsigned, b); }
; #define PG8_BAR __builtin_amdgcn_s_barrier()
;     __device__ __forceinline__ void operator()(const f32x4 (&acc)[2][2][4][2], const Unit& u, int wr, int wc, int fr, int fq) const {
;     ...
;             for (int m = 0; m < 4; ++m) { const int row = row0 + ai * HALF + m * 16; const float rs = row_rs(ss, row);
;                 float hv[8];
; #pragma unroll
;                 for (int n = 0; n < 2; ++n)
; #pragma unroll
;                     for (int i = 0; i < 4; ++i) { const float g = acc[ai][0][m][n][i] * rs, uu = acc[ai][1][m][n][i] * rs;
;                         hv[n * 4 + i] = g * __builtin_amdgcn_rcpf(1.0f + __expf(-g)) * uu; }
;                 u32x4 w; w.x = cvtpk(hv[0], hv[1]); w.y = cvtpk(hv[2], hv[3]); w.z = cvtpk(hv[4], hv[5]); w.w = cvtpk(hv[6], hv[7]);
;                 *(u32x4*)(H + (size_t)row * ldh + col0) = w; }
; template <class Epi, class Sched, bool ALIGN_EPI = false, bool SP2 = false>
; __device__ __forceinline__ void gemm_phase(PG8_LAS unsigned char* lds, const Gemm g, const Sched& S, const Epi& E) {
;     ...
;         if (!has_next) break;
; #pragma unroll
;         for (int a = 0; a < 2; ++a)
; #pragma unroll
;             for (int b = 0; b < 2; ++b)
; #pragma unroll
;                 for (int m = 0; m < 4; ++m)
; #pragma unroll
;                     for (int n = 0; n < 2; ++n) acc[a][b][m][n] = (f32x4){0.f, 0.f, 0.f, 0.f};
;         cur = nxt; cA = nA; cB = nB; ++ui;
;         if constexpr (ALIGN_EPI) { if (wr == 1) PG8_BAR; }
;     }
	v_cvt_f32_u32_e32 v32, v247
	v_cvt_f32_u32_e32 v34, v246
	v_add_u32_e32 v33, 0xa0, v144
	v_fmamk_f32 v32, v34, 0x2f800000, v32
	v_fmamk_f32 v32, v32, 0x3a800000, v158
	v_rsq_f32_e32 v32, v32
	v_mad_i64_i32 v[34:35], s[38:39], v33, s51, v[146:147]
	v_lshl_add_u64 v[34:35], v[34:35], 0, v[148:149]
	v_mul_f32_e32 v246, 0xbfb8aa3b, v32
	v_mul_f32_e32 v247, v32, v32
	v_pk_mul_f32 v[32:33], v[28:29], v[246:247] op_sel_hi:[1,0]
	v_pk_mul_f32 v[36:37], v[30:31], v[246:247] op_sel_hi:[1,0]
	v_pk_mul_f32 v[38:39], v[24:25], v[246:247] op_sel_hi:[1,0]
	v_pk_mul_f32 v[40:41], v[26:27], v[246:247] op_sel_hi:[1,0]
	v_pk_mul_f32 v[20:21], v[20:21], v[28:29]
	v_pk_mul_f32 v[22:23], v[22:23], v[30:31]
	v_pk_mul_f32 v[24:25], v[16:17], v[24:25]
	v_pk_mul_f32 v[26:27], v[18:19], v[26:27]
	v_exp_f32_e32 v32, v32
	v_exp_f32_e32 v33, v33
	v_exp_f32_e32 v36, v36
	v_exp_f32_e32 v37, v37
	v_exp_f32_e32 v38, v38
	v_exp_f32_e32 v39, v39
	v_exp_f32_e32 v40, v40
	v_exp_f32_e32 v41, v41
	v_pk_mul_f32 v[20:21], v[20:21], v[246:247] op_sel:[0,1] op_sel_hi:[1,1]
	v_pk_mul_f32 v[22:23], v[22:23], v[246:247] op_sel:[0,1] op_sel_hi:[1,1]
	v_pk_mul_f32 v[24:25], v[24:25], v[246:247] op_sel:[0,1] op_sel_hi:[1,1]
	v_pk_mul_f32 v[26:27], v[26:27], v[246:247] op_sel:[0,1] op_sel_hi:[1,1]
	v_pk_add_f32 v[32:33], v[32:33], 1.0 op_sel_hi:[1,0]
	v_pk_add_f32 v[36:37], v[36:37], 1.0 op_sel_hi:[1,0]
	v_pk_add_f32 v[38:39], v[38:39], 1.0 op_sel_hi:[1,0]
	v_pk_add_f32 v[40:41], v[40:41], 1.0 op_sel_hi:[1,0]
	v_rcp_f32_e32 v32, v32
	v_rcp_f32_e32 v33, v33
	v_rcp_f32_e32 v36, v36
	v_rcp_f32_e32 v37, v37
	v_rcp_f32_e32 v38, v38
	v_rcp_f32_e32 v39, v39
	v_rcp_f32_e32 v40, v40
	v_rcp_f32_e32 v41, v41
	v_pk_mul_f32 v[20:21], v[20:21], v[32:33]
	v_pk_mul_f32 v[22:23], v[22:23], v[36:37]
	v_pk_mul_f32 v[24:25], v[24:25], v[38:39]
	v_pk_mul_f32 v[26:27], v[26:27], v[40:41]
	v_cvt_pk_bf16_f32 v16, v20, v21
	v_cvt_pk_bf16_f32 v17, v22, v23
	v_cvt_pk_bf16_f32 v18, v24, v25
	v_cvt_pk_bf16_f32 v19, v26, v27
	global_store_dwordx4 v[34:35], v[16:19], off
	s_nop 0
	s_waitcnt vmcnt(7)
	v_cvt_f32_u32_e32 v16, v249
	v_cvt_f32_u32_e32 v18, v248
	v_add_u32_e32 v17, 0xb0, v144
	v_fmamk_f32 v16, v18, 0x2f800000, v16
	v_fmamk_f32 v16, v16, 0x3a800000, v158
	v_rsq_f32_e32 v16, v16
	v_mad_i64_i32 v[18:19], s[38:39], v17, s51, v[146:147]
	v_lshl_add_u64 v[18:19], v[18:19], 0, v[148:149]
	v_mul_f32_e32 v248, 0xbfb8aa3b, v16
	v_mul_f32_e32 v249, v16, v16
	v_pk_mul_f32 v[16:17], v[12:13], v[248:249] op_sel_hi:[1,0]
	v_pk_mul_f32 v[20:21], v[14:15], v[248:249] op_sel_hi:[1,0]
	v_pk_mul_f32 v[22:23], v[8:9], v[248:249] op_sel_hi:[1,0]
	v_pk_mul_f32 v[24:25], v[10:11], v[248:249] op_sel_hi:[1,0]
	v_pk_mul_f32 v[4:5], v[4:5], v[12:13]
	v_pk_mul_f32 v[6:7], v[6:7], v[14:15]
	v_pk_mul_f32 v[8:9], v[0:1], v[8:9]
	v_pk_mul_f32 v[10:11], v[2:3], v[10:11]
	v_exp_f32_e32 v16, v16
	v_exp_f32_e32 v17, v17
	v_exp_f32_e32 v20, v20
	v_exp_f32_e32 v21, v21
	v_exp_f32_e32 v22, v22
	v_exp_f32_e32 v23, v23
	v_exp_f32_e32 v24, v24
	v_exp_f32_e32 v25, v25
	v_pk_mul_f32 v[4:5], v[4:5], v[248:249] op_sel:[0,1] op_sel_hi:[1,1]
	v_pk_mul_f32 v[6:7], v[6:7], v[248:249] op_sel:[0,1] op_sel_hi:[1,1]
	v_pk_mul_f32 v[8:9], v[8:9], v[248:249] op_sel:[0,1] op_sel_hi:[1,1]
	v_pk_mul_f32 v[10:11], v[10:11], v[248:249] op_sel:[0,1] op_sel_hi:[1,1]
	v_pk_add_f32 v[16:17], v[16:17], 1.0 op_sel_hi:[1,0]
	v_pk_add_f32 v[20:21], v[20:21], 1.0 op_sel_hi:[1,0]
	v_pk_add_f32 v[22:23], v[22:23], 1.0 op_sel_hi:[1,0]
	v_pk_add_f32 v[24:25], v[24:25], 1.0 op_sel_hi:[1,0]
	v_rcp_f32_e32 v16, v16
	v_rcp_f32_e32 v17, v17
	v_rcp_f32_e32 v20, v20
	v_rcp_f32_e32 v21, v21
	v_rcp_f32_e32 v22, v22
	v_rcp_f32_e32 v23, v23
	v_rcp_f32_e32 v24, v24
	v_rcp_f32_e32 v25, v25
	v_pk_mul_f32 v[4:5], v[4:5], v[16:17]
	v_pk_mul_f32 v[6:7], v[6:7], v[20:21]
	v_pk_mul_f32 v[8:9], v[8:9], v[22:23]
	v_pk_mul_f32 v[10:11], v[10:11], v[24:25]
	v_cvt_pk_bf16_f32 v0, v4, v5
	v_cvt_pk_bf16_f32 v1, v6, v7
	v_cvt_pk_bf16_f32 v2, v8, v9
	v_cvt_pk_bf16_f32 v3, v10, v11
	global_store_dwordx4 v[18:19], v[0:3], off
	s_cbranch_vccnz .LBB0_1896
	s_andn2_b64 vcc, exec, s[6:7]
	s_cbranch_vccnz .LBB0_1895
	s_barrier
	s_branch .LBB0_1895
